# s7 + 64 of tail0's 128 layer-1 in_proj blocks relocated into the G2-tail loop (loop wrap), tail0 keeps one block per workgroup
# speedup vs baseline: 1.0049x; 1.0019x over previous
; #define LAS __attribute__((address_space(3)))
; __device__ __forceinline__ float bflo(unsigned w) { return __uint_as_float(w << 16); }
; __device__ __forceinline__ float bfhi(unsigned w) { return __uint_as_float(w & 0xffff0000u); }
; __device__ __forceinline__ void direct_w8_block(const Ctx& c, LAS unsigned char* lds, const float* Wsrc, const int INC_, int srccol, unsigned char* dstrow, float* swdst) {
;     ...
;     f32x4 sc, inv;
; #pragma unroll
;     for (int j = 0; j < 4; ++j) { sc[j] = cm[j] > 0.f ? cm[j] * (1.0f / 127.0f) : 1.0f; inv[j] = 1.0f / sc[j]; }
;     if (wave == 0 && kr == 0) *(f32x4*)(swdst + 4 * nc) = sc;
;     unsigned char* dst = dstrow + (size_t)(4 * nc) * DM + 512 * wave + 8 * kr;
; #pragma unroll
;     for (int t = 0; t < 8; ++t) { unsigned char* dt = dst + t * 64; asm volatile("" : "+v"(dt));
; #pragma unroll
;         for (int j = 0; j < 4; ++j) { v4u pk;
;             if (t < 4) { pk.x = held[t & 3][j][0]; pk.y = held[t & 3][j][1]; pk.z = held[t & 3][j][2]; pk.w = held[t & 3][j][3]; }
;             else pk = *(const LAS v4u*)(hl + ((t - 4) * 4 + j) * 1024);
;             int qi[8];
; #pragma unroll
;             for (int pr = 0; pr < 4; ++pr) { qi[2 * pr] = __float2int_rn(bflo(pk[pr]) * inv[j]); qi[2 * pr + 1] = __float2int_rn(bfhi(pk[pr]) * inv[j]); }
;             v2u w; w.x = (unsigned)(qi[0] & 255) | ((unsigned)(qi[1] & 255) << 8) | ((unsigned)(qi[2] & 255) << 16) | ((unsigned)(qi[3] & 255) << 24);
;             w.y = (unsigned)(qi[4] & 255) | ((unsigned)(qi[5] & 255) << 8) | ((unsigned)(qi[6] & 255) << 16) | ((unsigned)(qi[7] & 255) << 24);
;             *(v2u*)(dt + (size_t)j * DM) = w; } }
.LBB0_452:
	s_or_b64 exec, exec, s[8:9]
	v_div_scale_f32 v134, s[2:3], v130, v130, 1.0
	v_rcp_f32_e32 v135, v134
	v_cvt_pk_bf16_f32 v4, v0, v4
	v_cvt_pk_bf16_f32 v8, v8, v12
	v_lshlrev_b32_e32 v12, 16, v4
	v_fma_f32 v136, -v134, v135, 1.0
	v_fmac_f32_e32 v135, v136, v135
	v_div_scale_f32 v136, vcc, 1.0, v130, 1.0
	v_mul_f32_e32 v137, v136, v135
	v_fma_f32 v138, -v134, v137, v136
	v_fmac_f32_e32 v137, v138, v135
	v_fma_f32 v134, -v134, v137, v136
	v_div_fmas_f32 v134, v134, v135, v137
	v_div_fixup_f32 v135, v134, v130, 1.0
	v_div_scale_f32 v130, s[2:3], v131, v131, 1.0
	v_rcp_f32_e32 v134, v130
	v_and_b32_e32 v4, 0xffff0000, v4
	v_cvt_pk_bf16_f32 v11, v11, v15
	v_cvt_pk_bf16_f32 v15, v3, v7
	v_fma_f32 v136, -v130, v134, 1.0
	v_fmac_f32_e32 v134, v136, v134
	v_div_scale_f32 v136, vcc, 1.0, v131, 1.0
	v_mul_f32_e32 v137, v136, v134
	v_fma_f32 v138, -v130, v137, v136
	v_fmac_f32_e32 v137, v138, v134
	v_fma_f32 v130, -v130, v137, v136
	v_div_fmas_f32 v130, v130, v134, v137
	v_div_fixup_f32 v134, v130, v131, 1.0
	v_div_scale_f32 v130, s[2:3], v132, v132, 1.0
	v_rcp_f32_e32 v131, v130
	v_cvt_pk_bf16_f32 v7, v17, v21
	v_cvt_pk_bf16_f32 v16, v16, v20
	v_mul_f32_e32 v4, v135, v4
	v_fma_f32 v136, -v130, v131, 1.0
	v_lshlrev_b32_e32 v17, 16, v8
	v_and_b32_e32 v8, 0xffff0000, v8
	v_fmac_f32_e32 v131, v136, v131
	v_div_scale_f32 v136, vcc, 1.0, v132, 1.0
	v_cvt_pk_bf16_f32 v9, v9, v13
	v_cvt_pk_bf16_f32 v13, v1, v5
	v_cvt_pk_bf16_f32 v5, v24, v28
	v_mul_f32_e32 v12, v135, v12
	v_rndne_f32_e32 v4, v4
	v_mul_f32_e32 v17, v135, v17
	v_mul_f32_e32 v8, v135, v8
	v_lshlrev_b32_e32 v20, 16, v16
	v_and_b32_e32 v16, 0xffff0000, v16
	v_mul_f32_e32 v137, v136, v131
	v_rndne_f32_e32 v12, v12
	v_cvt_i32_f32_e32 v4, v4
	v_rndne_f32_e32 v17, v17
	v_rndne_f32_e32 v8, v8
	v_mul_f32_e32 v16, v135, v16
	v_lshlrev_b32_e32 v21, 16, v5
	v_and_b32_e32 v5, 0xffff0000, v5
	v_fma_f32 v138, -v130, v137, v136
	v_cvt_i32_f32_e32 v12, v12
	v_cvt_i32_f32_sdwa v17, v17 dst_sel:WORD_1 dst_unused:UNUSED_PAD src0_sel:DWORD
	v_cvt_i32_f32_e32 v8, v8
	v_mul_f32_e32 v20, v135, v20
	v_rndne_f32_e32 v16, v16
	v_mul_f32_e32 v21, v135, v21
	v_mul_f32_e32 v5, v135, v5
	v_fmac_f32_e32 v137, v138, v131
	v_rndne_f32_e32 v20, v20
	v_cvt_i32_f32_e32 v16, v16
	v_rndne_f32_e32 v21, v21
	v_rndne_f32_e32 v5, v5
	v_fma_f32 v130, -v130, v137, v136
	v_cvt_i32_f32_e32 v20, v20
	v_cvt_i32_f32_sdwa v21, v21 dst_sel:WORD_1 dst_unused:UNUSED_PAD src0_sel:DWORD
	v_cvt_i32_f32_e32 v5, v5
	v_div_fmas_f32 v130, v130, v131, v137
	v_lshlrev_b32_e32 v4, 8, v4
	v_div_fixup_f32 v131, v130, v132, 1.0
	v_div_scale_f32 v130, s[2:3], v133, v133, 1.0
	v_and_b32_e32 v4, 0xff00, v4
	v_and_b32_e32 v17, 0xff0000, v17
	v_perm_b32 v8, v8, v12, s81
	s_lshl_b64 s[2:3], s[10:11], 12
	v_or3_b32 v4, v8, v4, v17
	v_lshlrev_b32_e32 v8, 8, v16
	v_lshl_add_u64 v[0:1], v[166:167], 0, s[2:3]
	v_and_b32_e32 v8, 0xff00, v8
	v_and_b32_e32 v12, 0xff0000, v21
	v_perm_b32 v5, v5, v20, s81
	v_cvt_pk_bf16_f32 v10, v10, v14
	v_cvt_pk_bf16_f32 v14, v2, v6
	v_mov_b64_e32 v[2:3], v[0:1]
	v_or3_b32 v5, v5, v8, v12
	global_store_dwordx2 v[2:3], v[4:5], off
	v_and_b32_e32 v5, 0xffff0000, v13
	v_rcp_f32_e32 v132, v130
	v_lshlrev_b32_e32 v4, 16, v13
	v_mul_f32_e32 v5, v134, v5
	v_lshlrev_b32_e32 v8, 16, v9
	v_and_b32_e32 v9, 0xffff0000, v9
	v_cvt_pk_bf16_f32 v6, v25, v29
	v_mul_f32_e32 v4, v134, v4
	v_rndne_f32_e32 v5, v5
	v_mul_f32_e32 v8, v134, v8
	v_mul_f32_e32 v9, v134, v9
	v_lshlrev_b32_e32 v12, 16, v7
	v_and_b32_e32 v7, 0xffff0000, v7
	v_rndne_f32_e32 v4, v4
	v_cvt_i32_f32_e32 v5, v5
	v_rndne_f32_e32 v8, v8
	v_rndne_f32_e32 v9, v9
	v_mul_f32_e32 v7, v134, v7
	v_lshlrev_b32_e32 v13, 16, v6
	v_and_b32_e32 v6, 0xffff0000, v6
	v_cvt_i32_f32_e32 v4, v4
	v_cvt_i32_f32_sdwa v8, v8 dst_sel:WORD_1 dst_unused:UNUSED_PAD src0_sel:DWORD
	v_cvt_i32_f32_e32 v9, v9
	v_mul_f32_e32 v12, v134, v12
	v_rndne_f32_e32 v7, v7
	v_mul_f32_e32 v13, v134, v13
	v_mul_f32_e32 v6, v134, v6
	v_fma_f32 v136, -v130, v132, 1.0
	v_rndne_f32_e32 v12, v12
	v_cvt_i32_f32_e32 v7, v7
	v_rndne_f32_e32 v13, v13
	v_rndne_f32_e32 v6, v6
	v_fmac_f32_e32 v132, v136, v132
	v_div_scale_f32 v136, vcc, 1.0, v133, 1.0
	v_cvt_i32_f32_e32 v12, v12
	v_cvt_i32_f32_sdwa v13, v13 dst_sel:WORD_1 dst_unused:UNUSED_PAD src0_sel:DWORD
	v_cvt_i32_f32_e32 v6, v6
	v_mul_f32_e32 v137, v136, v132
	v_lshlrev_b32_e32 v5, 8, v5
	v_fma_f32 v138, -v130, v137, v136
	v_and_b32_e32 v5, 0xff00, v5
	v_and_b32_e32 v8, 0xff0000, v8
	v_perm_b32 v4, v9, v4, s81
	v_fmac_f32_e32 v137, v138, v132
	v_or3_b32 v4, v4, v5, v8
	v_lshlrev_b32_e32 v5, 8, v7
	v_fma_f32 v130, -v130, v137, v136
	v_and_b32_e32 v5, 0xff00, v5
	v_and_b32_e32 v7, 0xff0000, v13
	v_perm_b32 v6, v6, v12, s81
	v_div_fmas_f32 v130, v130, v132, v137
	v_or3_b32 v5, v6, v5, v7
	v_add_co_u32_e32 v6, vcc, s67, v2
	v_cvt_pk_bf16_f32 v18, v18, v22
	s_nop 0
	v_addc_co_u32_e32 v7, vcc, 0, v3, vcc
	global_store_dwordx2 v[6:7], v[4:5], off
	v_and_b32_e32 v5, 0xffff0000, v14
	v_lshlrev_b32_e32 v4, 16, v14
	v_mul_f32_e32 v5, v131, v5
	v_lshlrev_b32_e32 v6, 16, v10
	v_and_b32_e32 v7, 0xffff0000, v10
	v_cvt_pk_bf16_f32 v19, v19, v23
	v_cvt_pk_bf16_f32 v23, v26, v30
	v_mul_f32_e32 v4, v131, v4
	v_rndne_f32_e32 v5, v5
	v_mul_f32_e32 v6, v131, v6
	v_mul_f32_e32 v7, v131, v7
	v_and_b32_e32 v9, 0xffff0000, v18
	v_rndne_f32_e32 v4, v4
	v_cvt_i32_f32_e32 v5, v5
	v_rndne_f32_e32 v6, v6
	v_rndne_f32_e32 v7, v7
	v_lshlrev_b32_e32 v8, 16, v18
	v_mul_f32_e32 v9, v131, v9
	v_lshlrev_b32_e32 v10, 16, v23
	v_and_b32_e32 v12, 0xffff0000, v23
	v_cvt_i32_f32_e32 v4, v4
	v_cvt_i32_f32_sdwa v6, v6 dst_sel:WORD_1 dst_unused:UNUSED_PAD src0_sel:DWORD
	v_cvt_i32_f32_e32 v7, v7
	v_mul_f32_e32 v8, v131, v8
; #define LAS __attribute__((address_space(3)))
; __device__ __forceinline__ float bflo(unsigned w) { return __uint_as_float(w << 16); }
; __device__ __forceinline__ float bfhi(unsigned w) { return __uint_as_float(w & 0xffff0000u); }
; __device__ __forceinline__ void direct_w8_block(const Ctx& c, LAS unsigned char* lds, const float* Wsrc, const int INC_, int srccol, unsigned char* dstrow, float* swdst) {
;     ...
; #pragma unroll
;     for (int t = 0; t < 8; ++t) { unsigned char* dt = dst + t * 64; asm volatile("" : "+v"(dt));
; #pragma unroll
;         for (int j = 0; j < 4; ++j) { v4u pk;
;             if (t < 4) { pk.x = held[t & 3][j][0]; pk.y = held[t & 3][j][1]; pk.z = held[t & 3][j][2]; pk.w = held[t & 3][j][3]; }
;             else pk = *(const LAS v4u*)(hl + ((t - 4) * 4 + j) * 1024);
;             int qi[8];
; #pragma unroll
;             for (int pr = 0; pr < 4; ++pr) { qi[2 * pr] = __float2int_rn(bflo(pk[pr]) * inv[j]); qi[2 * pr + 1] = __float2int_rn(bfhi(pk[pr]) * inv[j]); }
;             v2u w; w.x = (unsigned)(qi[0] & 255) | ((unsigned)(qi[1] & 255) << 8) | ((unsigned)(qi[2] & 255) << 16) | ((unsigned)(qi[3] & 255) << 24);
;             w.y = (unsigned)(qi[4] & 255) | ((unsigned)(qi[5] & 255) << 8) | ((unsigned)(qi[6] & 255) << 16) | ((unsigned)(qi[7] & 255) << 24);
;             *(v2u*)(dt + (size_t)j * DM) = w; } }
	v_rndne_f32_e32 v9, v9
	v_mul_f32_e32 v10, v131, v10
	v_mul_f32_e32 v12, v131, v12
	v_rndne_f32_e32 v8, v8
	v_cvt_i32_f32_e32 v9, v9
	v_rndne_f32_e32 v10, v10
	v_rndne_f32_e32 v12, v12
	v_cvt_i32_f32_e32 v8, v8
	v_cvt_i32_f32_sdwa v10, v10 dst_sel:WORD_1 dst_unused:UNUSED_PAD src0_sel:DWORD
	v_cvt_i32_f32_e32 v12, v12
	v_lshlrev_b32_e32 v5, 8, v5
	v_and_b32_e32 v5, 0xff00, v5
	v_and_b32_e32 v6, 0xff0000, v6
	v_perm_b32 v4, v7, v4, s81
	v_or3_b32 v4, v4, v5, v6
	v_lshlrev_b32_e32 v5, 8, v9
	v_and_b32_e32 v5, 0xff00, v5
	v_and_b32_e32 v6, 0xff0000, v10
	v_perm_b32 v7, v12, v8, s81
	v_or3_b32 v5, v7, v5, v6
	v_add_co_u32_e32 v6, vcc, s33, v2
	v_div_fixup_f32 v130, v130, v133, 1.0
	s_nop 0
	v_addc_co_u32_e32 v7, vcc, 0, v3, vcc
	global_store_dwordx2 v[6:7], v[4:5], off
	v_and_b32_e32 v5, 0xffff0000, v15
	v_lshlrev_b32_e32 v4, 16, v15
	v_mul_f32_e32 v5, v130, v5
	v_lshlrev_b32_e32 v6, 16, v11
	v_and_b32_e32 v7, 0xffff0000, v11
	v_cvt_pk_bf16_f32 v27, v27, v31
	v_mul_f32_e32 v4, v130, v4
	v_rndne_f32_e32 v5, v5
	v_mul_f32_e32 v6, v130, v6
	v_mul_f32_e32 v7, v130, v7
	v_and_b32_e32 v9, 0xffff0000, v19
	v_rndne_f32_e32 v4, v4
	v_cvt_i32_f32_e32 v5, v5
	v_rndne_f32_e32 v6, v6
	v_rndne_f32_e32 v7, v7
	v_lshlrev_b32_e32 v8, 16, v19
	v_mul_f32_e32 v9, v130, v9
	v_lshlrev_b32_e32 v10, 16, v27
	v_and_b32_e32 v11, 0xffff0000, v27
	v_cvt_i32_f32_e32 v4, v4
	v_cvt_i32_f32_sdwa v6, v6 dst_sel:WORD_1 dst_unused:UNUSED_PAD src0_sel:DWORD
	v_cvt_i32_f32_e32 v7, v7
	v_mul_f32_e32 v8, v130, v8
	v_rndne_f32_e32 v9, v9
	v_mul_f32_e32 v10, v130, v10
	v_mul_f32_e32 v11, v130, v11
	v_rndne_f32_e32 v8, v8
	v_cvt_i32_f32_e32 v9, v9
	v_rndne_f32_e32 v10, v10
	v_rndne_f32_e32 v11, v11
	v_cvt_i32_f32_e32 v8, v8
	v_cvt_i32_f32_sdwa v10, v10 dst_sel:WORD_1 dst_unused:UNUSED_PAD src0_sel:DWORD
	v_cvt_i32_f32_e32 v11, v11
	v_lshlrev_b32_e32 v5, 8, v5
	v_and_b32_e32 v5, 0xff00, v5
	v_and_b32_e32 v6, 0xff0000, v6
	v_perm_b32 v4, v7, v4, s81
	v_or3_b32 v4, v4, v5, v6
	v_lshlrev_b32_e32 v5, 8, v9
	v_and_b32_e32 v5, 0xff00, v5
	v_and_b32_e32 v6, 0xff0000, v10
	v_perm_b32 v7, v11, v8, s81
	v_add_co_u32_e32 v2, vcc, s44, v2
	v_cvt_pk_bf16_f32 v32, v32, v36
	v_or3_b32 v5, v7, v5, v6
	v_addc_co_u32_e32 v3, vcc, 0, v3, vcc
	v_cvt_pk_bf16_f32 v40, v40, v44
	global_store_dwordx2 v[2:3], v[4:5], off
	v_and_b32_e32 v5, 0xffff0000, v32
	v_cvt_pk_bf16_f32 v41, v41, v45
	v_cvt_pk_bf16_f32 v45, v48, v52
	v_lshlrev_b32_e32 v4, 16, v32
	v_mul_f32_e32 v5, v135, v5
	v_lshlrev_b32_e32 v6, 16, v40
	v_and_b32_e32 v7, 0xffff0000, v40
	v_cvt_pk_bf16_f32 v33, v33, v37
	v_cvt_pk_bf16_f32 v37, v56, v60
	v_mul_f32_e32 v4, v135, v4
	v_rndne_f32_e32 v5, v5
	v_mul_f32_e32 v6, v135, v6
	v_mul_f32_e32 v7, v135, v7
	v_and_b32_e32 v9, 0xffff0000, v45
	v_rndne_f32_e32 v4, v4
	v_cvt_i32_f32_e32 v5, v5
	v_rndne_f32_e32 v6, v6
	v_rndne_f32_e32 v7, v7
	v_lshlrev_b32_e32 v8, 16, v45
	v_mul_f32_e32 v9, v135, v9
	v_lshlrev_b32_e32 v10, 16, v37
	v_and_b32_e32 v11, 0xffff0000, v37
	v_cvt_i32_f32_e32 v4, v4
	v_cvt_i32_f32_sdwa v6, v6 dst_sel:WORD_1 dst_unused:UNUSED_PAD src0_sel:DWORD
	v_cvt_i32_f32_e32 v7, v7
	v_mul_f32_e32 v8, v135, v8
	v_rndne_f32_e32 v9, v9
	v_mul_f32_e32 v10, v135, v10
	v_mul_f32_e32 v11, v135, v11
	v_rndne_f32_e32 v8, v8
	v_cvt_i32_f32_e32 v9, v9
	v_rndne_f32_e32 v10, v10
	v_rndne_f32_e32 v11, v11
	v_cvt_i32_f32_e32 v8, v8
	v_cvt_i32_f32_sdwa v10, v10 dst_sel:WORD_1 dst_unused:UNUSED_PAD src0_sel:DWORD
	v_cvt_i32_f32_e32 v11, v11
	v_lshlrev_b32_e32 v5, 8, v5
	v_and_b32_e32 v5, 0xff00, v5
	v_and_b32_e32 v6, 0xff0000, v6
	v_perm_b32 v4, v7, v4, s81
	v_or3_b32 v4, v4, v5, v6
	v_lshlrev_b32_e32 v5, 8, v9
	v_and_b32_e32 v5, 0xff00, v5
	v_and_b32_e32 v6, 0xff0000, v10
	v_perm_b32 v7, v11, v8, s81
	v_lshl_add_u64 v[2:3], v[0:1], 0, 64
	v_or3_b32 v5, v7, v5, v6
	global_store_dwordx2 v[2:3], v[4:5], off
	v_and_b32_e32 v5, 0xffff0000, v33
	v_cvt_pk_bf16_f32 v42, v42, v46
	v_cvt_pk_bf16_f32 v46, v49, v53
	v_lshlrev_b32_e32 v4, 16, v33
	v_mul_f32_e32 v5, v134, v5
	v_lshlrev_b32_e32 v6, 16, v41
	v_and_b32_e32 v7, 0xffff0000, v41
	v_cvt_pk_bf16_f32 v34, v34, v38
	v_cvt_pk_bf16_f32 v38, v57, v61
	v_mul_f32_e32 v4, v134, v4
	v_rndne_f32_e32 v5, v5
	v_mul_f32_e32 v6, v134, v6
	v_mul_f32_e32 v7, v134, v7
	v_and_b32_e32 v9, 0xffff0000, v46
	v_rndne_f32_e32 v4, v4
	v_cvt_i32_f32_e32 v5, v5
	v_rndne_f32_e32 v6, v6
	v_rndne_f32_e32 v7, v7
	v_lshlrev_b32_e32 v8, 16, v46
	v_mul_f32_e32 v9, v134, v9
	v_lshlrev_b32_e32 v10, 16, v38
	v_and_b32_e32 v11, 0xffff0000, v38
	v_cvt_i32_f32_e32 v4, v4
	v_cvt_i32_f32_sdwa v6, v6 dst_sel:WORD_1 dst_unused:UNUSED_PAD src0_sel:DWORD
	v_cvt_i32_f32_e32 v7, v7
	v_mul_f32_e32 v8, v134, v8
	v_rndne_f32_e32 v9, v9
	v_mul_f32_e32 v10, v134, v10
	v_mul_f32_e32 v11, v134, v11
	v_rndne_f32_e32 v8, v8
	v_cvt_i32_f32_e32 v9, v9
	v_rndne_f32_e32 v10, v10
	v_rndne_f32_e32 v11, v11
	v_cvt_i32_f32_e32 v8, v8
	v_cvt_i32_f32_sdwa v10, v10 dst_sel:WORD_1 dst_unused:UNUSED_PAD src0_sel:DWORD
	v_cvt_i32_f32_e32 v11, v11
	v_lshlrev_b32_e32 v5, 8, v5
	v_and_b32_e32 v5, 0xff00, v5
	v_and_b32_e32 v6, 0xff0000, v6
	v_perm_b32 v4, v7, v4, s81
	v_or3_b32 v4, v4, v5, v6
	v_lshlrev_b32_e32 v5, 8, v9
	v_and_b32_e32 v5, 0xff00, v5
	v_and_b32_e32 v6, 0xff0000, v10
	v_perm_b32 v7, v11, v8, s81
	v_or3_b32 v5, v7, v5, v6
	v_add_co_u32_e32 v6, vcc, s67, v2
	v_cvt_pk_bf16_f32 v43, v43, v47
	s_nop 0
	v_addc_co_u32_e32 v7, vcc, 0, v3, vcc
	global_store_dwordx2 v[6:7], v[4:5], off
	v_and_b32_e32 v5, 0xffff0000, v34
	v_cvt_pk_bf16_f32 v47, v50, v54
	v_lshlrev_b32_e32 v4, 16, v34
	v_mul_f32_e32 v5, v131, v5
	v_lshlrev_b32_e32 v6, 16, v42
	v_and_b32_e32 v7, 0xffff0000, v42
	v_cvt_pk_bf16_f32 v35, v35, v39
	v_cvt_pk_bf16_f32 v39, v58, v62
; #define LAS __attribute__((address_space(3)))
; __device__ __forceinline__ float bflo(unsigned w) { return __uint_as_float(w << 16); }
; __device__ __forceinline__ float bfhi(unsigned w) { return __uint_as_float(w & 0xffff0000u); }
; __device__ __forceinline__ void direct_w8_block(const Ctx& c, LAS unsigned char* lds, const float* Wsrc, const int INC_, int srccol, unsigned char* dstrow, float* swdst) {
;     ...
; #pragma unroll
;     for (int t = 0; t < 8; ++t) { unsigned char* dt = dst + t * 64; asm volatile("" : "+v"(dt));
; #pragma unroll
;         for (int j = 0; j < 4; ++j) { v4u pk;
;             if (t < 4) { pk.x = held[t & 3][j][0]; pk.y = held[t & 3][j][1]; pk.z = held[t & 3][j][2]; pk.w = held[t & 3][j][3]; }
;             else pk = *(const LAS v4u*)(hl + ((t - 4) * 4 + j) * 1024);
;             int qi[8];
; #pragma unroll
;             for (int pr = 0; pr < 4; ++pr) { qi[2 * pr] = __float2int_rn(bflo(pk[pr]) * inv[j]); qi[2 * pr + 1] = __float2int_rn(bfhi(pk[pr]) * inv[j]); }
;             v2u w; w.x = (unsigned)(qi[0] & 255) | ((unsigned)(qi[1] & 255) << 8) | ((unsigned)(qi[2] & 255) << 16) | ((unsigned)(qi[3] & 255) << 24);
;             w.y = (unsigned)(qi[4] & 255) | ((unsigned)(qi[5] & 255) << 8) | ((unsigned)(qi[6] & 255) << 16) | ((unsigned)(qi[7] & 255) << 24);
;             *(v2u*)(dt + (size_t)j * DM) = w; } }
	v_mul_f32_e32 v4, v131, v4
	v_rndne_f32_e32 v5, v5
	v_mul_f32_e32 v6, v131, v6
	v_mul_f32_e32 v7, v131, v7
	v_and_b32_e32 v9, 0xffff0000, v47
	v_rndne_f32_e32 v4, v4
	v_cvt_i32_f32_e32 v5, v5
	v_rndne_f32_e32 v6, v6
	v_rndne_f32_e32 v7, v7
	v_lshlrev_b32_e32 v8, 16, v47
	v_mul_f32_e32 v9, v131, v9
	v_lshlrev_b32_e32 v10, 16, v39
	v_and_b32_e32 v11, 0xffff0000, v39
	v_cvt_i32_f32_e32 v4, v4
	v_cvt_i32_f32_sdwa v6, v6 dst_sel:WORD_1 dst_unused:UNUSED_PAD src0_sel:DWORD
	v_cvt_i32_f32_e32 v7, v7
	v_mul_f32_e32 v8, v131, v8
	v_rndne_f32_e32 v9, v9
	v_mul_f32_e32 v10, v131, v10
	v_mul_f32_e32 v11, v131, v11
	v_rndne_f32_e32 v8, v8
	v_cvt_i32_f32_e32 v9, v9
	v_rndne_f32_e32 v10, v10
	v_rndne_f32_e32 v11, v11
	v_cvt_i32_f32_e32 v8, v8
	v_cvt_i32_f32_sdwa v10, v10 dst_sel:WORD_1 dst_unused:UNUSED_PAD src0_sel:DWORD
	v_cvt_i32_f32_e32 v11, v11
	v_lshlrev_b32_e32 v5, 8, v5
	v_and_b32_e32 v5, 0xff00, v5
	v_and_b32_e32 v6, 0xff0000, v6
	v_perm_b32 v4, v7, v4, s81
	v_or3_b32 v4, v4, v5, v6
	v_lshlrev_b32_e32 v5, 8, v9
	v_and_b32_e32 v5, 0xff00, v5
	v_and_b32_e32 v6, 0xff0000, v10
	v_perm_b32 v7, v11, v8, s81
	v_or3_b32 v5, v7, v5, v6
	v_add_co_u32_e32 v6, vcc, s33, v2
	v_cvt_pk_bf16_f32 v51, v51, v55
	s_nop 0
	v_addc_co_u32_e32 v7, vcc, 0, v3, vcc
	global_store_dwordx2 v[6:7], v[4:5], off
	v_and_b32_e32 v5, 0xffff0000, v35
	v_lshlrev_b32_e32 v4, 16, v35
	v_mul_f32_e32 v5, v130, v5
	v_lshlrev_b32_e32 v6, 16, v43
	v_and_b32_e32 v7, 0xffff0000, v43
	v_cvt_pk_bf16_f32 v59, v59, v63
	v_mul_f32_e32 v4, v130, v4
	v_rndne_f32_e32 v5, v5
	v_mul_f32_e32 v6, v130, v6
	v_mul_f32_e32 v7, v130, v7
	v_and_b32_e32 v9, 0xffff0000, v51
	v_rndne_f32_e32 v4, v4
	v_cvt_i32_f32_e32 v5, v5
	v_rndne_f32_e32 v6, v6
	v_rndne_f32_e32 v7, v7
	v_lshlrev_b32_e32 v8, 16, v51
	v_mul_f32_e32 v9, v130, v9
	v_lshlrev_b32_e32 v10, 16, v59
	v_and_b32_e32 v11, 0xffff0000, v59
	v_cvt_i32_f32_e32 v4, v4
	v_cvt_i32_f32_sdwa v6, v6 dst_sel:WORD_1 dst_unused:UNUSED_PAD src0_sel:DWORD
	v_cvt_i32_f32_e32 v7, v7
	v_mul_f32_e32 v8, v130, v8
	v_rndne_f32_e32 v9, v9
	v_mul_f32_e32 v10, v130, v10
	v_mul_f32_e32 v11, v130, v11
	v_rndne_f32_e32 v8, v8
	v_cvt_i32_f32_e32 v9, v9
	v_rndne_f32_e32 v10, v10
	v_rndne_f32_e32 v11, v11
	v_cvt_i32_f32_e32 v8, v8
	v_cvt_i32_f32_sdwa v10, v10 dst_sel:WORD_1 dst_unused:UNUSED_PAD src0_sel:DWORD
	v_cvt_i32_f32_e32 v11, v11
	v_lshlrev_b32_e32 v5, 8, v5
	v_and_b32_e32 v5, 0xff00, v5
	v_and_b32_e32 v6, 0xff0000, v6
	v_perm_b32 v4, v7, v4, s81
	v_or3_b32 v4, v4, v5, v6
	v_lshlrev_b32_e32 v5, 8, v9
	v_and_b32_e32 v5, 0xff00, v5
	v_and_b32_e32 v6, 0xff0000, v10
	v_perm_b32 v7, v11, v8, s81
	v_add_co_u32_e32 v2, vcc, s44, v2
	v_cvt_pk_bf16_f32 v64, v64, v68
	v_or3_b32 v5, v7, v5, v6
	v_addc_co_u32_e32 v3, vcc, 0, v3, vcc
	v_cvt_pk_bf16_f32 v72, v72, v76
	global_store_dwordx2 v[2:3], v[4:5], off
	v_and_b32_e32 v5, 0xffff0000, v64
	v_cvt_pk_bf16_f32 v73, v73, v77
	v_cvt_pk_bf16_f32 v77, v80, v84
	v_lshlrev_b32_e32 v4, 16, v64
	v_mul_f32_e32 v5, v135, v5
	v_lshlrev_b32_e32 v6, 16, v72
	v_and_b32_e32 v7, 0xffff0000, v72
	v_cvt_pk_bf16_f32 v65, v65, v69
	v_cvt_pk_bf16_f32 v69, v88, v92
	v_mul_f32_e32 v4, v135, v4
	v_rndne_f32_e32 v5, v5
	v_mul_f32_e32 v6, v135, v6
	v_mul_f32_e32 v7, v135, v7
	v_and_b32_e32 v9, 0xffff0000, v77
	v_rndne_f32_e32 v4, v4
	v_cvt_i32_f32_e32 v5, v5
	v_rndne_f32_e32 v6, v6
	v_rndne_f32_e32 v7, v7
	v_lshlrev_b32_e32 v8, 16, v77
	v_mul_f32_e32 v9, v135, v9
	v_lshlrev_b32_e32 v10, 16, v69
	v_and_b32_e32 v11, 0xffff0000, v69
	v_cvt_i32_f32_e32 v4, v4
	v_cvt_i32_f32_sdwa v6, v6 dst_sel:WORD_1 dst_unused:UNUSED_PAD src0_sel:DWORD
	v_cvt_i32_f32_e32 v7, v7
	v_mul_f32_e32 v8, v135, v8
	v_rndne_f32_e32 v9, v9
	v_mul_f32_e32 v10, v135, v10
	v_mul_f32_e32 v11, v135, v11
	v_rndne_f32_e32 v8, v8
	v_cvt_i32_f32_e32 v9, v9
	v_rndne_f32_e32 v10, v10
	v_rndne_f32_e32 v11, v11
	v_cvt_i32_f32_e32 v8, v8
	v_cvt_i32_f32_sdwa v10, v10 dst_sel:WORD_1 dst_unused:UNUSED_PAD src0_sel:DWORD
	v_cvt_i32_f32_e32 v11, v11
	v_lshlrev_b32_e32 v5, 8, v5
	v_and_b32_e32 v5, 0xff00, v5
	v_and_b32_e32 v6, 0xff0000, v6
	v_perm_b32 v4, v7, v4, s81
	v_or3_b32 v4, v4, v5, v6
	v_lshlrev_b32_e32 v5, 8, v9
	v_and_b32_e32 v5, 0xff00, v5
	v_and_b32_e32 v6, 0xff0000, v10
	v_perm_b32 v7, v11, v8, s81
	v_lshl_add_u64 v[2:3], v[0:1], 0, s[42:43]
	v_or3_b32 v5, v7, v5, v6
	global_store_dwordx2 v[2:3], v[4:5], off
	v_and_b32_e32 v5, 0xffff0000, v65
	v_cvt_pk_bf16_f32 v74, v74, v78
	v_cvt_pk_bf16_f32 v78, v81, v85
	v_lshlrev_b32_e32 v4, 16, v65
	v_mul_f32_e32 v5, v134, v5
	v_lshlrev_b32_e32 v6, 16, v73
	v_and_b32_e32 v7, 0xffff0000, v73
	v_cvt_pk_bf16_f32 v66, v66, v70
	v_cvt_pk_bf16_f32 v70, v89, v93
	v_mul_f32_e32 v4, v134, v4
	v_rndne_f32_e32 v5, v5
	v_mul_f32_e32 v6, v134, v6
	v_mul_f32_e32 v7, v134, v7
	v_and_b32_e32 v9, 0xffff0000, v78
	v_rndne_f32_e32 v4, v4
	v_cvt_i32_f32_e32 v5, v5
	v_rndne_f32_e32 v6, v6
	v_rndne_f32_e32 v7, v7
	v_lshlrev_b32_e32 v8, 16, v78
	v_mul_f32_e32 v9, v134, v9
	v_lshlrev_b32_e32 v10, 16, v70
	v_and_b32_e32 v11, 0xffff0000, v70
	v_cvt_i32_f32_e32 v4, v4
	v_cvt_i32_f32_sdwa v6, v6 dst_sel:WORD_1 dst_unused:UNUSED_PAD src0_sel:DWORD
	v_cvt_i32_f32_e32 v7, v7
	v_mul_f32_e32 v8, v134, v8
	v_rndne_f32_e32 v9, v9
	v_mul_f32_e32 v10, v134, v10
	v_mul_f32_e32 v11, v134, v11
	v_rndne_f32_e32 v8, v8
	v_cvt_i32_f32_e32 v9, v9
	v_rndne_f32_e32 v10, v10
	v_rndne_f32_e32 v11, v11
	v_cvt_i32_f32_e32 v8, v8
	v_cvt_i32_f32_sdwa v10, v10 dst_sel:WORD_1 dst_unused:UNUSED_PAD src0_sel:DWORD
	v_cvt_i32_f32_e32 v11, v11
	v_lshlrev_b32_e32 v5, 8, v5
	v_and_b32_e32 v5, 0xff00, v5
	v_and_b32_e32 v6, 0xff0000, v6
	v_perm_b32 v4, v7, v4, s81
	v_or3_b32 v4, v4, v5, v6
	v_lshlrev_b32_e32 v5, 8, v9
; #define LAS __attribute__((address_space(3)))
; __device__ __forceinline__ float bflo(unsigned w) { return __uint_as_float(w << 16); }
; __device__ __forceinline__ float bfhi(unsigned w) { return __uint_as_float(w & 0xffff0000u); }
; __device__ __forceinline__ void direct_w8_block(const Ctx& c, LAS unsigned char* lds, const float* Wsrc, const int INC_, int srccol, unsigned char* dstrow, float* swdst) {
;     ...
; #pragma unroll
;     for (int t = 0; t < 8; ++t) { unsigned char* dt = dst + t * 64; asm volatile("" : "+v"(dt));
; #pragma unroll
;         for (int j = 0; j < 4; ++j) { v4u pk;
;             if (t < 4) { pk.x = held[t & 3][j][0]; pk.y = held[t & 3][j][1]; pk.z = held[t & 3][j][2]; pk.w = held[t & 3][j][3]; }
;             else pk = *(const LAS v4u*)(hl + ((t - 4) * 4 + j) * 1024);
;             int qi[8];
; #pragma unroll
;             for (int pr = 0; pr < 4; ++pr) { qi[2 * pr] = __float2int_rn(bflo(pk[pr]) * inv[j]); qi[2 * pr + 1] = __float2int_rn(bfhi(pk[pr]) * inv[j]); }
;             v2u w; w.x = (unsigned)(qi[0] & 255) | ((unsigned)(qi[1] & 255) << 8) | ((unsigned)(qi[2] & 255) << 16) | ((unsigned)(qi[3] & 255) << 24);
;             w.y = (unsigned)(qi[4] & 255) | ((unsigned)(qi[5] & 255) << 8) | ((unsigned)(qi[6] & 255) << 16) | ((unsigned)(qi[7] & 255) << 24);
;             *(v2u*)(dt + (size_t)j * DM) = w; } }
	v_and_b32_e32 v5, 0xff00, v5
	v_and_b32_e32 v6, 0xff0000, v10
	v_perm_b32 v7, v11, v8, s81
	v_or3_b32 v5, v7, v5, v6
	v_add_co_u32_e32 v6, vcc, s67, v2
	v_cvt_pk_bf16_f32 v75, v75, v79
	s_nop 0
	v_addc_co_u32_e32 v7, vcc, 0, v3, vcc
	global_store_dwordx2 v[6:7], v[4:5], off
	v_and_b32_e32 v5, 0xffff0000, v66
	v_cvt_pk_bf16_f32 v79, v82, v86
	v_lshlrev_b32_e32 v4, 16, v66
	v_mul_f32_e32 v5, v131, v5
	v_lshlrev_b32_e32 v6, 16, v74
	v_and_b32_e32 v7, 0xffff0000, v74
	v_cvt_pk_bf16_f32 v67, v67, v71
	v_cvt_pk_bf16_f32 v71, v90, v94
	v_mul_f32_e32 v4, v131, v4
	v_rndne_f32_e32 v5, v5
	v_mul_f32_e32 v6, v131, v6
	v_mul_f32_e32 v7, v131, v7
	v_and_b32_e32 v9, 0xffff0000, v79
	v_rndne_f32_e32 v4, v4
	v_cvt_i32_f32_e32 v5, v5
	v_rndne_f32_e32 v6, v6
	v_rndne_f32_e32 v7, v7
	v_lshlrev_b32_e32 v8, 16, v79
	v_mul_f32_e32 v9, v131, v9
	v_lshlrev_b32_e32 v10, 16, v71
	v_and_b32_e32 v11, 0xffff0000, v71
	v_cvt_i32_f32_e32 v4, v4
	v_cvt_i32_f32_sdwa v6, v6 dst_sel:WORD_1 dst_unused:UNUSED_PAD src0_sel:DWORD
	v_cvt_i32_f32_e32 v7, v7
	v_mul_f32_e32 v8, v131, v8
	v_rndne_f32_e32 v9, v9
	v_mul_f32_e32 v10, v131, v10
	v_mul_f32_e32 v11, v131, v11
	v_rndne_f32_e32 v8, v8
	v_cvt_i32_f32_e32 v9, v9
	v_rndne_f32_e32 v10, v10
	v_rndne_f32_e32 v11, v11
	v_cvt_i32_f32_e32 v8, v8
	v_cvt_i32_f32_sdwa v10, v10 dst_sel:WORD_1 dst_unused:UNUSED_PAD src0_sel:DWORD
	v_cvt_i32_f32_e32 v11, v11
	v_lshlrev_b32_e32 v5, 8, v5
	v_and_b32_e32 v5, 0xff00, v5
	v_and_b32_e32 v6, 0xff0000, v6
	v_perm_b32 v4, v7, v4, s81
	v_or3_b32 v4, v4, v5, v6
	v_lshlrev_b32_e32 v5, 8, v9
	v_and_b32_e32 v5, 0xff00, v5
	v_and_b32_e32 v6, 0xff0000, v10
	v_perm_b32 v7, v11, v8, s81
	v_or3_b32 v5, v7, v5, v6
	v_add_co_u32_e32 v6, vcc, s33, v2
	v_cvt_pk_bf16_f32 v83, v83, v87
	s_nop 0
	v_addc_co_u32_e32 v7, vcc, 0, v3, vcc
	global_store_dwordx2 v[6:7], v[4:5], off
	v_and_b32_e32 v5, 0xffff0000, v67
	v_lshlrev_b32_e32 v4, 16, v67
	v_mul_f32_e32 v5, v130, v5
	v_lshlrev_b32_e32 v6, 16, v75
	v_and_b32_e32 v7, 0xffff0000, v75
	v_cvt_pk_bf16_f32 v91, v91, v95
	v_mul_f32_e32 v4, v130, v4
	v_rndne_f32_e32 v5, v5
	v_mul_f32_e32 v6, v130, v6
	v_mul_f32_e32 v7, v130, v7
	v_and_b32_e32 v9, 0xffff0000, v83
	v_rndne_f32_e32 v4, v4
	v_cvt_i32_f32_e32 v5, v5
	v_rndne_f32_e32 v6, v6
	v_rndne_f32_e32 v7, v7
	v_lshlrev_b32_e32 v8, 16, v83
	v_mul_f32_e32 v9, v130, v9
	v_lshlrev_b32_e32 v10, 16, v91
	v_and_b32_e32 v11, 0xffff0000, v91
	v_cvt_i32_f32_e32 v4, v4
	v_cvt_i32_f32_sdwa v6, v6 dst_sel:WORD_1 dst_unused:UNUSED_PAD src0_sel:DWORD
	v_cvt_i32_f32_e32 v7, v7
	v_mul_f32_e32 v8, v130, v8
	v_rndne_f32_e32 v9, v9
	v_mul_f32_e32 v10, v130, v10
	v_mul_f32_e32 v11, v130, v11
	v_rndne_f32_e32 v8, v8
	v_cvt_i32_f32_e32 v9, v9
	v_rndne_f32_e32 v10, v10
	v_rndne_f32_e32 v11, v11
	v_cvt_i32_f32_e32 v8, v8
	v_cvt_i32_f32_sdwa v10, v10 dst_sel:WORD_1 dst_unused:UNUSED_PAD src0_sel:DWORD
	v_cvt_i32_f32_e32 v11, v11
	v_lshlrev_b32_e32 v5, 8, v5
	v_and_b32_e32 v5, 0xff00, v5
	v_and_b32_e32 v6, 0xff0000, v6
	v_perm_b32 v4, v7, v4, s81
	v_or3_b32 v4, v4, v5, v6
	v_lshlrev_b32_e32 v5, 8, v9
	v_and_b32_e32 v5, 0xff00, v5
	v_and_b32_e32 v6, 0xff0000, v10
	v_perm_b32 v7, v11, v8, s81
	v_add_co_u32_e32 v2, vcc, s44, v2
	v_cvt_pk_bf16_f32 v98, v98, v102
	v_or3_b32 v5, v7, v5, v6
	v_addc_co_u32_e32 v3, vcc, 0, v3, vcc
	v_cvt_pk_bf16_f32 v106, v106, v110
	global_store_dwordx2 v[2:3], v[4:5], off
	v_and_b32_e32 v5, 0xffff0000, v98
	v_cvt_pk_bf16_f32 v107, v107, v111
	v_cvt_pk_bf16_f32 v111, v114, v118
	v_lshlrev_b32_e32 v4, 16, v98
	v_mul_f32_e32 v5, v135, v5
	v_lshlrev_b32_e32 v6, 16, v106
	v_and_b32_e32 v7, 0xffff0000, v106
	v_cvt_pk_bf16_f32 v99, v99, v103
	v_cvt_pk_bf16_f32 v103, v122, v126
	v_mul_f32_e32 v4, v135, v4
	v_rndne_f32_e32 v5, v5
	v_mul_f32_e32 v6, v135, v6
	v_mul_f32_e32 v7, v135, v7
	v_and_b32_e32 v9, 0xffff0000, v111
	v_rndne_f32_e32 v4, v4
	v_cvt_i32_f32_e32 v5, v5
	v_rndne_f32_e32 v6, v6
	v_rndne_f32_e32 v7, v7
	v_lshlrev_b32_e32 v8, 16, v111
	v_mul_f32_e32 v9, v135, v9
	v_lshlrev_b32_e32 v10, 16, v103
	v_and_b32_e32 v11, 0xffff0000, v103
	v_cvt_i32_f32_e32 v4, v4
	v_cvt_i32_f32_sdwa v6, v6 dst_sel:WORD_1 dst_unused:UNUSED_PAD src0_sel:DWORD
	v_cvt_i32_f32_e32 v7, v7
	v_mul_f32_e32 v8, v135, v8
	v_rndne_f32_e32 v9, v9
	v_mul_f32_e32 v10, v135, v10
	v_mul_f32_e32 v11, v135, v11
	v_rndne_f32_e32 v8, v8
	v_cvt_i32_f32_e32 v9, v9
	v_rndne_f32_e32 v10, v10
	v_rndne_f32_e32 v11, v11
	v_cvt_i32_f32_e32 v8, v8
	v_cvt_i32_f32_sdwa v10, v10 dst_sel:WORD_1 dst_unused:UNUSED_PAD src0_sel:DWORD
	v_cvt_i32_f32_e32 v11, v11
	v_lshlrev_b32_e32 v5, 8, v5
	v_and_b32_e32 v5, 0xff00, v5
	v_and_b32_e32 v6, 0xff0000, v6
	v_perm_b32 v4, v7, v4, s81
	v_or3_b32 v4, v4, v5, v6
	v_lshlrev_b32_e32 v5, 8, v9
	s_mov_b64 s[2:3], 0xc0
	v_and_b32_e32 v5, 0xff00, v5
	v_and_b32_e32 v6, 0xff0000, v10
	v_perm_b32 v7, v11, v8, s81
	v_lshl_add_u64 v[2:3], v[0:1], 0, s[2:3]
	v_or3_b32 v5, v7, v5, v6
	global_store_dwordx2 v[2:3], v[4:5], off
	v_and_b32_e32 v5, 0xffff0000, v99
	v_cvt_pk_bf16_f32 v108, v108, v112
	v_cvt_pk_bf16_f32 v112, v115, v119
	v_lshlrev_b32_e32 v4, 16, v99
	v_mul_f32_e32 v5, v134, v5
	v_lshlrev_b32_e32 v6, 16, v107
	v_and_b32_e32 v7, 0xffff0000, v107
	v_cvt_pk_bf16_f32 v100, v100, v104
	v_cvt_pk_bf16_f32 v104, v123, v127
	v_mul_f32_e32 v4, v134, v4
	v_rndne_f32_e32 v5, v5
	v_mul_f32_e32 v6, v134, v6
	v_mul_f32_e32 v7, v134, v7
	v_and_b32_e32 v9, 0xffff0000, v112
	v_rndne_f32_e32 v4, v4
	v_cvt_i32_f32_e32 v5, v5
	v_rndne_f32_e32 v6, v6
	v_rndne_f32_e32 v7, v7
	v_lshlrev_b32_e32 v8, 16, v112
	v_mul_f32_e32 v9, v134, v9
	v_lshlrev_b32_e32 v10, 16, v104
	v_and_b32_e32 v11, 0xffff0000, v104
	v_cvt_i32_f32_e32 v4, v4
; #define LAS __attribute__((address_space(3)))
; __device__ __forceinline__ float bflo(unsigned w) { return __uint_as_float(w << 16); }
; __device__ __forceinline__ float bfhi(unsigned w) { return __uint_as_float(w & 0xffff0000u); }
; __device__ __forceinline__ void direct_w8_block(const Ctx& c, LAS unsigned char* lds, const float* Wsrc, const int INC_, int srccol, unsigned char* dstrow, float* swdst) {
;     ...
; #pragma unroll
;     for (int t = 0; t < 8; ++t) { unsigned char* dt = dst + t * 64; asm volatile("" : "+v"(dt));
; #pragma unroll
;         for (int j = 0; j < 4; ++j) { v4u pk;
;             if (t < 4) { pk.x = held[t & 3][j][0]; pk.y = held[t & 3][j][1]; pk.z = held[t & 3][j][2]; pk.w = held[t & 3][j][3]; }
;             else pk = *(const LAS v4u*)(hl + ((t - 4) * 4 + j) * 1024);
;             int qi[8];
; #pragma unroll
;             for (int pr = 0; pr < 4; ++pr) { qi[2 * pr] = __float2int_rn(bflo(pk[pr]) * inv[j]); qi[2 * pr + 1] = __float2int_rn(bfhi(pk[pr]) * inv[j]); }
;             v2u w; w.x = (unsigned)(qi[0] & 255) | ((unsigned)(qi[1] & 255) << 8) | ((unsigned)(qi[2] & 255) << 16) | ((unsigned)(qi[3] & 255) << 24);
;             w.y = (unsigned)(qi[4] & 255) | ((unsigned)(qi[5] & 255) << 8) | ((unsigned)(qi[6] & 255) << 16) | ((unsigned)(qi[7] & 255) << 24);
;             *(v2u*)(dt + (size_t)j * DM) = w; } }
; __device__ __forceinline__ void phase_tail_transposes(LAS unsigned char* lds, int part, int wv) {
;     ...
;         for (int cb = c.vcu - 192; cb < NT0; cb += 64) direct_win_block(c, lds, 1, cb);
	v_cvt_i32_f32_sdwa v6, v6 dst_sel:WORD_1 dst_unused:UNUSED_PAD src0_sel:DWORD
	v_cvt_i32_f32_e32 v7, v7
	v_mul_f32_e32 v8, v134, v8
	v_rndne_f32_e32 v9, v9
	v_mul_f32_e32 v10, v134, v10
	v_mul_f32_e32 v11, v134, v11
	v_rndne_f32_e32 v8, v8
	v_cvt_i32_f32_e32 v9, v9
	v_rndne_f32_e32 v10, v10
	v_rndne_f32_e32 v11, v11
	v_cvt_i32_f32_e32 v8, v8
	v_cvt_i32_f32_sdwa v10, v10 dst_sel:WORD_1 dst_unused:UNUSED_PAD src0_sel:DWORD
	v_cvt_i32_f32_e32 v11, v11
	v_lshlrev_b32_e32 v5, 8, v5
	v_and_b32_e32 v5, 0xff00, v5
	v_and_b32_e32 v6, 0xff0000, v6
	v_perm_b32 v4, v7, v4, s81
	v_or3_b32 v4, v4, v5, v6
	v_lshlrev_b32_e32 v5, 8, v9
	v_and_b32_e32 v5, 0xff00, v5
	v_and_b32_e32 v6, 0xff0000, v10
	v_perm_b32 v7, v11, v8, s81
	v_or3_b32 v5, v7, v5, v6
	v_add_co_u32_e32 v6, vcc, s67, v2
	v_cvt_pk_bf16_f32 v109, v109, v113
	s_nop 0
	v_addc_co_u32_e32 v7, vcc, 0, v3, vcc
	global_store_dwordx2 v[6:7], v[4:5], off
	v_and_b32_e32 v5, 0xffff0000, v100
	v_cvt_pk_bf16_f32 v113, v116, v120
	v_lshlrev_b32_e32 v4, 16, v100
	v_mul_f32_e32 v5, v131, v5
	v_lshlrev_b32_e32 v6, 16, v108
	v_and_b32_e32 v7, 0xffff0000, v108
	v_cvt_pk_bf16_f32 v101, v101, v105
	v_cvt_pk_bf16_f32 v105, v124, v128
	v_mul_f32_e32 v4, v131, v4
	v_rndne_f32_e32 v5, v5
	v_mul_f32_e32 v6, v131, v6
	v_mul_f32_e32 v7, v131, v7
	v_and_b32_e32 v9, 0xffff0000, v113
	v_rndne_f32_e32 v4, v4
	v_cvt_i32_f32_e32 v5, v5
	v_rndne_f32_e32 v6, v6
	v_rndne_f32_e32 v7, v7
	v_lshlrev_b32_e32 v8, 16, v113
	v_mul_f32_e32 v9, v131, v9
	v_lshlrev_b32_e32 v10, 16, v105
	v_and_b32_e32 v11, 0xffff0000, v105
	v_cvt_i32_f32_e32 v4, v4
	v_cvt_i32_f32_sdwa v6, v6 dst_sel:WORD_1 dst_unused:UNUSED_PAD src0_sel:DWORD
	v_cvt_i32_f32_e32 v7, v7
	v_mul_f32_e32 v8, v131, v8
	v_rndne_f32_e32 v9, v9
	v_mul_f32_e32 v10, v131, v10
	v_mul_f32_e32 v11, v131, v11
	v_rndne_f32_e32 v8, v8
	v_cvt_i32_f32_e32 v9, v9
	v_rndne_f32_e32 v10, v10
	v_rndne_f32_e32 v11, v11
	v_cvt_i32_f32_e32 v8, v8
	v_cvt_i32_f32_sdwa v10, v10 dst_sel:WORD_1 dst_unused:UNUSED_PAD src0_sel:DWORD
	v_cvt_i32_f32_e32 v11, v11
	v_lshlrev_b32_e32 v5, 8, v5
	v_and_b32_e32 v5, 0xff00, v5
	v_and_b32_e32 v6, 0xff0000, v6
	v_perm_b32 v4, v7, v4, s81
	v_or3_b32 v4, v4, v5, v6
	v_lshlrev_b32_e32 v5, 8, v9
	v_and_b32_e32 v5, 0xff00, v5
	v_and_b32_e32 v6, 0xff0000, v10
	v_perm_b32 v7, v11, v8, s81
	v_or3_b32 v5, v7, v5, v6
	v_add_co_u32_e32 v6, vcc, s33, v2
	v_cvt_pk_bf16_f32 v117, v117, v121
	s_nop 0
	v_addc_co_u32_e32 v7, vcc, 0, v3, vcc
	global_store_dwordx2 v[6:7], v[4:5], off
	v_and_b32_e32 v5, 0xffff0000, v101
	v_lshlrev_b32_e32 v4, 16, v101
	v_mul_f32_e32 v5, v130, v5
	v_lshlrev_b32_e32 v6, 16, v109
	v_and_b32_e32 v7, 0xffff0000, v109
	v_cvt_pk_bf16_f32 v125, v125, v129
	v_mul_f32_e32 v4, v130, v4
	v_rndne_f32_e32 v5, v5
	v_mul_f32_e32 v6, v130, v6
	v_mul_f32_e32 v7, v130, v7
	v_and_b32_e32 v9, 0xffff0000, v117
	v_rndne_f32_e32 v4, v4
	v_cvt_i32_f32_e32 v5, v5
	v_rndne_f32_e32 v6, v6
	v_rndne_f32_e32 v7, v7
	v_lshlrev_b32_e32 v8, 16, v117
	v_mul_f32_e32 v9, v130, v9
	v_lshlrev_b32_e32 v10, 16, v125
	v_and_b32_e32 v11, 0xffff0000, v125
	v_cvt_i32_f32_e32 v4, v4
	v_cvt_i32_f32_sdwa v6, v6 dst_sel:WORD_1 dst_unused:UNUSED_PAD src0_sel:DWORD
	v_cvt_i32_f32_e32 v7, v7
	v_mul_f32_e32 v8, v130, v8
	v_rndne_f32_e32 v9, v9
	v_mul_f32_e32 v10, v130, v10
	v_mul_f32_e32 v11, v130, v11
	v_rndne_f32_e32 v8, v8
	v_cvt_i32_f32_e32 v9, v9
	v_rndne_f32_e32 v10, v10
	v_rndne_f32_e32 v11, v11
	v_cvt_i32_f32_e32 v8, v8
	v_cvt_i32_f32_sdwa v10, v10 dst_sel:WORD_1 dst_unused:UNUSED_PAD src0_sel:DWORD
	v_cvt_i32_f32_e32 v11, v11
	v_lshlrev_b32_e32 v5, 8, v5
	v_and_b32_e32 v5, 0xff00, v5
	v_and_b32_e32 v6, 0xff0000, v6
	v_perm_b32 v4, v7, v4, s81
	v_or3_b32 v4, v4, v5, v6
	v_lshlrev_b32_e32 v5, 8, v9
	v_and_b32_e32 v5, 0xff00, v5
	v_and_b32_e32 v6, 0xff0000, v10
	v_perm_b32 v7, v11, v8, s81
	v_add_co_u32_e32 v2, vcc, s44, v2
	s_mov_b64 s[2:3], 0x100
	v_or3_b32 v5, v7, v5, v6
	v_addc_co_u32_e32 v3, vcc, 0, v3, vcc
	v_lshl_add_u64 v[6:7], v[0:1], 0, s[2:3]
	global_store_dwordx2 v[2:3], v[4:5], off
	ds_read_b128 v[2:5], v96
	s_mov_b64 s[2:3], 0x140
	s_add_i32 s1, s1, 64
	s_addk_i32 s10, 0x800
	s_cmp_gt_i32 s1, -1
	s_waitcnt lgkmcnt(0)
	v_lshlrev_b32_e32 v8, 16, v2
	v_and_b32_e32 v2, 0xffff0000, v2
	v_mul_f32_e32 v2, v135, v2
	v_lshlrev_b32_e32 v9, 16, v3
	v_and_b32_e32 v3, 0xffff0000, v3
	v_mul_f32_e32 v8, v135, v8
	v_rndne_f32_e32 v2, v2
	v_mul_f32_e32 v9, v135, v9
	v_mul_f32_e32 v3, v135, v3
	v_lshlrev_b32_e32 v10, 16, v4
	v_and_b32_e32 v4, 0xffff0000, v4
	v_rndne_f32_e32 v8, v8
	v_cvt_i32_f32_e32 v2, v2
	v_rndne_f32_e32 v9, v9
	v_rndne_f32_e32 v3, v3
	v_mul_f32_e32 v4, v135, v4
	v_lshlrev_b32_e32 v11, 16, v5
	v_and_b32_e32 v5, 0xffff0000, v5
	v_cvt_i32_f32_e32 v8, v8
	v_cvt_i32_f32_sdwa v9, v9 dst_sel:WORD_1 dst_unused:UNUSED_PAD src0_sel:DWORD
	v_cvt_i32_f32_e32 v3, v3
	v_mul_f32_e32 v10, v135, v10
	v_rndne_f32_e32 v4, v4
	v_mul_f32_e32 v11, v135, v11
	v_mul_f32_e32 v5, v135, v5
	v_rndne_f32_e32 v10, v10
	v_cvt_i32_f32_e32 v4, v4
	v_rndne_f32_e32 v11, v11
	v_rndne_f32_e32 v5, v5
	v_cvt_i32_f32_e32 v10, v10
	v_cvt_i32_f32_sdwa v11, v11 dst_sel:WORD_1 dst_unused:UNUSED_PAD src0_sel:DWORD
	v_cvt_i32_f32_e32 v5, v5
	v_lshlrev_b32_e32 v2, 8, v2
	v_and_b32_e32 v2, 0xff00, v2
	v_and_b32_e32 v9, 0xff0000, v9
	v_perm_b32 v3, v3, v8, s81
	v_or3_b32 v2, v3, v2, v9
	v_lshlrev_b32_e32 v3, 8, v4
	v_and_b32_e32 v3, 0xff00, v3
	v_and_b32_e32 v4, 0xff0000, v11
	v_perm_b32 v5, v5, v10, s81
	v_or3_b32 v3, v5, v3, v4
	global_store_dwordx2 v[6:7], v[2:3], off
	ds_read_b128 v[2:5], v96 offset:1024
	s_waitcnt lgkmcnt(0)
; #define LAS __attribute__((address_space(3)))
; __device__ __forceinline__ float bflo(unsigned w) { return __uint_as_float(w << 16); }
; __device__ __forceinline__ float bfhi(unsigned w) { return __uint_as_float(w & 0xffff0000u); }
; __device__ __forceinline__ void direct_w8_block(const Ctx& c, LAS unsigned char* lds, const float* Wsrc, const int INC_, int srccol, unsigned char* dstrow, float* swdst) {
;     ...
; #pragma unroll
;     for (int t = 0; t < 8; ++t) { unsigned char* dt = dst + t * 64; asm volatile("" : "+v"(dt));
; #pragma unroll
;         for (int j = 0; j < 4; ++j) { v4u pk;
;             if (t < 4) { pk.x = held[t & 3][j][0]; pk.y = held[t & 3][j][1]; pk.z = held[t & 3][j][2]; pk.w = held[t & 3][j][3]; }
;             else pk = *(const LAS v4u*)(hl + ((t - 4) * 4 + j) * 1024);
;             int qi[8];
; #pragma unroll
;             for (int pr = 0; pr < 4; ++pr) { qi[2 * pr] = __float2int_rn(bflo(pk[pr]) * inv[j]); qi[2 * pr + 1] = __float2int_rn(bfhi(pk[pr]) * inv[j]); }
;             v2u w; w.x = (unsigned)(qi[0] & 255) | ((unsigned)(qi[1] & 255) << 8) | ((unsigned)(qi[2] & 255) << 16) | ((unsigned)(qi[3] & 255) << 24);
;             w.y = (unsigned)(qi[4] & 255) | ((unsigned)(qi[5] & 255) << 8) | ((unsigned)(qi[6] & 255) << 16) | ((unsigned)(qi[7] & 255) << 24);
;             *(v2u*)(dt + (size_t)j * DM) = w; } }
	v_lshlrev_b32_e32 v8, 16, v2
	v_and_b32_e32 v2, 0xffff0000, v2
	v_mul_f32_e32 v2, v134, v2
	v_lshlrev_b32_e32 v9, 16, v3
	v_and_b32_e32 v3, 0xffff0000, v3
	v_mul_f32_e32 v8, v134, v8
	v_rndne_f32_e32 v2, v2
	v_mul_f32_e32 v9, v134, v9
	v_mul_f32_e32 v3, v134, v3
	v_lshlrev_b32_e32 v10, 16, v4
	v_and_b32_e32 v4, 0xffff0000, v4
	v_rndne_f32_e32 v8, v8
	v_cvt_i32_f32_e32 v2, v2
	v_rndne_f32_e32 v9, v9
	v_rndne_f32_e32 v3, v3
	v_mul_f32_e32 v4, v134, v4
	v_lshlrev_b32_e32 v11, 16, v5
	v_and_b32_e32 v5, 0xffff0000, v5
	v_cvt_i32_f32_e32 v8, v8
	v_cvt_i32_f32_sdwa v9, v9 dst_sel:WORD_1 dst_unused:UNUSED_PAD src0_sel:DWORD
	v_cvt_i32_f32_e32 v3, v3
	v_mul_f32_e32 v10, v134, v10
	v_rndne_f32_e32 v4, v4
	v_mul_f32_e32 v11, v134, v11
	v_mul_f32_e32 v5, v134, v5
	v_rndne_f32_e32 v10, v10
	v_cvt_i32_f32_e32 v4, v4
	v_rndne_f32_e32 v11, v11
	v_rndne_f32_e32 v5, v5
	v_cvt_i32_f32_e32 v10, v10
	v_cvt_i32_f32_sdwa v11, v11 dst_sel:WORD_1 dst_unused:UNUSED_PAD src0_sel:DWORD
	v_cvt_i32_f32_e32 v5, v5
	v_lshlrev_b32_e32 v2, 8, v2
	v_and_b32_e32 v2, 0xff00, v2
	v_and_b32_e32 v9, 0xff0000, v9
	v_perm_b32 v3, v3, v8, s81
	v_or3_b32 v2, v3, v2, v9
	v_lshlrev_b32_e32 v3, 8, v4
	v_and_b32_e32 v3, 0xff00, v3
	v_and_b32_e32 v4, 0xff0000, v11
	v_perm_b32 v5, v5, v10, s81
	v_or3_b32 v3, v5, v3, v4
	v_add_co_u32_e32 v4, vcc, s67, v6
	s_nop 1
	v_addc_co_u32_e32 v5, vcc, 0, v7, vcc
	global_store_dwordx2 v[4:5], v[2:3], off
	ds_read_b128 v[2:5], v96 offset:2048
	s_waitcnt lgkmcnt(0)
	v_lshlrev_b32_e32 v8, 16, v2
	v_and_b32_e32 v2, 0xffff0000, v2
	v_mul_f32_e32 v2, v131, v2
	v_lshlrev_b32_e32 v9, 16, v3
	v_and_b32_e32 v3, 0xffff0000, v3
	v_mul_f32_e32 v8, v131, v8
	v_rndne_f32_e32 v2, v2
	v_mul_f32_e32 v9, v131, v9
	v_mul_f32_e32 v3, v131, v3
	v_lshlrev_b32_e32 v10, 16, v4
	v_and_b32_e32 v4, 0xffff0000, v4
	v_rndne_f32_e32 v8, v8
	v_cvt_i32_f32_e32 v2, v2
	v_rndne_f32_e32 v9, v9
	v_rndne_f32_e32 v3, v3
	v_mul_f32_e32 v4, v131, v4
	v_lshlrev_b32_e32 v11, 16, v5
	v_and_b32_e32 v5, 0xffff0000, v5
	v_cvt_i32_f32_e32 v8, v8
	v_cvt_i32_f32_sdwa v9, v9 dst_sel:WORD_1 dst_unused:UNUSED_PAD src0_sel:DWORD
	v_cvt_i32_f32_e32 v3, v3
	v_mul_f32_e32 v10, v131, v10
	v_rndne_f32_e32 v4, v4
	v_mul_f32_e32 v11, v131, v11
	v_mul_f32_e32 v5, v131, v5
	v_rndne_f32_e32 v10, v10
	v_cvt_i32_f32_e32 v4, v4
	v_rndne_f32_e32 v11, v11
	v_rndne_f32_e32 v5, v5
	v_cvt_i32_f32_e32 v10, v10
	v_cvt_i32_f32_sdwa v11, v11 dst_sel:WORD_1 dst_unused:UNUSED_PAD src0_sel:DWORD
	v_cvt_i32_f32_e32 v5, v5
	v_lshlrev_b32_e32 v2, 8, v2
	v_and_b32_e32 v2, 0xff00, v2
	v_and_b32_e32 v9, 0xff0000, v9
	v_perm_b32 v3, v3, v8, s81
	v_or3_b32 v2, v3, v2, v9
	v_lshlrev_b32_e32 v3, 8, v4
	v_and_b32_e32 v3, 0xff00, v3
	v_and_b32_e32 v4, 0xff0000, v11
	v_perm_b32 v5, v5, v10, s81
	v_or3_b32 v3, v5, v3, v4
	v_add_co_u32_e32 v4, vcc, s33, v6
	s_nop 1
	v_addc_co_u32_e32 v5, vcc, 0, v7, vcc
	global_store_dwordx2 v[4:5], v[2:3], off
	ds_read_b128 v[2:5], v96 offset:3072
	s_waitcnt lgkmcnt(0)
	v_lshlrev_b32_e32 v8, 16, v2
	v_and_b32_e32 v2, 0xffff0000, v2
	v_mul_f32_e32 v2, v130, v2
	v_lshlrev_b32_e32 v9, 16, v3
	v_and_b32_e32 v3, 0xffff0000, v3
	v_mul_f32_e32 v8, v130, v8
	v_rndne_f32_e32 v2, v2
	v_mul_f32_e32 v9, v130, v9
	v_mul_f32_e32 v3, v130, v3
	v_lshlrev_b32_e32 v10, 16, v4
	v_and_b32_e32 v4, 0xffff0000, v4
	v_rndne_f32_e32 v8, v8
	v_cvt_i32_f32_e32 v2, v2
	v_rndne_f32_e32 v9, v9
	v_rndne_f32_e32 v3, v3
	v_mul_f32_e32 v4, v130, v4
	v_lshlrev_b32_e32 v11, 16, v5
	v_and_b32_e32 v5, 0xffff0000, v5
	v_cvt_i32_f32_e32 v8, v8
	v_cvt_i32_f32_sdwa v9, v9 dst_sel:WORD_1 dst_unused:UNUSED_PAD src0_sel:DWORD
	v_cvt_i32_f32_e32 v3, v3
	v_mul_f32_e32 v10, v130, v10
	v_rndne_f32_e32 v4, v4
	v_mul_f32_e32 v11, v130, v11
	v_mul_f32_e32 v5, v130, v5
	v_rndne_f32_e32 v10, v10
	v_cvt_i32_f32_e32 v4, v4
	v_rndne_f32_e32 v11, v11
	v_rndne_f32_e32 v5, v5
	v_cvt_i32_f32_e32 v10, v10
	v_cvt_i32_f32_sdwa v11, v11 dst_sel:WORD_1 dst_unused:UNUSED_PAD src0_sel:DWORD
	v_cvt_i32_f32_e32 v5, v5
	v_lshlrev_b32_e32 v2, 8, v2
	v_and_b32_e32 v2, 0xff00, v2
	v_and_b32_e32 v9, 0xff0000, v9
	v_perm_b32 v3, v3, v8, s81
	v_or3_b32 v2, v3, v2, v9
	v_lshlrev_b32_e32 v3, 8, v4
	v_and_b32_e32 v3, 0xff00, v3
	v_and_b32_e32 v4, 0xff0000, v11
	v_perm_b32 v5, v5, v10, s81
	v_or3_b32 v3, v5, v3, v4
	v_add_co_u32_e32 v4, vcc, s44, v6
	s_nop 1
	v_addc_co_u32_e32 v5, vcc, 0, v7, vcc
	v_lshl_add_u64 v[6:7], v[0:1], 0, s[2:3]
	global_store_dwordx2 v[4:5], v[2:3], off
	ds_read_b128 v[2:5], v96 offset:4096
	s_mov_b64 s[2:3], 0x180
	s_waitcnt lgkmcnt(0)
	v_lshlrev_b32_e32 v8, 16, v2
	v_and_b32_e32 v2, 0xffff0000, v2
	v_mul_f32_e32 v2, v135, v2
	v_lshlrev_b32_e32 v9, 16, v3
	v_and_b32_e32 v3, 0xffff0000, v3
	v_mul_f32_e32 v8, v135, v8
	v_rndne_f32_e32 v2, v2
	v_mul_f32_e32 v9, v135, v9
	v_mul_f32_e32 v3, v135, v3
	v_lshlrev_b32_e32 v10, 16, v4
	v_and_b32_e32 v4, 0xffff0000, v4
	v_rndne_f32_e32 v8, v8
	v_cvt_i32_f32_e32 v2, v2
	v_rndne_f32_e32 v9, v9
	v_rndne_f32_e32 v3, v3
	v_mul_f32_e32 v4, v135, v4
	v_lshlrev_b32_e32 v11, 16, v5
	v_and_b32_e32 v5, 0xffff0000, v5
	v_cvt_i32_f32_e32 v8, v8
	v_cvt_i32_f32_sdwa v9, v9 dst_sel:WORD_1 dst_unused:UNUSED_PAD src0_sel:DWORD
	v_cvt_i32_f32_e32 v3, v3
	v_mul_f32_e32 v10, v135, v10
	v_rndne_f32_e32 v4, v4
	v_mul_f32_e32 v11, v135, v11
	v_mul_f32_e32 v5, v135, v5
	v_rndne_f32_e32 v10, v10
	v_cvt_i32_f32_e32 v4, v4
	v_rndne_f32_e32 v11, v11
	v_rndne_f32_e32 v5, v5
	v_cvt_i32_f32_e32 v10, v10
	v_cvt_i32_f32_sdwa v11, v11 dst_sel:WORD_1 dst_unused:UNUSED_PAD src0_sel:DWORD
	v_cvt_i32_f32_e32 v5, v5
	v_lshlrev_b32_e32 v2, 8, v2
	v_and_b32_e32 v2, 0xff00, v2
	v_and_b32_e32 v9, 0xff0000, v9
	v_perm_b32 v3, v3, v8, s81
	v_or3_b32 v2, v3, v2, v9
	v_lshlrev_b32_e32 v3, 8, v4
	v_and_b32_e32 v3, 0xff00, v3
	v_and_b32_e32 v4, 0xff0000, v11
	v_perm_b32 v5, v5, v10, s81
	v_or3_b32 v3, v5, v3, v4
	global_store_dwordx2 v[6:7], v[2:3], off
	ds_read_b128 v[2:5], v96 offset:5120
	s_waitcnt lgkmcnt(0)
; #define LAS __attribute__((address_space(3)))
; __device__ __forceinline__ float bflo(unsigned w) { return __uint_as_float(w << 16); }
; __device__ __forceinline__ float bfhi(unsigned w) { return __uint_as_float(w & 0xffff0000u); }
; __device__ __forceinline__ void direct_w8_block(const Ctx& c, LAS unsigned char* lds, const float* Wsrc, const int INC_, int srccol, unsigned char* dstrow, float* swdst) {
;     ...
; #pragma unroll
;     for (int t = 0; t < 8; ++t) { unsigned char* dt = dst + t * 64; asm volatile("" : "+v"(dt));
; #pragma unroll
;         for (int j = 0; j < 4; ++j) { v4u pk;
;             if (t < 4) { pk.x = held[t & 3][j][0]; pk.y = held[t & 3][j][1]; pk.z = held[t & 3][j][2]; pk.w = held[t & 3][j][3]; }
;             else pk = *(const LAS v4u*)(hl + ((t - 4) * 4 + j) * 1024);
;             int qi[8];
; #pragma unroll
;             for (int pr = 0; pr < 4; ++pr) { qi[2 * pr] = __float2int_rn(bflo(pk[pr]) * inv[j]); qi[2 * pr + 1] = __float2int_rn(bfhi(pk[pr]) * inv[j]); }
;             v2u w; w.x = (unsigned)(qi[0] & 255) | ((unsigned)(qi[1] & 255) << 8) | ((unsigned)(qi[2] & 255) << 16) | ((unsigned)(qi[3] & 255) << 24);
;             w.y = (unsigned)(qi[4] & 255) | ((unsigned)(qi[5] & 255) << 8) | ((unsigned)(qi[6] & 255) << 16) | ((unsigned)(qi[7] & 255) << 24);
;             *(v2u*)(dt + (size_t)j * DM) = w; } }
	v_lshlrev_b32_e32 v8, 16, v2
	v_and_b32_e32 v2, 0xffff0000, v2
	v_mul_f32_e32 v2, v134, v2
	v_lshlrev_b32_e32 v9, 16, v3
	v_and_b32_e32 v3, 0xffff0000, v3
	v_mul_f32_e32 v8, v134, v8
	v_rndne_f32_e32 v2, v2
	v_mul_f32_e32 v9, v134, v9
	v_mul_f32_e32 v3, v134, v3
	v_lshlrev_b32_e32 v10, 16, v4
	v_and_b32_e32 v4, 0xffff0000, v4
	v_rndne_f32_e32 v8, v8
	v_cvt_i32_f32_e32 v2, v2
	v_rndne_f32_e32 v9, v9
	v_rndne_f32_e32 v3, v3
	v_mul_f32_e32 v4, v134, v4
	v_lshlrev_b32_e32 v11, 16, v5
	v_and_b32_e32 v5, 0xffff0000, v5
	v_cvt_i32_f32_e32 v8, v8
	v_cvt_i32_f32_sdwa v9, v9 dst_sel:WORD_1 dst_unused:UNUSED_PAD src0_sel:DWORD
	v_cvt_i32_f32_e32 v3, v3
	v_mul_f32_e32 v10, v134, v10
	v_rndne_f32_e32 v4, v4
	v_mul_f32_e32 v11, v134, v11
	v_mul_f32_e32 v5, v134, v5
	v_rndne_f32_e32 v10, v10
	v_cvt_i32_f32_e32 v4, v4
	v_rndne_f32_e32 v11, v11
	v_rndne_f32_e32 v5, v5
	v_cvt_i32_f32_e32 v10, v10
	v_cvt_i32_f32_sdwa v11, v11 dst_sel:WORD_1 dst_unused:UNUSED_PAD src0_sel:DWORD
	v_cvt_i32_f32_e32 v5, v5
	v_lshlrev_b32_e32 v2, 8, v2
	v_and_b32_e32 v2, 0xff00, v2
	v_and_b32_e32 v9, 0xff0000, v9
	v_perm_b32 v3, v3, v8, s81
	v_or3_b32 v2, v3, v2, v9
	v_lshlrev_b32_e32 v3, 8, v4
	v_and_b32_e32 v3, 0xff00, v3
	v_and_b32_e32 v4, 0xff0000, v11
	v_perm_b32 v5, v5, v10, s81
	v_or3_b32 v3, v5, v3, v4
	v_add_co_u32_e32 v4, vcc, s67, v6
	s_nop 1
	v_addc_co_u32_e32 v5, vcc, 0, v7, vcc
	global_store_dwordx2 v[4:5], v[2:3], off
	ds_read_b128 v[2:5], v96 offset:6144
	s_waitcnt lgkmcnt(0)
	v_lshlrev_b32_e32 v8, 16, v2
	v_and_b32_e32 v2, 0xffff0000, v2
	v_mul_f32_e32 v2, v131, v2
	v_lshlrev_b32_e32 v9, 16, v3
	v_and_b32_e32 v3, 0xffff0000, v3
	v_mul_f32_e32 v8, v131, v8
	v_rndne_f32_e32 v2, v2
	v_mul_f32_e32 v9, v131, v9
	v_mul_f32_e32 v3, v131, v3
	v_lshlrev_b32_e32 v10, 16, v4
	v_and_b32_e32 v4, 0xffff0000, v4
	v_rndne_f32_e32 v8, v8
	v_cvt_i32_f32_e32 v2, v2
	v_rndne_f32_e32 v9, v9
	v_rndne_f32_e32 v3, v3
	v_mul_f32_e32 v4, v131, v4
	v_lshlrev_b32_e32 v11, 16, v5
	v_and_b32_e32 v5, 0xffff0000, v5
	v_cvt_i32_f32_e32 v8, v8
	v_cvt_i32_f32_sdwa v9, v9 dst_sel:WORD_1 dst_unused:UNUSED_PAD src0_sel:DWORD
	v_cvt_i32_f32_e32 v3, v3
	v_mul_f32_e32 v10, v131, v10
	v_rndne_f32_e32 v4, v4
	v_mul_f32_e32 v11, v131, v11
	v_mul_f32_e32 v5, v131, v5
	v_rndne_f32_e32 v10, v10
	v_cvt_i32_f32_e32 v4, v4
	v_rndne_f32_e32 v11, v11
	v_rndne_f32_e32 v5, v5
	v_cvt_i32_f32_e32 v10, v10
	v_cvt_i32_f32_sdwa v11, v11 dst_sel:WORD_1 dst_unused:UNUSED_PAD src0_sel:DWORD
	v_cvt_i32_f32_e32 v5, v5
	v_lshlrev_b32_e32 v2, 8, v2
	v_and_b32_e32 v2, 0xff00, v2
	v_and_b32_e32 v9, 0xff0000, v9
	v_perm_b32 v3, v3, v8, s81
	v_or3_b32 v2, v3, v2, v9
	v_lshlrev_b32_e32 v3, 8, v4
	v_and_b32_e32 v3, 0xff00, v3
	v_and_b32_e32 v4, 0xff0000, v11
	v_perm_b32 v5, v5, v10, s81
	v_or3_b32 v3, v5, v3, v4
	v_add_co_u32_e32 v4, vcc, s33, v6
	s_nop 1
	v_addc_co_u32_e32 v5, vcc, 0, v7, vcc
	global_store_dwordx2 v[4:5], v[2:3], off
	ds_read_b128 v[2:5], v96 offset:7168
	s_waitcnt lgkmcnt(0)
	v_lshlrev_b32_e32 v8, 16, v2
	v_and_b32_e32 v2, 0xffff0000, v2
	v_mul_f32_e32 v2, v130, v2
	v_lshlrev_b32_e32 v9, 16, v3
	v_and_b32_e32 v3, 0xffff0000, v3
	v_mul_f32_e32 v8, v130, v8
	v_rndne_f32_e32 v2, v2
	v_mul_f32_e32 v9, v130, v9
	v_mul_f32_e32 v3, v130, v3
	v_lshlrev_b32_e32 v10, 16, v4
	v_and_b32_e32 v4, 0xffff0000, v4
	v_rndne_f32_e32 v8, v8
	v_cvt_i32_f32_e32 v2, v2
	v_rndne_f32_e32 v9, v9
	v_rndne_f32_e32 v3, v3
	v_mul_f32_e32 v4, v130, v4
	v_lshlrev_b32_e32 v11, 16, v5
	v_and_b32_e32 v5, 0xffff0000, v5
	v_cvt_i32_f32_e32 v8, v8
	v_cvt_i32_f32_sdwa v9, v9 dst_sel:WORD_1 dst_unused:UNUSED_PAD src0_sel:DWORD
	v_cvt_i32_f32_e32 v3, v3
	v_mul_f32_e32 v10, v130, v10
	v_rndne_f32_e32 v4, v4
	v_mul_f32_e32 v11, v130, v11
	v_mul_f32_e32 v5, v130, v5
	v_rndne_f32_e32 v10, v10
	v_cvt_i32_f32_e32 v4, v4
	v_rndne_f32_e32 v11, v11
	v_rndne_f32_e32 v5, v5
	v_cvt_i32_f32_e32 v10, v10
	v_cvt_i32_f32_sdwa v11, v11 dst_sel:WORD_1 dst_unused:UNUSED_PAD src0_sel:DWORD
	v_cvt_i32_f32_e32 v5, v5
	v_lshlrev_b32_e32 v2, 8, v2
	v_and_b32_e32 v2, 0xff00, v2
	v_and_b32_e32 v9, 0xff0000, v9
	v_perm_b32 v3, v3, v8, s81
	v_or3_b32 v2, v3, v2, v9
	v_lshlrev_b32_e32 v3, 8, v4
	v_and_b32_e32 v3, 0xff00, v3
	v_and_b32_e32 v4, 0xff0000, v11
	v_perm_b32 v5, v5, v10, s81
	v_or3_b32 v3, v5, v3, v4
	v_add_co_u32_e32 v4, vcc, s44, v6
	s_nop 1
	v_addc_co_u32_e32 v5, vcc, 0, v7, vcc
	v_lshl_add_u64 v[6:7], v[0:1], 0, s[2:3]
	global_store_dwordx2 v[4:5], v[2:3], off
	ds_read_b128 v[2:5], v96 offset:8192
	s_mov_b64 s[2:3], 0x1c0
	s_waitcnt lgkmcnt(0)
	v_lshlrev_b32_e32 v8, 16, v2
	v_and_b32_e32 v2, 0xffff0000, v2
	v_mul_f32_e32 v2, v135, v2
	v_lshlrev_b32_e32 v9, 16, v3
	v_and_b32_e32 v3, 0xffff0000, v3
	v_mul_f32_e32 v8, v135, v8
	v_rndne_f32_e32 v2, v2
	v_mul_f32_e32 v9, v135, v9
	v_mul_f32_e32 v3, v135, v3
	v_lshlrev_b32_e32 v10, 16, v4
	v_and_b32_e32 v4, 0xffff0000, v4
	v_rndne_f32_e32 v8, v8
	v_cvt_i32_f32_e32 v2, v2
	v_rndne_f32_e32 v9, v9
	v_rndne_f32_e32 v3, v3
	v_mul_f32_e32 v4, v135, v4
	v_lshlrev_b32_e32 v11, 16, v5
	v_and_b32_e32 v5, 0xffff0000, v5
	v_cvt_i32_f32_e32 v8, v8
	v_cvt_i32_f32_sdwa v9, v9 dst_sel:WORD_1 dst_unused:UNUSED_PAD src0_sel:DWORD
	v_cvt_i32_f32_e32 v3, v3
	v_mul_f32_e32 v10, v135, v10
	v_rndne_f32_e32 v4, v4
	v_mul_f32_e32 v11, v135, v11
	v_mul_f32_e32 v5, v135, v5
	v_rndne_f32_e32 v10, v10
	v_cvt_i32_f32_e32 v4, v4
	v_rndne_f32_e32 v11, v11
	v_rndne_f32_e32 v5, v5
	v_cvt_i32_f32_e32 v10, v10
	v_cvt_i32_f32_sdwa v11, v11 dst_sel:WORD_1 dst_unused:UNUSED_PAD src0_sel:DWORD
	v_cvt_i32_f32_e32 v5, v5
	v_lshlrev_b32_e32 v2, 8, v2
	v_and_b32_e32 v2, 0xff00, v2
	v_and_b32_e32 v9, 0xff0000, v9
	v_perm_b32 v3, v3, v8, s81
	v_or3_b32 v2, v3, v2, v9
	v_lshlrev_b32_e32 v3, 8, v4
	v_and_b32_e32 v3, 0xff00, v3
	v_and_b32_e32 v4, 0xff0000, v11
	v_perm_b32 v5, v5, v10, s81
	v_or3_b32 v3, v5, v3, v4
	global_store_dwordx2 v[6:7], v[2:3], off
	ds_read_b128 v[2:5], v96 offset:9216
	s_waitcnt lgkmcnt(0)
; #define LAS __attribute__((address_space(3)))
; __device__ __forceinline__ float bflo(unsigned w) { return __uint_as_float(w << 16); }
; __device__ __forceinline__ float bfhi(unsigned w) { return __uint_as_float(w & 0xffff0000u); }
; __device__ __forceinline__ void direct_w8_block(const Ctx& c, LAS unsigned char* lds, const float* Wsrc, const int INC_, int srccol, unsigned char* dstrow, float* swdst) {
;     ...
; #pragma unroll
;     for (int t = 0; t < 8; ++t) { unsigned char* dt = dst + t * 64; asm volatile("" : "+v"(dt));
; #pragma unroll
;         for (int j = 0; j < 4; ++j) { v4u pk;
;             if (t < 4) { pk.x = held[t & 3][j][0]; pk.y = held[t & 3][j][1]; pk.z = held[t & 3][j][2]; pk.w = held[t & 3][j][3]; }
;             else pk = *(const LAS v4u*)(hl + ((t - 4) * 4 + j) * 1024);
;             int qi[8];
; #pragma unroll
;             for (int pr = 0; pr < 4; ++pr) { qi[2 * pr] = __float2int_rn(bflo(pk[pr]) * inv[j]); qi[2 * pr + 1] = __float2int_rn(bfhi(pk[pr]) * inv[j]); }
;             v2u w; w.x = (unsigned)(qi[0] & 255) | ((unsigned)(qi[1] & 255) << 8) | ((unsigned)(qi[2] & 255) << 16) | ((unsigned)(qi[3] & 255) << 24);
;             w.y = (unsigned)(qi[4] & 255) | ((unsigned)(qi[5] & 255) << 8) | ((unsigned)(qi[6] & 255) << 16) | ((unsigned)(qi[7] & 255) << 24);
;             *(v2u*)(dt + (size_t)j * DM) = w; } }
	v_lshlrev_b32_e32 v8, 16, v2
	v_and_b32_e32 v2, 0xffff0000, v2
	v_mul_f32_e32 v2, v134, v2
	v_lshlrev_b32_e32 v9, 16, v3
	v_and_b32_e32 v3, 0xffff0000, v3
	v_mul_f32_e32 v8, v134, v8
	v_rndne_f32_e32 v2, v2
	v_mul_f32_e32 v9, v134, v9
	v_mul_f32_e32 v3, v134, v3
	v_lshlrev_b32_e32 v10, 16, v4
	v_and_b32_e32 v4, 0xffff0000, v4
	v_rndne_f32_e32 v8, v8
	v_cvt_i32_f32_e32 v2, v2
	v_rndne_f32_e32 v9, v9
	v_rndne_f32_e32 v3, v3
	v_mul_f32_e32 v4, v134, v4
	v_lshlrev_b32_e32 v11, 16, v5
	v_and_b32_e32 v5, 0xffff0000, v5
	v_cvt_i32_f32_e32 v8, v8
	v_cvt_i32_f32_sdwa v9, v9 dst_sel:WORD_1 dst_unused:UNUSED_PAD src0_sel:DWORD
	v_cvt_i32_f32_e32 v3, v3
	v_mul_f32_e32 v10, v134, v10
	v_rndne_f32_e32 v4, v4
	v_mul_f32_e32 v11, v134, v11
	v_mul_f32_e32 v5, v134, v5
	v_rndne_f32_e32 v10, v10
	v_cvt_i32_f32_e32 v4, v4
	v_rndne_f32_e32 v11, v11
	v_rndne_f32_e32 v5, v5
	v_cvt_i32_f32_e32 v10, v10
	v_cvt_i32_f32_sdwa v11, v11 dst_sel:WORD_1 dst_unused:UNUSED_PAD src0_sel:DWORD
	v_cvt_i32_f32_e32 v5, v5
	v_lshlrev_b32_e32 v2, 8, v2
	v_and_b32_e32 v2, 0xff00, v2
	v_and_b32_e32 v9, 0xff0000, v9
	v_perm_b32 v3, v3, v8, s81
	v_or3_b32 v2, v3, v2, v9
	v_lshlrev_b32_e32 v3, 8, v4
	v_and_b32_e32 v3, 0xff00, v3
	v_and_b32_e32 v4, 0xff0000, v11
	v_perm_b32 v5, v5, v10, s81
	v_or3_b32 v3, v5, v3, v4
	v_add_co_u32_e32 v4, vcc, s67, v6
	s_nop 1
	v_addc_co_u32_e32 v5, vcc, 0, v7, vcc
	global_store_dwordx2 v[4:5], v[2:3], off
	ds_read_b128 v[2:5], v96 offset:10240
	s_waitcnt lgkmcnt(0)
	v_lshlrev_b32_e32 v8, 16, v2
	v_and_b32_e32 v2, 0xffff0000, v2
	v_mul_f32_e32 v2, v131, v2
	v_lshlrev_b32_e32 v9, 16, v3
	v_and_b32_e32 v3, 0xffff0000, v3
	v_mul_f32_e32 v8, v131, v8
	v_rndne_f32_e32 v2, v2
	v_mul_f32_e32 v9, v131, v9
	v_mul_f32_e32 v3, v131, v3
	v_lshlrev_b32_e32 v10, 16, v4
	v_and_b32_e32 v4, 0xffff0000, v4
	v_rndne_f32_e32 v8, v8
	v_cvt_i32_f32_e32 v2, v2
	v_rndne_f32_e32 v9, v9
	v_rndne_f32_e32 v3, v3
	v_mul_f32_e32 v4, v131, v4
	v_lshlrev_b32_e32 v11, 16, v5
	v_and_b32_e32 v5, 0xffff0000, v5
	v_cvt_i32_f32_e32 v8, v8
	v_cvt_i32_f32_sdwa v9, v9 dst_sel:WORD_1 dst_unused:UNUSED_PAD src0_sel:DWORD
	v_cvt_i32_f32_e32 v3, v3
	v_mul_f32_e32 v10, v131, v10
	v_rndne_f32_e32 v4, v4
	v_mul_f32_e32 v11, v131, v11
	v_mul_f32_e32 v5, v131, v5
	v_rndne_f32_e32 v10, v10
	v_cvt_i32_f32_e32 v4, v4
	v_rndne_f32_e32 v11, v11
	v_rndne_f32_e32 v5, v5
	v_cvt_i32_f32_e32 v10, v10
	v_cvt_i32_f32_sdwa v11, v11 dst_sel:WORD_1 dst_unused:UNUSED_PAD src0_sel:DWORD
	v_cvt_i32_f32_e32 v5, v5
	v_lshlrev_b32_e32 v2, 8, v2
	v_and_b32_e32 v2, 0xff00, v2
	v_and_b32_e32 v9, 0xff0000, v9
	v_perm_b32 v3, v3, v8, s81
	v_or3_b32 v2, v3, v2, v9
	v_lshlrev_b32_e32 v3, 8, v4
	v_and_b32_e32 v3, 0xff00, v3
	v_and_b32_e32 v4, 0xff0000, v11
	v_perm_b32 v5, v5, v10, s81
	v_or3_b32 v3, v5, v3, v4
	v_add_co_u32_e32 v4, vcc, s33, v6
	s_nop 1
	v_addc_co_u32_e32 v5, vcc, 0, v7, vcc
	global_store_dwordx2 v[4:5], v[2:3], off
	ds_read_b128 v[2:5], v96 offset:11264
	s_waitcnt lgkmcnt(0)
	v_lshlrev_b32_e32 v8, 16, v2
	v_and_b32_e32 v2, 0xffff0000, v2
	v_mul_f32_e32 v2, v130, v2
	v_lshlrev_b32_e32 v9, 16, v3
	v_and_b32_e32 v3, 0xffff0000, v3
	v_mul_f32_e32 v8, v130, v8
	v_rndne_f32_e32 v2, v2
	v_mul_f32_e32 v9, v130, v9
	v_mul_f32_e32 v3, v130, v3
	v_lshlrev_b32_e32 v10, 16, v4
	v_and_b32_e32 v4, 0xffff0000, v4
	v_rndne_f32_e32 v8, v8
	v_cvt_i32_f32_e32 v2, v2
	v_rndne_f32_e32 v9, v9
	v_rndne_f32_e32 v3, v3
	v_mul_f32_e32 v4, v130, v4
	v_lshlrev_b32_e32 v11, 16, v5
	v_and_b32_e32 v5, 0xffff0000, v5
	v_cvt_i32_f32_e32 v8, v8
	v_cvt_i32_f32_sdwa v9, v9 dst_sel:WORD_1 dst_unused:UNUSED_PAD src0_sel:DWORD
	v_cvt_i32_f32_e32 v3, v3
	v_mul_f32_e32 v10, v130, v10
	v_rndne_f32_e32 v4, v4
	v_mul_f32_e32 v11, v130, v11
	v_mul_f32_e32 v5, v130, v5
	v_rndne_f32_e32 v10, v10
	v_cvt_i32_f32_e32 v4, v4
	v_rndne_f32_e32 v11, v11
	v_rndne_f32_e32 v5, v5
	v_cvt_i32_f32_e32 v10, v10
	v_cvt_i32_f32_sdwa v11, v11 dst_sel:WORD_1 dst_unused:UNUSED_PAD src0_sel:DWORD
	v_cvt_i32_f32_e32 v5, v5
	v_lshlrev_b32_e32 v2, 8, v2
	v_and_b32_e32 v2, 0xff00, v2
	v_and_b32_e32 v9, 0xff0000, v9
	v_perm_b32 v3, v3, v8, s81
	v_or3_b32 v2, v3, v2, v9
	v_lshlrev_b32_e32 v3, 8, v4
	v_and_b32_e32 v3, 0xff00, v3
	v_and_b32_e32 v4, 0xff0000, v11
	v_perm_b32 v5, v5, v10, s81
	v_or3_b32 v3, v5, v3, v4
	v_add_co_u32_e32 v4, vcc, s44, v6
	s_nop 1
	v_addc_co_u32_e32 v5, vcc, 0, v7, vcc
	global_store_dwordx2 v[4:5], v[2:3], off
	v_lshl_add_u64 v[4:5], v[0:1], 0, s[2:3]
	ds_read_b128 v[0:3], v96 offset:12288
	s_waitcnt lgkmcnt(0)
; #define LAS __attribute__((address_space(3)))
; __device__ __forceinline__ float bflo(unsigned w) { return __uint_as_float(w << 16); }
; __device__ __forceinline__ float bfhi(unsigned w) { return __uint_as_float(w & 0xffff0000u); }
; __device__ __forceinline__ void direct_w8_block(const Ctx& c, LAS unsigned char* lds, const float* Wsrc, const int INC_, int srccol, unsigned char* dstrow, float* swdst) {
;     ...
; #pragma unroll
;     for (int t = 0; t < 8; ++t) { unsigned char* dt = dst + t * 64; asm volatile("" : "+v"(dt));
; #pragma unroll
;         for (int j = 0; j < 4; ++j) { v4u pk;
;             if (t < 4) { pk.x = held[t & 3][j][0]; pk.y = held[t & 3][j][1]; pk.z = held[t & 3][j][2]; pk.w = held[t & 3][j][3]; }
;             else pk = *(const LAS v4u*)(hl + ((t - 4) * 4 + j) * 1024);
;             int qi[8];
; #pragma unroll
;             for (int pr = 0; pr < 4; ++pr) { qi[2 * pr] = __float2int_rn(bflo(pk[pr]) * inv[j]); qi[2 * pr + 1] = __float2int_rn(bfhi(pk[pr]) * inv[j]); }
;             v2u w; w.x = (unsigned)(qi[0] & 255) | ((unsigned)(qi[1] & 255) << 8) | ((unsigned)(qi[2] & 255) << 16) | ((unsigned)(qi[3] & 255) << 24);
;             w.y = (unsigned)(qi[4] & 255) | ((unsigned)(qi[5] & 255) << 8) | ((unsigned)(qi[6] & 255) << 16) | ((unsigned)(qi[7] & 255) << 24);
;             *(v2u*)(dt + (size_t)j * DM) = w; } }
	v_lshlrev_b32_e32 v6, 16, v0
	v_and_b32_e32 v0, 0xffff0000, v0
	v_mul_f32_e32 v0, v135, v0
	v_lshlrev_b32_e32 v7, 16, v1
	v_and_b32_e32 v1, 0xffff0000, v1
	v_mul_f32_e32 v6, v135, v6
	v_rndne_f32_e32 v0, v0
	v_mul_f32_e32 v7, v135, v7
	v_mul_f32_e32 v1, v135, v1
	v_lshlrev_b32_e32 v8, 16, v2
	v_and_b32_e32 v2, 0xffff0000, v2
	v_rndne_f32_e32 v6, v6
	v_cvt_i32_f32_e32 v0, v0
	v_rndne_f32_e32 v7, v7
	v_rndne_f32_e32 v1, v1
	v_mul_f32_e32 v2, v135, v2
	v_lshlrev_b32_e32 v9, 16, v3
	v_and_b32_e32 v3, 0xffff0000, v3
	v_cvt_i32_f32_e32 v6, v6
	v_cvt_i32_f32_sdwa v7, v7 dst_sel:WORD_1 dst_unused:UNUSED_PAD src0_sel:DWORD
	v_cvt_i32_f32_e32 v1, v1
	v_mul_f32_e32 v8, v135, v8
	v_rndne_f32_e32 v2, v2
	v_mul_f32_e32 v9, v135, v9
	v_mul_f32_e32 v3, v135, v3
	v_rndne_f32_e32 v8, v8
	v_cvt_i32_f32_e32 v2, v2
	v_rndne_f32_e32 v9, v9
	v_rndne_f32_e32 v3, v3
	v_cvt_i32_f32_e32 v8, v8
	v_cvt_i32_f32_sdwa v9, v9 dst_sel:WORD_1 dst_unused:UNUSED_PAD src0_sel:DWORD
	v_cvt_i32_f32_e32 v3, v3
	v_lshlrev_b32_e32 v0, 8, v0
	v_and_b32_e32 v0, 0xff00, v0
	v_and_b32_e32 v7, 0xff0000, v7
	v_perm_b32 v1, v1, v6, s81
	v_or3_b32 v0, v1, v0, v7
	v_lshlrev_b32_e32 v1, 8, v2
	v_and_b32_e32 v1, 0xff00, v1
	v_and_b32_e32 v2, 0xff0000, v9
	v_perm_b32 v3, v3, v8, s81
	v_or3_b32 v1, v3, v1, v2
	global_store_dwordx2 v[4:5], v[0:1], off
	ds_read_b128 v[0:3], v96 offset:13312
	s_waitcnt lgkmcnt(0)
	v_lshlrev_b32_e32 v6, 16, v0
	v_and_b32_e32 v0, 0xffff0000, v0
	v_mul_f32_e32 v0, v134, v0
	v_lshlrev_b32_e32 v7, 16, v1
	v_and_b32_e32 v1, 0xffff0000, v1
	v_mul_f32_e32 v6, v134, v6
	v_rndne_f32_e32 v0, v0
	v_mul_f32_e32 v7, v134, v7
	v_mul_f32_e32 v1, v134, v1
	v_lshlrev_b32_e32 v8, 16, v2
	v_and_b32_e32 v2, 0xffff0000, v2
	v_rndne_f32_e32 v6, v6
	v_cvt_i32_f32_e32 v0, v0
	v_rndne_f32_e32 v7, v7
	v_rndne_f32_e32 v1, v1
	v_mul_f32_e32 v2, v134, v2
	v_lshlrev_b32_e32 v9, 16, v3
	v_and_b32_e32 v3, 0xffff0000, v3
	v_cvt_i32_f32_e32 v6, v6
	v_cvt_i32_f32_sdwa v7, v7 dst_sel:WORD_1 dst_unused:UNUSED_PAD src0_sel:DWORD
	v_cvt_i32_f32_e32 v1, v1
	v_mul_f32_e32 v8, v134, v8
	v_rndne_f32_e32 v2, v2
	v_mul_f32_e32 v9, v134, v9
	v_mul_f32_e32 v3, v134, v3
	v_rndne_f32_e32 v8, v8
	v_cvt_i32_f32_e32 v2, v2
	v_rndne_f32_e32 v9, v9
	v_rndne_f32_e32 v3, v3
	v_cvt_i32_f32_e32 v8, v8
	v_cvt_i32_f32_sdwa v9, v9 dst_sel:WORD_1 dst_unused:UNUSED_PAD src0_sel:DWORD
	v_cvt_i32_f32_e32 v3, v3
	v_lshlrev_b32_e32 v0, 8, v0
	v_and_b32_e32 v0, 0xff00, v0
	v_and_b32_e32 v7, 0xff0000, v7
	v_perm_b32 v1, v1, v6, s81
	v_or3_b32 v0, v1, v0, v7
	v_lshlrev_b32_e32 v1, 8, v2
	v_and_b32_e32 v1, 0xff00, v1
	v_and_b32_e32 v2, 0xff0000, v9
	v_perm_b32 v3, v3, v8, s81
	v_or3_b32 v1, v3, v1, v2
	v_add_co_u32_e32 v2, vcc, s67, v4
	s_nop 1
	v_addc_co_u32_e32 v3, vcc, 0, v5, vcc
	global_store_dwordx2 v[2:3], v[0:1], off
	ds_read_b128 v[0:3], v96 offset:14336
	s_waitcnt lgkmcnt(0)
	v_lshlrev_b32_e32 v6, 16, v0
	v_and_b32_e32 v0, 0xffff0000, v0
	v_mul_f32_e32 v0, v131, v0
	v_lshlrev_b32_e32 v7, 16, v1
	v_and_b32_e32 v1, 0xffff0000, v1
	v_mul_f32_e32 v6, v131, v6
	v_rndne_f32_e32 v0, v0
	v_mul_f32_e32 v7, v131, v7
	v_mul_f32_e32 v1, v131, v1
	v_lshlrev_b32_e32 v8, 16, v2
	v_and_b32_e32 v2, 0xffff0000, v2
	v_rndne_f32_e32 v6, v6
	v_cvt_i32_f32_e32 v0, v0
	v_rndne_f32_e32 v7, v7
	v_rndne_f32_e32 v1, v1
	v_mul_f32_e32 v2, v131, v2
	v_lshlrev_b32_e32 v9, 16, v3
	v_and_b32_e32 v3, 0xffff0000, v3
	v_cvt_i32_f32_e32 v6, v6
	v_cvt_i32_f32_sdwa v7, v7 dst_sel:WORD_1 dst_unused:UNUSED_PAD src0_sel:DWORD
	v_cvt_i32_f32_e32 v1, v1
	v_mul_f32_e32 v8, v131, v8
	v_rndne_f32_e32 v2, v2
	v_mul_f32_e32 v9, v131, v9
	v_mul_f32_e32 v3, v131, v3
	v_rndne_f32_e32 v8, v8
	v_cvt_i32_f32_e32 v2, v2
	v_rndne_f32_e32 v9, v9
	v_rndne_f32_e32 v3, v3
	v_cvt_i32_f32_e32 v8, v8
	v_cvt_i32_f32_sdwa v9, v9 dst_sel:WORD_1 dst_unused:UNUSED_PAD src0_sel:DWORD
	v_cvt_i32_f32_e32 v3, v3
	v_lshlrev_b32_e32 v0, 8, v0
	v_and_b32_e32 v0, 0xff00, v0
	v_and_b32_e32 v7, 0xff0000, v7
	v_perm_b32 v1, v1, v6, s81
	v_or3_b32 v0, v1, v0, v7
	v_lshlrev_b32_e32 v1, 8, v2
	v_and_b32_e32 v1, 0xff00, v1
	v_and_b32_e32 v2, 0xff0000, v9
	v_perm_b32 v3, v3, v8, s81
	v_or3_b32 v1, v3, v1, v2
	v_add_co_u32_e32 v2, vcc, s33, v4
	s_nop 1
	v_addc_co_u32_e32 v3, vcc, 0, v5, vcc
	global_store_dwordx2 v[2:3], v[0:1], off
	ds_read_b128 v[0:3], v96 offset:15360
	s_waitcnt lgkmcnt(0)
	v_lshlrev_b32_e32 v6, 16, v0
	v_and_b32_e32 v0, 0xffff0000, v0
	v_mul_f32_e32 v0, v130, v0
	v_lshlrev_b32_e32 v7, 16, v1
	v_and_b32_e32 v1, 0xffff0000, v1
	v_mul_f32_e32 v6, v130, v6
	v_rndne_f32_e32 v0, v0
	v_mul_f32_e32 v7, v130, v7
	v_mul_f32_e32 v1, v130, v1
	v_lshlrev_b32_e32 v8, 16, v2
	v_and_b32_e32 v2, 0xffff0000, v2
	v_rndne_f32_e32 v6, v6
	v_cvt_i32_f32_e32 v0, v0
	v_rndne_f32_e32 v7, v7
	v_rndne_f32_e32 v1, v1
	v_mul_f32_e32 v2, v130, v2
	v_lshlrev_b32_e32 v9, 16, v3
	v_and_b32_e32 v3, 0xffff0000, v3
	v_cvt_i32_f32_e32 v6, v6
	v_cvt_i32_f32_sdwa v7, v7 dst_sel:WORD_1 dst_unused:UNUSED_PAD src0_sel:DWORD
	v_cvt_i32_f32_e32 v1, v1
	v_mul_f32_e32 v8, v130, v8
	v_rndne_f32_e32 v2, v2
	v_mul_f32_e32 v9, v130, v9
	v_mul_f32_e32 v3, v130, v3
	v_rndne_f32_e32 v8, v8
	v_cvt_i32_f32_e32 v2, v2
	v_rndne_f32_e32 v9, v9
	v_rndne_f32_e32 v3, v3
	v_cvt_i32_f32_e32 v8, v8
	v_cvt_i32_f32_sdwa v9, v9 dst_sel:WORD_1 dst_unused:UNUSED_PAD src0_sel:DWORD
	v_cvt_i32_f32_e32 v3, v3
	v_lshlrev_b32_e32 v0, 8, v0
	v_and_b32_e32 v0, 0xff00, v0
	v_and_b32_e32 v7, 0xff0000, v7
	v_perm_b32 v1, v1, v6, s81
	v_or3_b32 v0, v1, v0, v7
	v_lshlrev_b32_e32 v1, 8, v2
	v_and_b32_e32 v1, 0xff00, v1
	v_and_b32_e32 v2, 0xff0000, v9
	v_perm_b32 v3, v3, v8, s81
	v_or3_b32 v1, v3, v1, v2
	v_add_co_u32_e32 v2, vcc, 0x3000, v4
	s_nop 1
	v_addc_co_u32_e32 v3, vcc, 0, v5, vcc
	global_store_dwordx2 v[2:3], v[0:1], off
	s_cbranch_scc1 .LBB0_457

; #define LAS __attribute__((address_space(3)))
; __device__ __forceinline__ float bflo(unsigned w) { return __uint_as_float(w << 16); }
; __device__ __forceinline__ float bfhi(unsigned w) { return __uint_as_float(w & 0xffff0000u); }
; __device__ __forceinline__ void direct_w8_block(const Ctx& c, LAS unsigned char* lds, const float* Wsrc, const int INC_, int srccol, unsigned char* dstrow, float* swdst) {
;     ...
;     for (int j = 0; j < 4; ++j) { sc[j] = cm[j] > 0.f ? cm[j] * (1.0f / 127.0f) : 1.0f; inv[j] = 1.0f / sc[j]; }
;     if (wave == 0 && kr == 0) *(f32x4*)(swdst + 4 * nc) = sc;
;     unsigned char* dst = dstrow + (size_t)(4 * nc) * DM + 512 * wave + 8 * kr;
; #pragma unroll
;     for (int t = 0; t < 8; ++t) { unsigned char* dt = dst + t * 64; asm volatile("" : "+v"(dt));
; #pragma unroll
;         for (int j = 0; j < 4; ++j) { v4u pk;
;             if (t < 4) { pk.x = held[t & 3][j][0]; pk.y = held[t & 3][j][1]; pk.z = held[t & 3][j][2]; pk.w = held[t & 3][j][3]; }
;             else pk = *(const LAS v4u*)(hl + ((t - 4) * 4 + j) * 1024);
;             int qi[8];
; #pragma unroll
;             for (int pr = 0; pr < 4; ++pr) { qi[2 * pr] = __float2int_rn(bflo(pk[pr]) * inv[j]); qi[2 * pr + 1] = __float2int_rn(bfhi(pk[pr]) * inv[j]); }
;             v2u w; w.x = (unsigned)(qi[0] & 255) | ((unsigned)(qi[1] & 255) << 8) | ((unsigned)(qi[2] & 255) << 16) | ((unsigned)(qi[3] & 255) << 24);
;             w.y = (unsigned)(qi[4] & 255) | ((unsigned)(qi[5] & 255) << 8) | ((unsigned)(qi[6] & 255) << 16) | ((unsigned)(qi[7] & 255) << 24);
;             *(v2u*)(dt + (size_t)j * DM) = w; } }
; __device__ __forceinline__ void phase_tail_transposes(LAS unsigned char* lds, int part, int wv) {
;     ...
;         const int rot = nidle > NBO ? nidle - NBO : 0;
;         for (int k = (idx + rot) % nidle; k < NB1 - NT0; k += nidle) direct_win_block(c, lds, 1, NT0 + k); }
.LBB0_783:
	s_abs_i32 s6, s0
	v_cvt_f32_u32_e32 v0, s6
	s_max_i32 s7, s0, 0x80
	s_add_i32 s3, s3, s7
	s_add_i32 s7, s3, 0xffffff80
	v_rcp_iflag_f32_e32 v0, v0
	s_sub_i32 s3, 0x80, s3
	s_ashr_i32 s8, s7, 31
	s_max_i32 s3, s7, s3
	v_mul_f32_e32 v0, 0x4f7ffffe, v0
	v_cvt_u32_f32_e32 v0, v0
	s_sub_i32 s7, 0, s6
	v_readfirstlane_b32 s9, v0
	s_mul_i32 s7, s7, s9
	s_mul_hi_u32 s7, s9, s7
	s_add_i32 s9, s9, s7
	s_mul_hi_u32 s7, s3, s9
	s_mul_i32 s7, s7, s6
	s_sub_i32 s3, s3, s7
	s_sub_i32 s7, s3, s6
	s_cmp_ge_u32 s3, s6
	s_cselect_b32 s3, s7, s3
	s_sub_i32 s7, s3, s6
	s_cmp_ge_u32 s3, s6
	s_cselect_b32 s3, s7, s3
	s_xor_b32 s9, s3, s8
	s_sub_i32 s3, s9, s8
	s_cmpk_gt_i32 s3, 0x1df
	s_cbranch_scc1 .LBB0_790
	s_load_dwordx2 s[10:11], s[14:15], 0x30
	v_lshlrev_b32_e32 v96, 2, v176
	v_readlane_b32 s12, v254, 12
	v_cmp_gt_u32_e64 s[6:7], 8, v169
	v_mov_b32_e32 v165, v97
	s_waitcnt lgkmcnt(0)
	v_mov_b64_e32 v[0:1], s[10:11]
	v_mad_u64_u32 v[0:1], s[10:11], v166, s61, v[0:1]
	v_lshl_add_u64 v[0:1], v[0:1], 0, v[96:97]
	s_mov_b64 s[10:11], 0x18000000
	v_lshl_add_u64 v[166:167], v[0:1], 0, s[10:11]
	s_add_i32 s10, 0, 0x20800
	v_add_u32_e32 v163, s12, v96
	v_add_u32_e32 v170, s10, v96
	v_lshl_add_u64 v[0:1], s[4:5], 0, v[96:97]
	s_mov_b64 s[12:13], 0x6ff11000
	v_lshlrev_b32_e32 v96, 12, v176
	v_lshl_add_u64 v[168:169], v[0:1], 0, s[12:13]
	v_lshl_add_u64 v[0:1], s[4:5], 0, v[96:97]
	v_readlane_b32 s4, v254, 13
	v_readlane_b32 s5, v254, 14
	v_readlane_b32 s10, v254, 4
	v_readlane_b32 s11, v254, 5
	v_lshl_add_u64 v[0:1], v[0:1], 0, s[4:5]
	v_lshl_add_u64 v[0:1], v[0:1], 0, v[164:165]
	s_mov_b64 s[4:5], 0x6b800000
	v_lshl_add_u64 v[164:165], v[0:1], 0, s[4:5]
	s_lshl_b32 s4, s9, 5
	s_lshl_b32 s5, s8, 5
	s_sub_i32 s4, s4, s5
	s_lshl_b32 s1, s1, 5
	s_lshl_b32 s2, s2, 5
	s_and_b64 s[10:11], s[10:11], s[6:7]
	s_add_i32 s12, s4, 0x2c00
	s_sub_i32 s1, s1, s2
	s_branch .LBB0_786
.LBB0_785:
	s_or_b64 exec, exec, s[8:9]
	v_div_scale_f32 v134, s[8:9], v130, v130, 1.0
	v_rcp_f32_e32 v135, v134
	v_cvt_pk_bf16_f32 v4, v0, v4
	v_cvt_pk_bf16_f32 v8, v8, v12
	v_lshlrev_b32_e32 v12, 16, v4
	v_fma_f32 v136, -v134, v135, 1.0
	v_fmac_f32_e32 v135, v136, v135
	v_div_scale_f32 v136, vcc, 1.0, v130, 1.0
	v_mul_f32_e32 v137, v136, v135
	v_fma_f32 v138, -v134, v137, v136
	v_fmac_f32_e32 v137, v138, v135
	v_fma_f32 v134, -v134, v137, v136
	v_div_fmas_f32 v134, v134, v135, v137
	v_div_fixup_f32 v135, v134, v130, 1.0
	v_div_scale_f32 v130, s[8:9], v131, v131, 1.0
	v_rcp_f32_e32 v134, v130
	v_and_b32_e32 v4, 0xffff0000, v4
	v_cvt_pk_bf16_f32 v11, v11, v15
	v_cvt_pk_bf16_f32 v15, v3, v7
	v_fma_f32 v136, -v130, v134, 1.0
	v_fmac_f32_e32 v134, v136, v134
	v_div_scale_f32 v136, vcc, 1.0, v131, 1.0
	v_mul_f32_e32 v137, v136, v134
	v_fma_f32 v138, -v130, v137, v136
	v_fmac_f32_e32 v137, v138, v134
	v_fma_f32 v130, -v130, v137, v136
	v_div_fmas_f32 v130, v130, v134, v137
	v_div_fixup_f32 v134, v130, v131, 1.0
	v_div_scale_f32 v130, s[8:9], v132, v132, 1.0
	v_rcp_f32_e32 v131, v130
	v_cvt_pk_bf16_f32 v7, v17, v21
	v_cvt_pk_bf16_f32 v16, v16, v20
	v_mul_f32_e32 v4, v135, v4
	v_lshlrev_b32_e32 v17, 16, v8
	v_and_b32_e32 v8, 0xffff0000, v8
	v_cvt_pk_bf16_f32 v9, v9, v13
	v_cvt_pk_bf16_f32 v13, v1, v5
	v_cvt_pk_bf16_f32 v5, v24, v28
	v_mul_f32_e32 v12, v135, v12
	v_rndne_f32_e32 v4, v4
	v_mul_f32_e32 v17, v135, v17
	v_mul_f32_e32 v8, v135, v8
	v_lshlrev_b32_e32 v20, 16, v16
	v_and_b32_e32 v16, 0xffff0000, v16
	v_rndne_f32_e32 v12, v12
	v_cvt_i32_f32_e32 v4, v4
	v_rndne_f32_e32 v17, v17
	v_rndne_f32_e32 v8, v8
	v_mul_f32_e32 v16, v135, v16
	v_lshlrev_b32_e32 v21, 16, v5
	v_and_b32_e32 v5, 0xffff0000, v5
	v_cvt_i32_f32_e32 v12, v12
	v_cvt_i32_f32_sdwa v17, v17 dst_sel:WORD_1 dst_unused:UNUSED_PAD src0_sel:DWORD
	v_cvt_i32_f32_e32 v8, v8
	v_mul_f32_e32 v20, v135, v20
	v_rndne_f32_e32 v16, v16
	v_mul_f32_e32 v21, v135, v21
	v_mul_f32_e32 v5, v135, v5
	v_fma_f32 v136, -v130, v131, 1.0
	v_rndne_f32_e32 v20, v20
	v_cvt_i32_f32_e32 v16, v16
	v_rndne_f32_e32 v21, v21
	v_rndne_f32_e32 v5, v5
	v_fmac_f32_e32 v131, v136, v131
	v_div_scale_f32 v136, vcc, 1.0, v132, 1.0
	v_cvt_i32_f32_e32 v20, v20
	v_cvt_i32_f32_sdwa v21, v21 dst_sel:WORD_1 dst_unused:UNUSED_PAD src0_sel:DWORD
	v_cvt_i32_f32_e32 v5, v5
	v_mul_f32_e32 v137, v136, v131
	v_lshlrev_b32_e32 v4, 8, v4
	v_fma_f32 v138, -v130, v137, v136
	v_and_b32_e32 v4, 0xff00, v4
	v_and_b32_e32 v17, 0xff0000, v17
	v_perm_b32 v8, v8, v12, s81
	v_fmac_f32_e32 v137, v138, v131
	s_lshl_b64 s[4:5], s[4:5], 12
	v_or3_b32 v4, v8, v4, v17
	v_lshlrev_b32_e32 v8, 8, v16
	v_fma_f32 v130, -v130, v137, v136
	v_lshl_add_u64 v[0:1], v[164:165], 0, s[4:5]
	v_and_b32_e32 v8, 0xff00, v8
	v_and_b32_e32 v12, 0xff0000, v21
	v_perm_b32 v5, v5, v20, s81
	v_div_fmas_f32 v130, v130, v131, v137
	v_cvt_pk_bf16_f32 v10, v10, v14
	v_cvt_pk_bf16_f32 v14, v2, v6
	v_mov_b64_e32 v[2:3], v[0:1]
	v_or3_b32 v5, v5, v8, v12
	v_div_fixup_f32 v131, v130, v132, 1.0
	v_div_scale_f32 v130, s[8:9], v133, v133, 1.0
	flat_store_dwordx2 v[2:3], v[4:5]
	v_and_b32_e32 v5, 0xffff0000, v13
	v_rcp_f32_e32 v132, v130
	v_lshlrev_b32_e32 v4, 16, v13
	v_mul_f32_e32 v5, v134, v5
	v_lshlrev_b32_e32 v8, 16, v9
	v_and_b32_e32 v9, 0xffff0000, v9
	v_cvt_pk_bf16_f32 v6, v25, v29
	v_mul_f32_e32 v4, v134, v4
	v_rndne_f32_e32 v5, v5
	v_mul_f32_e32 v8, v134, v8
	v_mul_f32_e32 v9, v134, v9
	v_lshlrev_b32_e32 v12, 16, v7
	v_and_b32_e32 v7, 0xffff0000, v7
	v_rndne_f32_e32 v4, v4
	v_cvt_i32_f32_e32 v5, v5
	v_rndne_f32_e32 v8, v8
	v_rndne_f32_e32 v9, v9
	v_mul_f32_e32 v7, v134, v7
	v_lshlrev_b32_e32 v13, 16, v6
	v_and_b32_e32 v6, 0xffff0000, v6
	v_cvt_i32_f32_e32 v4, v4
	v_cvt_i32_f32_sdwa v8, v8 dst_sel:WORD_1 dst_unused:UNUSED_PAD src0_sel:DWORD
; #define LAS __attribute__((address_space(3)))
; __device__ __forceinline__ float bflo(unsigned w) { return __uint_as_float(w << 16); }
; __device__ __forceinline__ float bfhi(unsigned w) { return __uint_as_float(w & 0xffff0000u); }
; __device__ __forceinline__ void direct_w8_block(const Ctx& c, LAS unsigned char* lds, const float* Wsrc, const int INC_, int srccol, unsigned char* dstrow, float* swdst) {
;     ...
;     f32x4 sc, inv;
; #pragma unroll
;     for (int j = 0; j < 4; ++j) { sc[j] = cm[j] > 0.f ? cm[j] * (1.0f / 127.0f) : 1.0f; inv[j] = 1.0f / sc[j]; }
;     if (wave == 0 && kr == 0) *(f32x4*)(swdst + 4 * nc) = sc;
;     unsigned char* dst = dstrow + (size_t)(4 * nc) * DM + 512 * wave + 8 * kr;
; #pragma unroll
;     for (int t = 0; t < 8; ++t) { unsigned char* dt = dst + t * 64; asm volatile("" : "+v"(dt));
; #pragma unroll
;         for (int j = 0; j < 4; ++j) { v4u pk;
;             if (t < 4) { pk.x = held[t & 3][j][0]; pk.y = held[t & 3][j][1]; pk.z = held[t & 3][j][2]; pk.w = held[t & 3][j][3]; }
;             else pk = *(const LAS v4u*)(hl + ((t - 4) * 4 + j) * 1024);
;             int qi[8];
; #pragma unroll
;             for (int pr = 0; pr < 4; ++pr) { qi[2 * pr] = __float2int_rn(bflo(pk[pr]) * inv[j]); qi[2 * pr + 1] = __float2int_rn(bfhi(pk[pr]) * inv[j]); }
;             v2u w; w.x = (unsigned)(qi[0] & 255) | ((unsigned)(qi[1] & 255) << 8) | ((unsigned)(qi[2] & 255) << 16) | ((unsigned)(qi[3] & 255) << 24);
;             w.y = (unsigned)(qi[4] & 255) | ((unsigned)(qi[5] & 255) << 8) | ((unsigned)(qi[6] & 255) << 16) | ((unsigned)(qi[7] & 255) << 24);
;             *(v2u*)(dt + (size_t)j * DM) = w; } }
	v_cvt_i32_f32_e32 v9, v9
	v_mul_f32_e32 v12, v134, v12
	v_rndne_f32_e32 v7, v7
	v_mul_f32_e32 v13, v134, v13
	v_mul_f32_e32 v6, v134, v6
	v_fma_f32 v136, -v130, v132, 1.0
	v_rndne_f32_e32 v12, v12
	v_cvt_i32_f32_e32 v7, v7
	v_rndne_f32_e32 v13, v13
	v_rndne_f32_e32 v6, v6
	v_fmac_f32_e32 v132, v136, v132
	v_div_scale_f32 v136, vcc, 1.0, v133, 1.0
	v_cvt_i32_f32_e32 v12, v12
	v_cvt_i32_f32_sdwa v13, v13 dst_sel:WORD_1 dst_unused:UNUSED_PAD src0_sel:DWORD
	v_cvt_i32_f32_e32 v6, v6
	v_mul_f32_e32 v137, v136, v132
	v_lshlrev_b32_e32 v5, 8, v5
	v_fma_f32 v138, -v130, v137, v136
	v_and_b32_e32 v5, 0xff00, v5
	v_and_b32_e32 v8, 0xff0000, v8
	v_perm_b32 v4, v9, v4, s81
	v_fmac_f32_e32 v137, v138, v132
	v_or3_b32 v4, v4, v5, v8
	v_lshlrev_b32_e32 v5, 8, v7
	v_fma_f32 v130, -v130, v137, v136
	v_and_b32_e32 v5, 0xff00, v5
	v_and_b32_e32 v7, 0xff0000, v13
	v_perm_b32 v6, v6, v12, s81
	v_div_fmas_f32 v130, v130, v132, v137
	v_or3_b32 v5, v6, v5, v7
	v_add_co_u32_e32 v6, vcc, s67, v2
	v_cvt_pk_bf16_f32 v18, v18, v22
	s_nop 0
	v_addc_co_u32_e32 v7, vcc, 0, v3, vcc
	flat_store_dwordx2 v[6:7], v[4:5]
	v_and_b32_e32 v5, 0xffff0000, v14
	v_lshlrev_b32_e32 v4, 16, v14
	v_mul_f32_e32 v5, v131, v5
	v_lshlrev_b32_e32 v6, 16, v10
	v_and_b32_e32 v7, 0xffff0000, v10
	v_cvt_pk_bf16_f32 v19, v19, v23
	v_cvt_pk_bf16_f32 v23, v26, v30
	v_mul_f32_e32 v4, v131, v4
	v_rndne_f32_e32 v5, v5
	v_mul_f32_e32 v6, v131, v6
	v_mul_f32_e32 v7, v131, v7
	v_and_b32_e32 v9, 0xffff0000, v18
	v_rndne_f32_e32 v4, v4
	v_cvt_i32_f32_e32 v5, v5
	v_rndne_f32_e32 v6, v6
	v_rndne_f32_e32 v7, v7
	v_lshlrev_b32_e32 v8, 16, v18
	v_mul_f32_e32 v9, v131, v9
	v_lshlrev_b32_e32 v10, 16, v23
	v_and_b32_e32 v12, 0xffff0000, v23
	v_cvt_i32_f32_e32 v4, v4
	v_cvt_i32_f32_sdwa v6, v6 dst_sel:WORD_1 dst_unused:UNUSED_PAD src0_sel:DWORD
	v_cvt_i32_f32_e32 v7, v7
	v_mul_f32_e32 v8, v131, v8
	v_rndne_f32_e32 v9, v9
	v_mul_f32_e32 v10, v131, v10
	v_mul_f32_e32 v12, v131, v12
	v_rndne_f32_e32 v8, v8
	v_cvt_i32_f32_e32 v9, v9
	v_rndne_f32_e32 v10, v10
	v_rndne_f32_e32 v12, v12
	v_cvt_i32_f32_e32 v8, v8
	v_cvt_i32_f32_sdwa v10, v10 dst_sel:WORD_1 dst_unused:UNUSED_PAD src0_sel:DWORD
	v_cvt_i32_f32_e32 v12, v12
	v_lshlrev_b32_e32 v5, 8, v5
	v_and_b32_e32 v5, 0xff00, v5
	v_and_b32_e32 v6, 0xff0000, v6
	v_perm_b32 v4, v7, v4, s81
	v_or3_b32 v4, v4, v5, v6
	v_lshlrev_b32_e32 v5, 8, v9
	v_and_b32_e32 v5, 0xff00, v5
	v_and_b32_e32 v6, 0xff0000, v10
	v_perm_b32 v7, v12, v8, s81
	v_or3_b32 v5, v7, v5, v6
	v_add_co_u32_e32 v6, vcc, s33, v2
	v_div_fixup_f32 v130, v130, v133, 1.0
	s_nop 0
	v_addc_co_u32_e32 v7, vcc, 0, v3, vcc
	flat_store_dwordx2 v[6:7], v[4:5]
	v_and_b32_e32 v5, 0xffff0000, v15
	v_lshlrev_b32_e32 v4, 16, v15
	v_mul_f32_e32 v5, v130, v5
	v_lshlrev_b32_e32 v6, 16, v11
	v_and_b32_e32 v7, 0xffff0000, v11
	v_cvt_pk_bf16_f32 v27, v27, v31
	v_mul_f32_e32 v4, v130, v4
	v_rndne_f32_e32 v5, v5
	v_mul_f32_e32 v6, v130, v6
	v_mul_f32_e32 v7, v130, v7
	v_and_b32_e32 v9, 0xffff0000, v19
	v_rndne_f32_e32 v4, v4
	v_cvt_i32_f32_e32 v5, v5
	v_rndne_f32_e32 v6, v6
	v_rndne_f32_e32 v7, v7
	v_lshlrev_b32_e32 v8, 16, v19
	v_mul_f32_e32 v9, v130, v9
	v_lshlrev_b32_e32 v10, 16, v27
	v_and_b32_e32 v11, 0xffff0000, v27
	v_cvt_i32_f32_e32 v4, v4
	v_cvt_i32_f32_sdwa v6, v6 dst_sel:WORD_1 dst_unused:UNUSED_PAD src0_sel:DWORD
	v_cvt_i32_f32_e32 v7, v7
	v_mul_f32_e32 v8, v130, v8
	v_rndne_f32_e32 v9, v9
	v_mul_f32_e32 v10, v130, v10
	v_mul_f32_e32 v11, v130, v11
	v_rndne_f32_e32 v8, v8
	v_cvt_i32_f32_e32 v9, v9
	v_rndne_f32_e32 v10, v10
	v_rndne_f32_e32 v11, v11
	v_cvt_i32_f32_e32 v8, v8
	v_cvt_i32_f32_sdwa v10, v10 dst_sel:WORD_1 dst_unused:UNUSED_PAD src0_sel:DWORD
	v_cvt_i32_f32_e32 v11, v11
	v_lshlrev_b32_e32 v5, 8, v5
	v_and_b32_e32 v5, 0xff00, v5
	v_and_b32_e32 v6, 0xff0000, v6
	v_perm_b32 v4, v7, v4, s81
	v_or3_b32 v4, v4, v5, v6
	v_lshlrev_b32_e32 v5, 8, v9
	v_and_b32_e32 v5, 0xff00, v5
	v_and_b32_e32 v6, 0xff0000, v10
	v_perm_b32 v7, v11, v8, s81
	v_add_co_u32_e32 v2, vcc, s44, v2
	v_cvt_pk_bf16_f32 v32, v32, v36
	v_or3_b32 v5, v7, v5, v6
	v_addc_co_u32_e32 v3, vcc, 0, v3, vcc
	v_cvt_pk_bf16_f32 v40, v40, v44
	flat_store_dwordx2 v[2:3], v[4:5]
	v_and_b32_e32 v5, 0xffff0000, v32
	v_cvt_pk_bf16_f32 v41, v41, v45
	v_cvt_pk_bf16_f32 v45, v48, v52
	v_lshlrev_b32_e32 v4, 16, v32
	v_mul_f32_e32 v5, v135, v5
	v_lshlrev_b32_e32 v6, 16, v40
	v_and_b32_e32 v7, 0xffff0000, v40
	v_cvt_pk_bf16_f32 v33, v33, v37
	v_cvt_pk_bf16_f32 v37, v56, v60
	v_mul_f32_e32 v4, v135, v4
	v_rndne_f32_e32 v5, v5
	v_mul_f32_e32 v6, v135, v6
	v_mul_f32_e32 v7, v135, v7
	v_and_b32_e32 v9, 0xffff0000, v45
	v_rndne_f32_e32 v4, v4
	v_cvt_i32_f32_e32 v5, v5
	v_rndne_f32_e32 v6, v6
	v_rndne_f32_e32 v7, v7
	v_lshlrev_b32_e32 v8, 16, v45
	v_mul_f32_e32 v9, v135, v9
	v_lshlrev_b32_e32 v10, 16, v37
	v_and_b32_e32 v11, 0xffff0000, v37
	v_cvt_i32_f32_e32 v4, v4
	v_cvt_i32_f32_sdwa v6, v6 dst_sel:WORD_1 dst_unused:UNUSED_PAD src0_sel:DWORD
	v_cvt_i32_f32_e32 v7, v7
	v_mul_f32_e32 v8, v135, v8
	v_rndne_f32_e32 v9, v9
	v_mul_f32_e32 v10, v135, v10
	v_mul_f32_e32 v11, v135, v11
	v_rndne_f32_e32 v8, v8
	v_cvt_i32_f32_e32 v9, v9
	v_rndne_f32_e32 v10, v10
	v_rndne_f32_e32 v11, v11
	v_cvt_i32_f32_e32 v8, v8
	v_cvt_i32_f32_sdwa v10, v10 dst_sel:WORD_1 dst_unused:UNUSED_PAD src0_sel:DWORD
	v_cvt_i32_f32_e32 v11, v11
	v_lshlrev_b32_e32 v5, 8, v5
	v_and_b32_e32 v5, 0xff00, v5
	v_and_b32_e32 v6, 0xff0000, v6
	v_perm_b32 v4, v7, v4, s81
	v_or3_b32 v4, v4, v5, v6
	v_lshlrev_b32_e32 v5, 8, v9
	v_and_b32_e32 v5, 0xff00, v5
	v_and_b32_e32 v6, 0xff0000, v10
	v_perm_b32 v7, v11, v8, s81
	v_lshl_add_u64 v[2:3], v[0:1], 0, 64
	v_or3_b32 v5, v7, v5, v6
	flat_store_dwordx2 v[2:3], v[4:5]
; #define LAS __attribute__((address_space(3)))
; __device__ __forceinline__ float bflo(unsigned w) { return __uint_as_float(w << 16); }
; __device__ __forceinline__ float bfhi(unsigned w) { return __uint_as_float(w & 0xffff0000u); }
; __device__ __forceinline__ void direct_w8_block(const Ctx& c, LAS unsigned char* lds, const float* Wsrc, const int INC_, int srccol, unsigned char* dstrow, float* swdst) {
;     ...
; #pragma unroll
;     for (int t = 0; t < 8; ++t) { unsigned char* dt = dst + t * 64; asm volatile("" : "+v"(dt));
; #pragma unroll
;         for (int j = 0; j < 4; ++j) { v4u pk;
;             if (t < 4) { pk.x = held[t & 3][j][0]; pk.y = held[t & 3][j][1]; pk.z = held[t & 3][j][2]; pk.w = held[t & 3][j][3]; }
;             else pk = *(const LAS v4u*)(hl + ((t - 4) * 4 + j) * 1024);
;             int qi[8];
; #pragma unroll
;             for (int pr = 0; pr < 4; ++pr) { qi[2 * pr] = __float2int_rn(bflo(pk[pr]) * inv[j]); qi[2 * pr + 1] = __float2int_rn(bfhi(pk[pr]) * inv[j]); }
;             v2u w; w.x = (unsigned)(qi[0] & 255) | ((unsigned)(qi[1] & 255) << 8) | ((unsigned)(qi[2] & 255) << 16) | ((unsigned)(qi[3] & 255) << 24);
;             w.y = (unsigned)(qi[4] & 255) | ((unsigned)(qi[5] & 255) << 8) | ((unsigned)(qi[6] & 255) << 16) | ((unsigned)(qi[7] & 255) << 24);
;             *(v2u*)(dt + (size_t)j * DM) = w; } }
	v_and_b32_e32 v5, 0xffff0000, v33
	v_cvt_pk_bf16_f32 v42, v42, v46
	v_cvt_pk_bf16_f32 v46, v49, v53
	v_lshlrev_b32_e32 v4, 16, v33
	v_mul_f32_e32 v5, v134, v5
	v_lshlrev_b32_e32 v6, 16, v41
	v_and_b32_e32 v7, 0xffff0000, v41
	v_cvt_pk_bf16_f32 v34, v34, v38
	v_cvt_pk_bf16_f32 v38, v57, v61
	v_mul_f32_e32 v4, v134, v4
	v_rndne_f32_e32 v5, v5
	v_mul_f32_e32 v6, v134, v6
	v_mul_f32_e32 v7, v134, v7
	v_and_b32_e32 v9, 0xffff0000, v46
	v_rndne_f32_e32 v4, v4
	v_cvt_i32_f32_e32 v5, v5
	v_rndne_f32_e32 v6, v6
	v_rndne_f32_e32 v7, v7
	v_lshlrev_b32_e32 v8, 16, v46
	v_mul_f32_e32 v9, v134, v9
	v_lshlrev_b32_e32 v10, 16, v38
	v_and_b32_e32 v11, 0xffff0000, v38
	v_cvt_i32_f32_e32 v4, v4
	v_cvt_i32_f32_sdwa v6, v6 dst_sel:WORD_1 dst_unused:UNUSED_PAD src0_sel:DWORD
	v_cvt_i32_f32_e32 v7, v7
	v_mul_f32_e32 v8, v134, v8
	v_rndne_f32_e32 v9, v9
	v_mul_f32_e32 v10, v134, v10
	v_mul_f32_e32 v11, v134, v11
	v_rndne_f32_e32 v8, v8
	v_cvt_i32_f32_e32 v9, v9
	v_rndne_f32_e32 v10, v10
	v_rndne_f32_e32 v11, v11
	v_cvt_i32_f32_e32 v8, v8
	v_cvt_i32_f32_sdwa v10, v10 dst_sel:WORD_1 dst_unused:UNUSED_PAD src0_sel:DWORD
	v_cvt_i32_f32_e32 v11, v11
	v_lshlrev_b32_e32 v5, 8, v5
	v_and_b32_e32 v5, 0xff00, v5
	v_and_b32_e32 v6, 0xff0000, v6
	v_perm_b32 v4, v7, v4, s81
	v_or3_b32 v4, v4, v5, v6
	v_lshlrev_b32_e32 v5, 8, v9
	v_and_b32_e32 v5, 0xff00, v5
	v_and_b32_e32 v6, 0xff0000, v10
	v_perm_b32 v7, v11, v8, s81
	v_or3_b32 v5, v7, v5, v6
	v_add_co_u32_e32 v6, vcc, s67, v2
	v_cvt_pk_bf16_f32 v43, v43, v47
	s_nop 0
	v_addc_co_u32_e32 v7, vcc, 0, v3, vcc
	flat_store_dwordx2 v[6:7], v[4:5]
	v_and_b32_e32 v5, 0xffff0000, v34
	v_cvt_pk_bf16_f32 v47, v50, v54
	v_lshlrev_b32_e32 v4, 16, v34
	v_mul_f32_e32 v5, v131, v5
	v_lshlrev_b32_e32 v6, 16, v42
	v_and_b32_e32 v7, 0xffff0000, v42
	v_cvt_pk_bf16_f32 v35, v35, v39
	v_cvt_pk_bf16_f32 v39, v58, v62
	v_mul_f32_e32 v4, v131, v4
	v_rndne_f32_e32 v5, v5
	v_mul_f32_e32 v6, v131, v6
	v_mul_f32_e32 v7, v131, v7
	v_and_b32_e32 v9, 0xffff0000, v47
	v_rndne_f32_e32 v4, v4
	v_cvt_i32_f32_e32 v5, v5
	v_rndne_f32_e32 v6, v6
	v_rndne_f32_e32 v7, v7
	v_lshlrev_b32_e32 v8, 16, v47
	v_mul_f32_e32 v9, v131, v9
	v_lshlrev_b32_e32 v10, 16, v39
	v_and_b32_e32 v11, 0xffff0000, v39
	v_cvt_i32_f32_e32 v4, v4
	v_cvt_i32_f32_sdwa v6, v6 dst_sel:WORD_1 dst_unused:UNUSED_PAD src0_sel:DWORD
	v_cvt_i32_f32_e32 v7, v7
	v_mul_f32_e32 v8, v131, v8
	v_rndne_f32_e32 v9, v9
	v_mul_f32_e32 v10, v131, v10
	v_mul_f32_e32 v11, v131, v11
	v_rndne_f32_e32 v8, v8
	v_cvt_i32_f32_e32 v9, v9
	v_rndne_f32_e32 v10, v10
	v_rndne_f32_e32 v11, v11
	v_cvt_i32_f32_e32 v8, v8
	v_cvt_i32_f32_sdwa v10, v10 dst_sel:WORD_1 dst_unused:UNUSED_PAD src0_sel:DWORD
	v_cvt_i32_f32_e32 v11, v11
	v_lshlrev_b32_e32 v5, 8, v5
	v_and_b32_e32 v5, 0xff00, v5
	v_and_b32_e32 v6, 0xff0000, v6
	v_perm_b32 v4, v7, v4, s81
	v_or3_b32 v4, v4, v5, v6
	v_lshlrev_b32_e32 v5, 8, v9
	v_and_b32_e32 v5, 0xff00, v5
	v_and_b32_e32 v6, 0xff0000, v10
	v_perm_b32 v7, v11, v8, s81
	v_or3_b32 v5, v7, v5, v6
	v_add_co_u32_e32 v6, vcc, s33, v2
	v_cvt_pk_bf16_f32 v51, v51, v55
	s_nop 0
	v_addc_co_u32_e32 v7, vcc, 0, v3, vcc
	flat_store_dwordx2 v[6:7], v[4:5]
	v_and_b32_e32 v5, 0xffff0000, v35
	v_lshlrev_b32_e32 v4, 16, v35
	v_mul_f32_e32 v5, v130, v5
	v_lshlrev_b32_e32 v6, 16, v43
	v_and_b32_e32 v7, 0xffff0000, v43
	v_cvt_pk_bf16_f32 v59, v59, v63
	v_mul_f32_e32 v4, v130, v4
	v_rndne_f32_e32 v5, v5
	v_mul_f32_e32 v6, v130, v6
	v_mul_f32_e32 v7, v130, v7
	v_and_b32_e32 v9, 0xffff0000, v51
	v_rndne_f32_e32 v4, v4
	v_cvt_i32_f32_e32 v5, v5
	v_rndne_f32_e32 v6, v6
	v_rndne_f32_e32 v7, v7
	v_lshlrev_b32_e32 v8, 16, v51
	v_mul_f32_e32 v9, v130, v9
	v_lshlrev_b32_e32 v10, 16, v59
	v_and_b32_e32 v11, 0xffff0000, v59
	v_cvt_i32_f32_e32 v4, v4
	v_cvt_i32_f32_sdwa v6, v6 dst_sel:WORD_1 dst_unused:UNUSED_PAD src0_sel:DWORD
	v_cvt_i32_f32_e32 v7, v7
	v_mul_f32_e32 v8, v130, v8
	v_rndne_f32_e32 v9, v9
	v_mul_f32_e32 v10, v130, v10
	v_mul_f32_e32 v11, v130, v11
	v_rndne_f32_e32 v8, v8
	v_cvt_i32_f32_e32 v9, v9
	v_rndne_f32_e32 v10, v10
	v_rndne_f32_e32 v11, v11
	v_cvt_i32_f32_e32 v8, v8
	v_cvt_i32_f32_sdwa v10, v10 dst_sel:WORD_1 dst_unused:UNUSED_PAD src0_sel:DWORD
	v_cvt_i32_f32_e32 v11, v11
	v_lshlrev_b32_e32 v5, 8, v5
	v_and_b32_e32 v5, 0xff00, v5
	v_and_b32_e32 v6, 0xff0000, v6
	v_perm_b32 v4, v7, v4, s81
	v_or3_b32 v4, v4, v5, v6
	v_lshlrev_b32_e32 v5, 8, v9
	v_and_b32_e32 v5, 0xff00, v5
	v_and_b32_e32 v6, 0xff0000, v10
	v_perm_b32 v7, v11, v8, s81
	v_add_co_u32_e32 v2, vcc, s44, v2
	v_cvt_pk_bf16_f32 v64, v64, v68
	v_or3_b32 v5, v7, v5, v6
	v_addc_co_u32_e32 v3, vcc, 0, v3, vcc
	v_cvt_pk_bf16_f32 v72, v72, v76
	flat_store_dwordx2 v[2:3], v[4:5]
	v_and_b32_e32 v5, 0xffff0000, v64
	v_cvt_pk_bf16_f32 v73, v73, v77
	v_cvt_pk_bf16_f32 v77, v80, v84
	v_lshlrev_b32_e32 v4, 16, v64
	v_mul_f32_e32 v5, v135, v5
	v_lshlrev_b32_e32 v6, 16, v72
	v_and_b32_e32 v7, 0xffff0000, v72
	v_cvt_pk_bf16_f32 v65, v65, v69
	v_cvt_pk_bf16_f32 v69, v88, v92
	v_mul_f32_e32 v4, v135, v4
	v_rndne_f32_e32 v5, v5
	v_mul_f32_e32 v6, v135, v6
	v_mul_f32_e32 v7, v135, v7
	v_and_b32_e32 v9, 0xffff0000, v77
	v_rndne_f32_e32 v4, v4
	v_cvt_i32_f32_e32 v5, v5
	v_rndne_f32_e32 v6, v6
	v_rndne_f32_e32 v7, v7
	v_lshlrev_b32_e32 v8, 16, v77
	v_mul_f32_e32 v9, v135, v9
	v_lshlrev_b32_e32 v10, 16, v69
	v_and_b32_e32 v11, 0xffff0000, v69
	v_cvt_i32_f32_e32 v4, v4
	v_cvt_i32_f32_sdwa v6, v6 dst_sel:WORD_1 dst_unused:UNUSED_PAD src0_sel:DWORD
	v_cvt_i32_f32_e32 v7, v7
	v_mul_f32_e32 v8, v135, v8
	v_rndne_f32_e32 v9, v9
	v_mul_f32_e32 v10, v135, v10
	v_mul_f32_e32 v11, v135, v11
	v_rndne_f32_e32 v8, v8
	v_cvt_i32_f32_e32 v9, v9
	v_rndne_f32_e32 v10, v10
	v_rndne_f32_e32 v11, v11
; #define LAS __attribute__((address_space(3)))
; __device__ __forceinline__ float bflo(unsigned w) { return __uint_as_float(w << 16); }
; __device__ __forceinline__ float bfhi(unsigned w) { return __uint_as_float(w & 0xffff0000u); }
; __device__ __forceinline__ void direct_w8_block(const Ctx& c, LAS unsigned char* lds, const float* Wsrc, const int INC_, int srccol, unsigned char* dstrow, float* swdst) {
;     ...
; #pragma unroll
;     for (int t = 0; t < 8; ++t) { unsigned char* dt = dst + t * 64; asm volatile("" : "+v"(dt));
; #pragma unroll
;         for (int j = 0; j < 4; ++j) { v4u pk;
;             if (t < 4) { pk.x = held[t & 3][j][0]; pk.y = held[t & 3][j][1]; pk.z = held[t & 3][j][2]; pk.w = held[t & 3][j][3]; }
;             else pk = *(const LAS v4u*)(hl + ((t - 4) * 4 + j) * 1024);
;             int qi[8];
; #pragma unroll
;             for (int pr = 0; pr < 4; ++pr) { qi[2 * pr] = __float2int_rn(bflo(pk[pr]) * inv[j]); qi[2 * pr + 1] = __float2int_rn(bfhi(pk[pr]) * inv[j]); }
;             v2u w; w.x = (unsigned)(qi[0] & 255) | ((unsigned)(qi[1] & 255) << 8) | ((unsigned)(qi[2] & 255) << 16) | ((unsigned)(qi[3] & 255) << 24);
;             w.y = (unsigned)(qi[4] & 255) | ((unsigned)(qi[5] & 255) << 8) | ((unsigned)(qi[6] & 255) << 16) | ((unsigned)(qi[7] & 255) << 24);
;             *(v2u*)(dt + (size_t)j * DM) = w; } }
	v_cvt_i32_f32_e32 v8, v8
	v_cvt_i32_f32_sdwa v10, v10 dst_sel:WORD_1 dst_unused:UNUSED_PAD src0_sel:DWORD
	v_cvt_i32_f32_e32 v11, v11
	v_lshlrev_b32_e32 v5, 8, v5
	v_and_b32_e32 v5, 0xff00, v5
	v_and_b32_e32 v6, 0xff0000, v6
	v_perm_b32 v4, v7, v4, s81
	v_or3_b32 v4, v4, v5, v6
	v_lshlrev_b32_e32 v5, 8, v9
	v_and_b32_e32 v5, 0xff00, v5
	v_and_b32_e32 v6, 0xff0000, v10
	v_perm_b32 v7, v11, v8, s81
	v_lshl_add_u64 v[2:3], v[0:1], 0, s[42:43]
	v_or3_b32 v5, v7, v5, v6
	flat_store_dwordx2 v[2:3], v[4:5]
	v_and_b32_e32 v5, 0xffff0000, v65
	v_cvt_pk_bf16_f32 v74, v74, v78
	v_cvt_pk_bf16_f32 v78, v81, v85
	v_lshlrev_b32_e32 v4, 16, v65
	v_mul_f32_e32 v5, v134, v5
	v_lshlrev_b32_e32 v6, 16, v73
	v_and_b32_e32 v7, 0xffff0000, v73
	v_cvt_pk_bf16_f32 v66, v66, v70
	v_cvt_pk_bf16_f32 v70, v89, v93
	v_mul_f32_e32 v4, v134, v4
	v_rndne_f32_e32 v5, v5
	v_mul_f32_e32 v6, v134, v6
	v_mul_f32_e32 v7, v134, v7
	v_and_b32_e32 v9, 0xffff0000, v78
	v_rndne_f32_e32 v4, v4
	v_cvt_i32_f32_e32 v5, v5
	v_rndne_f32_e32 v6, v6
	v_rndne_f32_e32 v7, v7
	v_lshlrev_b32_e32 v8, 16, v78
	v_mul_f32_e32 v9, v134, v9
	v_lshlrev_b32_e32 v10, 16, v70
	v_and_b32_e32 v11, 0xffff0000, v70
	v_cvt_i32_f32_e32 v4, v4
	v_cvt_i32_f32_sdwa v6, v6 dst_sel:WORD_1 dst_unused:UNUSED_PAD src0_sel:DWORD
	v_cvt_i32_f32_e32 v7, v7
	v_mul_f32_e32 v8, v134, v8
	v_rndne_f32_e32 v9, v9
	v_mul_f32_e32 v10, v134, v10
	v_mul_f32_e32 v11, v134, v11
	v_rndne_f32_e32 v8, v8
	v_cvt_i32_f32_e32 v9, v9
	v_rndne_f32_e32 v10, v10
	v_rndne_f32_e32 v11, v11
	v_cvt_i32_f32_e32 v8, v8
	v_cvt_i32_f32_sdwa v10, v10 dst_sel:WORD_1 dst_unused:UNUSED_PAD src0_sel:DWORD
	v_cvt_i32_f32_e32 v11, v11
	v_lshlrev_b32_e32 v5, 8, v5
	v_and_b32_e32 v5, 0xff00, v5
	v_and_b32_e32 v6, 0xff0000, v6
	v_perm_b32 v4, v7, v4, s81
	v_or3_b32 v4, v4, v5, v6
	v_lshlrev_b32_e32 v5, 8, v9
	v_and_b32_e32 v5, 0xff00, v5
	v_and_b32_e32 v6, 0xff0000, v10
	v_perm_b32 v7, v11, v8, s81
	v_or3_b32 v5, v7, v5, v6
	v_add_co_u32_e32 v6, vcc, s67, v2
	v_cvt_pk_bf16_f32 v75, v75, v79
	s_nop 0
	v_addc_co_u32_e32 v7, vcc, 0, v3, vcc
	flat_store_dwordx2 v[6:7], v[4:5]
	v_and_b32_e32 v5, 0xffff0000, v66
	v_cvt_pk_bf16_f32 v79, v82, v86
	v_lshlrev_b32_e32 v4, 16, v66
	v_mul_f32_e32 v5, v131, v5
	v_lshlrev_b32_e32 v6, 16, v74
	v_and_b32_e32 v7, 0xffff0000, v74
	v_cvt_pk_bf16_f32 v67, v67, v71
	v_cvt_pk_bf16_f32 v71, v90, v94
	v_mul_f32_e32 v4, v131, v4
	v_rndne_f32_e32 v5, v5
	v_mul_f32_e32 v6, v131, v6
	v_mul_f32_e32 v7, v131, v7
	v_and_b32_e32 v9, 0xffff0000, v79
	v_rndne_f32_e32 v4, v4
	v_cvt_i32_f32_e32 v5, v5
	v_rndne_f32_e32 v6, v6
	v_rndne_f32_e32 v7, v7
	v_lshlrev_b32_e32 v8, 16, v79
	v_mul_f32_e32 v9, v131, v9
	v_lshlrev_b32_e32 v10, 16, v71
	v_and_b32_e32 v11, 0xffff0000, v71
	v_cvt_i32_f32_e32 v4, v4
	v_cvt_i32_f32_sdwa v6, v6 dst_sel:WORD_1 dst_unused:UNUSED_PAD src0_sel:DWORD
	v_cvt_i32_f32_e32 v7, v7
	v_mul_f32_e32 v8, v131, v8
	v_rndne_f32_e32 v9, v9
	v_mul_f32_e32 v10, v131, v10
	v_mul_f32_e32 v11, v131, v11
	v_rndne_f32_e32 v8, v8
	v_cvt_i32_f32_e32 v9, v9
	v_rndne_f32_e32 v10, v10
	v_rndne_f32_e32 v11, v11
	v_cvt_i32_f32_e32 v8, v8
	v_cvt_i32_f32_sdwa v10, v10 dst_sel:WORD_1 dst_unused:UNUSED_PAD src0_sel:DWORD
	v_cvt_i32_f32_e32 v11, v11
	v_lshlrev_b32_e32 v5, 8, v5
	v_and_b32_e32 v5, 0xff00, v5
	v_and_b32_e32 v6, 0xff0000, v6
	v_perm_b32 v4, v7, v4, s81
	v_or3_b32 v4, v4, v5, v6
	v_lshlrev_b32_e32 v5, 8, v9
	v_and_b32_e32 v5, 0xff00, v5
	v_and_b32_e32 v6, 0xff0000, v10
	v_perm_b32 v7, v11, v8, s81
	v_or3_b32 v5, v7, v5, v6
	v_add_co_u32_e32 v6, vcc, s33, v2
	v_cvt_pk_bf16_f32 v83, v83, v87
	s_nop 0
	v_addc_co_u32_e32 v7, vcc, 0, v3, vcc
	flat_store_dwordx2 v[6:7], v[4:5]
	v_and_b32_e32 v5, 0xffff0000, v67
	v_lshlrev_b32_e32 v4, 16, v67
	v_mul_f32_e32 v5, v130, v5
	v_lshlrev_b32_e32 v6, 16, v75
	v_and_b32_e32 v7, 0xffff0000, v75
	v_cvt_pk_bf16_f32 v91, v91, v95
	v_mul_f32_e32 v4, v130, v4
	v_rndne_f32_e32 v5, v5
	v_mul_f32_e32 v6, v130, v6
	v_mul_f32_e32 v7, v130, v7
	v_and_b32_e32 v9, 0xffff0000, v83
	v_rndne_f32_e32 v4, v4
	v_cvt_i32_f32_e32 v5, v5
	v_rndne_f32_e32 v6, v6
	v_rndne_f32_e32 v7, v7
	v_lshlrev_b32_e32 v8, 16, v83
	v_mul_f32_e32 v9, v130, v9
	v_lshlrev_b32_e32 v10, 16, v91
	v_and_b32_e32 v11, 0xffff0000, v91
	v_cvt_i32_f32_e32 v4, v4
	v_cvt_i32_f32_sdwa v6, v6 dst_sel:WORD_1 dst_unused:UNUSED_PAD src0_sel:DWORD
	v_cvt_i32_f32_e32 v7, v7
	v_mul_f32_e32 v8, v130, v8
	v_rndne_f32_e32 v9, v9
	v_mul_f32_e32 v10, v130, v10
	v_mul_f32_e32 v11, v130, v11
	v_rndne_f32_e32 v8, v8
	v_cvt_i32_f32_e32 v9, v9
	v_rndne_f32_e32 v10, v10
	v_rndne_f32_e32 v11, v11
	v_cvt_i32_f32_e32 v8, v8
	v_cvt_i32_f32_sdwa v10, v10 dst_sel:WORD_1 dst_unused:UNUSED_PAD src0_sel:DWORD
	v_cvt_i32_f32_e32 v11, v11
	v_lshlrev_b32_e32 v5, 8, v5
	v_and_b32_e32 v5, 0xff00, v5
	v_and_b32_e32 v6, 0xff0000, v6
	v_perm_b32 v4, v7, v4, s81
	v_or3_b32 v4, v4, v5, v6
	v_lshlrev_b32_e32 v5, 8, v9
	v_and_b32_e32 v5, 0xff00, v5
	v_and_b32_e32 v6, 0xff0000, v10
	v_perm_b32 v7, v11, v8, s81
	v_add_co_u32_e32 v2, vcc, s44, v2
	v_cvt_pk_bf16_f32 v98, v98, v102
	v_or3_b32 v5, v7, v5, v6
	v_addc_co_u32_e32 v3, vcc, 0, v3, vcc
	v_cvt_pk_bf16_f32 v106, v106, v110
	flat_store_dwordx2 v[2:3], v[4:5]
	v_and_b32_e32 v5, 0xffff0000, v98
	v_cvt_pk_bf16_f32 v107, v107, v111
	v_cvt_pk_bf16_f32 v111, v114, v118
	v_lshlrev_b32_e32 v4, 16, v98
	v_mul_f32_e32 v5, v135, v5
	v_lshlrev_b32_e32 v6, 16, v106
	v_and_b32_e32 v7, 0xffff0000, v106
	v_cvt_pk_bf16_f32 v99, v99, v103
	v_cvt_pk_bf16_f32 v103, v122, v126
	v_mul_f32_e32 v4, v135, v4
	v_rndne_f32_e32 v5, v5
	v_mul_f32_e32 v6, v135, v6
	v_mul_f32_e32 v7, v135, v7
	v_and_b32_e32 v9, 0xffff0000, v111
	v_rndne_f32_e32 v4, v4
	v_cvt_i32_f32_e32 v5, v5
; #define LAS __attribute__((address_space(3)))
; __device__ __forceinline__ float bflo(unsigned w) { return __uint_as_float(w << 16); }
; __device__ __forceinline__ float bfhi(unsigned w) { return __uint_as_float(w & 0xffff0000u); }
; __device__ __forceinline__ void direct_w8_block(const Ctx& c, LAS unsigned char* lds, const float* Wsrc, const int INC_, int srccol, unsigned char* dstrow, float* swdst) {
;     ...
; #pragma unroll
;     for (int t = 0; t < 8; ++t) { unsigned char* dt = dst + t * 64; asm volatile("" : "+v"(dt));
; #pragma unroll
;         for (int j = 0; j < 4; ++j) { v4u pk;
;             if (t < 4) { pk.x = held[t & 3][j][0]; pk.y = held[t & 3][j][1]; pk.z = held[t & 3][j][2]; pk.w = held[t & 3][j][3]; }
;             else pk = *(const LAS v4u*)(hl + ((t - 4) * 4 + j) * 1024);
;             int qi[8];
; #pragma unroll
;             for (int pr = 0; pr < 4; ++pr) { qi[2 * pr] = __float2int_rn(bflo(pk[pr]) * inv[j]); qi[2 * pr + 1] = __float2int_rn(bfhi(pk[pr]) * inv[j]); }
;             v2u w; w.x = (unsigned)(qi[0] & 255) | ((unsigned)(qi[1] & 255) << 8) | ((unsigned)(qi[2] & 255) << 16) | ((unsigned)(qi[3] & 255) << 24);
;             w.y = (unsigned)(qi[4] & 255) | ((unsigned)(qi[5] & 255) << 8) | ((unsigned)(qi[6] & 255) << 16) | ((unsigned)(qi[7] & 255) << 24);
;             *(v2u*)(dt + (size_t)j * DM) = w; } }
; __device__ __forceinline__ void phase_tail_transposes(LAS unsigned char* lds, int part, int wv) {
;     ...
;         for (int k = (idx + rot) % nidle; k < NB1 - NT0; k += nidle) direct_win_block(c, lds, 1, NT0 + k); }
	v_rndne_f32_e32 v6, v6
	v_rndne_f32_e32 v7, v7
	v_lshlrev_b32_e32 v8, 16, v111
	v_mul_f32_e32 v9, v135, v9
	v_lshlrev_b32_e32 v10, 16, v103
	v_and_b32_e32 v11, 0xffff0000, v103
	v_cvt_i32_f32_e32 v4, v4
	v_cvt_i32_f32_sdwa v6, v6 dst_sel:WORD_1 dst_unused:UNUSED_PAD src0_sel:DWORD
	v_cvt_i32_f32_e32 v7, v7
	v_mul_f32_e32 v8, v135, v8
	v_rndne_f32_e32 v9, v9
	v_mul_f32_e32 v10, v135, v10
	v_mul_f32_e32 v11, v135, v11
	v_rndne_f32_e32 v8, v8
	v_cvt_i32_f32_e32 v9, v9
	v_rndne_f32_e32 v10, v10
	v_rndne_f32_e32 v11, v11
	v_cvt_i32_f32_e32 v8, v8
	v_cvt_i32_f32_sdwa v10, v10 dst_sel:WORD_1 dst_unused:UNUSED_PAD src0_sel:DWORD
	v_cvt_i32_f32_e32 v11, v11
	v_lshlrev_b32_e32 v5, 8, v5
	v_and_b32_e32 v5, 0xff00, v5
	v_and_b32_e32 v6, 0xff0000, v6
	v_perm_b32 v4, v7, v4, s81
	v_or3_b32 v4, v4, v5, v6
	v_lshlrev_b32_e32 v5, 8, v9
	s_mov_b64 s[4:5], 0xc0
	v_and_b32_e32 v5, 0xff00, v5
	v_and_b32_e32 v6, 0xff0000, v10
	v_perm_b32 v7, v11, v8, s81
	v_lshl_add_u64 v[2:3], v[0:1], 0, s[4:5]
	v_or3_b32 v5, v7, v5, v6
	flat_store_dwordx2 v[2:3], v[4:5]
	v_and_b32_e32 v5, 0xffff0000, v99
	v_cvt_pk_bf16_f32 v108, v108, v112
	v_cvt_pk_bf16_f32 v112, v115, v119
	v_lshlrev_b32_e32 v4, 16, v99
	v_mul_f32_e32 v5, v134, v5
	v_lshlrev_b32_e32 v6, 16, v107
	v_and_b32_e32 v7, 0xffff0000, v107
	v_cvt_pk_bf16_f32 v100, v100, v104
	v_cvt_pk_bf16_f32 v104, v123, v127
	v_mul_f32_e32 v4, v134, v4
	v_rndne_f32_e32 v5, v5
	v_mul_f32_e32 v6, v134, v6
	v_mul_f32_e32 v7, v134, v7
	v_and_b32_e32 v9, 0xffff0000, v112
	v_rndne_f32_e32 v4, v4
	v_cvt_i32_f32_e32 v5, v5
	v_rndne_f32_e32 v6, v6
	v_rndne_f32_e32 v7, v7
	v_lshlrev_b32_e32 v8, 16, v112
	v_mul_f32_e32 v9, v134, v9
	v_lshlrev_b32_e32 v10, 16, v104
	v_and_b32_e32 v11, 0xffff0000, v104
	v_cvt_i32_f32_e32 v4, v4
	v_cvt_i32_f32_sdwa v6, v6 dst_sel:WORD_1 dst_unused:UNUSED_PAD src0_sel:DWORD
	v_cvt_i32_f32_e32 v7, v7
	v_mul_f32_e32 v8, v134, v8
	v_rndne_f32_e32 v9, v9
	v_mul_f32_e32 v10, v134, v10
	v_mul_f32_e32 v11, v134, v11
	v_rndne_f32_e32 v8, v8
	v_cvt_i32_f32_e32 v9, v9
	v_rndne_f32_e32 v10, v10
	v_rndne_f32_e32 v11, v11
	v_cvt_i32_f32_e32 v8, v8
	v_cvt_i32_f32_sdwa v10, v10 dst_sel:WORD_1 dst_unused:UNUSED_PAD src0_sel:DWORD
	v_cvt_i32_f32_e32 v11, v11
	v_lshlrev_b32_e32 v5, 8, v5
	v_and_b32_e32 v5, 0xff00, v5
	v_and_b32_e32 v6, 0xff0000, v6
	v_perm_b32 v4, v7, v4, s81
	v_or3_b32 v4, v4, v5, v6
	v_lshlrev_b32_e32 v5, 8, v9
	v_and_b32_e32 v5, 0xff00, v5
	v_and_b32_e32 v6, 0xff0000, v10
	v_perm_b32 v7, v11, v8, s81
	v_or3_b32 v5, v7, v5, v6
	v_add_co_u32_e32 v6, vcc, s67, v2
	v_cvt_pk_bf16_f32 v109, v109, v113
	s_nop 0
	v_addc_co_u32_e32 v7, vcc, 0, v3, vcc
	flat_store_dwordx2 v[6:7], v[4:5]
	v_and_b32_e32 v5, 0xffff0000, v100
	v_cvt_pk_bf16_f32 v113, v116, v120
	v_lshlrev_b32_e32 v4, 16, v100
	v_mul_f32_e32 v5, v131, v5
	v_lshlrev_b32_e32 v6, 16, v108
	v_and_b32_e32 v7, 0xffff0000, v108
	v_cvt_pk_bf16_f32 v101, v101, v105
	v_cvt_pk_bf16_f32 v105, v124, v128
	v_mul_f32_e32 v4, v131, v4
	v_rndne_f32_e32 v5, v5
	v_mul_f32_e32 v6, v131, v6
	v_mul_f32_e32 v7, v131, v7
	v_and_b32_e32 v9, 0xffff0000, v113
	v_rndne_f32_e32 v4, v4
	v_cvt_i32_f32_e32 v5, v5
	v_rndne_f32_e32 v6, v6
	v_rndne_f32_e32 v7, v7
	v_lshlrev_b32_e32 v8, 16, v113
	v_mul_f32_e32 v9, v131, v9
	v_lshlrev_b32_e32 v10, 16, v105
	v_and_b32_e32 v11, 0xffff0000, v105
	v_cvt_i32_f32_e32 v4, v4
	v_cvt_i32_f32_sdwa v6, v6 dst_sel:WORD_1 dst_unused:UNUSED_PAD src0_sel:DWORD
	v_cvt_i32_f32_e32 v7, v7
	v_mul_f32_e32 v8, v131, v8
	v_rndne_f32_e32 v9, v9
	v_mul_f32_e32 v10, v131, v10
	v_mul_f32_e32 v11, v131, v11
	v_rndne_f32_e32 v8, v8
	v_cvt_i32_f32_e32 v9, v9
	v_rndne_f32_e32 v10, v10
	v_rndne_f32_e32 v11, v11
	v_cvt_i32_f32_e32 v8, v8
	v_cvt_i32_f32_sdwa v10, v10 dst_sel:WORD_1 dst_unused:UNUSED_PAD src0_sel:DWORD
	v_cvt_i32_f32_e32 v11, v11
	v_lshlrev_b32_e32 v5, 8, v5
	v_and_b32_e32 v5, 0xff00, v5
	v_and_b32_e32 v6, 0xff0000, v6
	v_perm_b32 v4, v7, v4, s81
	v_or3_b32 v4, v4, v5, v6
	v_lshlrev_b32_e32 v5, 8, v9
	v_and_b32_e32 v5, 0xff00, v5
	v_and_b32_e32 v6, 0xff0000, v10
	v_perm_b32 v7, v11, v8, s81
	v_or3_b32 v5, v7, v5, v6
	v_add_co_u32_e32 v6, vcc, s33, v2
	v_cvt_pk_bf16_f32 v117, v117, v121
	s_nop 0
	v_addc_co_u32_e32 v7, vcc, 0, v3, vcc
	flat_store_dwordx2 v[6:7], v[4:5]
	v_and_b32_e32 v5, 0xffff0000, v101
	v_lshlrev_b32_e32 v4, 16, v101
	v_mul_f32_e32 v5, v130, v5
	v_lshlrev_b32_e32 v6, 16, v109
	v_and_b32_e32 v7, 0xffff0000, v109
	v_cvt_pk_bf16_f32 v125, v125, v129
	v_mul_f32_e32 v4, v130, v4
	v_rndne_f32_e32 v5, v5
	v_mul_f32_e32 v6, v130, v6
	v_mul_f32_e32 v7, v130, v7
	v_and_b32_e32 v9, 0xffff0000, v117
	v_rndne_f32_e32 v4, v4
	v_cvt_i32_f32_e32 v5, v5
	v_rndne_f32_e32 v6, v6
	v_rndne_f32_e32 v7, v7
	v_lshlrev_b32_e32 v8, 16, v117
	v_mul_f32_e32 v9, v130, v9
	v_lshlrev_b32_e32 v10, 16, v125
	v_and_b32_e32 v11, 0xffff0000, v125
	v_cvt_i32_f32_e32 v4, v4
	v_cvt_i32_f32_sdwa v6, v6 dst_sel:WORD_1 dst_unused:UNUSED_PAD src0_sel:DWORD
	v_cvt_i32_f32_e32 v7, v7
	v_mul_f32_e32 v8, v130, v8
	v_rndne_f32_e32 v9, v9
	v_mul_f32_e32 v10, v130, v10
	v_mul_f32_e32 v11, v130, v11
	v_rndne_f32_e32 v8, v8
	v_cvt_i32_f32_e32 v9, v9
	v_rndne_f32_e32 v10, v10
	v_rndne_f32_e32 v11, v11
	v_cvt_i32_f32_e32 v8, v8
	v_cvt_i32_f32_sdwa v10, v10 dst_sel:WORD_1 dst_unused:UNUSED_PAD src0_sel:DWORD
	v_cvt_i32_f32_e32 v11, v11
	v_lshlrev_b32_e32 v5, 8, v5
	v_and_b32_e32 v5, 0xff00, v5
	v_and_b32_e32 v6, 0xff0000, v6
	v_perm_b32 v4, v7, v4, s81
	v_or3_b32 v4, v4, v5, v6
	v_lshlrev_b32_e32 v5, 8, v9
	v_and_b32_e32 v5, 0xff00, v5
	v_and_b32_e32 v6, 0xff0000, v10
	v_perm_b32 v7, v11, v8, s81
	v_add_co_u32_e32 v2, vcc, s44, v2
	s_mov_b64 s[4:5], 0x100
	v_or3_b32 v5, v7, v5, v6
	v_addc_co_u32_e32 v3, vcc, 0, v3, vcc
	v_lshl_add_u64 v[6:7], v[0:1], 0, s[4:5]
	flat_store_dwordx2 v[2:3], v[4:5]
	ds_read_b128 v[2:5], v96
	s_mov_b64 s[4:5], 0x140
	s_add_i32 s3, s3, s0
	s_add_i32 s12, s12, s1
	s_cmpk_lt_i32 s3, 0x1e0
	s_waitcnt lgkmcnt(0)
; #define LAS __attribute__((address_space(3)))
; __device__ __forceinline__ float bflo(unsigned w) { return __uint_as_float(w << 16); }
; __device__ __forceinline__ float bfhi(unsigned w) { return __uint_as_float(w & 0xffff0000u); }
; __device__ __forceinline__ void direct_w8_block(const Ctx& c, LAS unsigned char* lds, const float* Wsrc, const int INC_, int srccol, unsigned char* dstrow, float* swdst) {
;     ...
; #pragma unroll
;     for (int t = 0; t < 8; ++t) { unsigned char* dt = dst + t * 64; asm volatile("" : "+v"(dt));
; #pragma unroll
;         for (int j = 0; j < 4; ++j) { v4u pk;
;             if (t < 4) { pk.x = held[t & 3][j][0]; pk.y = held[t & 3][j][1]; pk.z = held[t & 3][j][2]; pk.w = held[t & 3][j][3]; }
;             else pk = *(const LAS v4u*)(hl + ((t - 4) * 4 + j) * 1024);
;             int qi[8];
; #pragma unroll
;             for (int pr = 0; pr < 4; ++pr) { qi[2 * pr] = __float2int_rn(bflo(pk[pr]) * inv[j]); qi[2 * pr + 1] = __float2int_rn(bfhi(pk[pr]) * inv[j]); }
;             v2u w; w.x = (unsigned)(qi[0] & 255) | ((unsigned)(qi[1] & 255) << 8) | ((unsigned)(qi[2] & 255) << 16) | ((unsigned)(qi[3] & 255) << 24);
;             w.y = (unsigned)(qi[4] & 255) | ((unsigned)(qi[5] & 255) << 8) | ((unsigned)(qi[6] & 255) << 16) | ((unsigned)(qi[7] & 255) << 24);
;             *(v2u*)(dt + (size_t)j * DM) = w; } }
	v_lshlrev_b32_e32 v8, 16, v2
	v_and_b32_e32 v2, 0xffff0000, v2
	v_mul_f32_e32 v2, v135, v2
	v_lshlrev_b32_e32 v9, 16, v3
	v_and_b32_e32 v3, 0xffff0000, v3
	v_mul_f32_e32 v8, v135, v8
	v_rndne_f32_e32 v2, v2
	v_mul_f32_e32 v9, v135, v9
	v_mul_f32_e32 v3, v135, v3
	v_lshlrev_b32_e32 v10, 16, v4
	v_and_b32_e32 v4, 0xffff0000, v4
	v_rndne_f32_e32 v8, v8
	v_cvt_i32_f32_e32 v2, v2
	v_rndne_f32_e32 v9, v9
	v_rndne_f32_e32 v3, v3
	v_mul_f32_e32 v4, v135, v4
	v_lshlrev_b32_e32 v11, 16, v5
	v_and_b32_e32 v5, 0xffff0000, v5
	v_cvt_i32_f32_e32 v8, v8
	v_cvt_i32_f32_sdwa v9, v9 dst_sel:WORD_1 dst_unused:UNUSED_PAD src0_sel:DWORD
	v_cvt_i32_f32_e32 v3, v3
	v_mul_f32_e32 v10, v135, v10
	v_rndne_f32_e32 v4, v4
	v_mul_f32_e32 v11, v135, v11
	v_mul_f32_e32 v5, v135, v5
	v_rndne_f32_e32 v10, v10
	v_cvt_i32_f32_e32 v4, v4
	v_rndne_f32_e32 v11, v11
	v_rndne_f32_e32 v5, v5
	v_cvt_i32_f32_e32 v10, v10
	v_cvt_i32_f32_sdwa v11, v11 dst_sel:WORD_1 dst_unused:UNUSED_PAD src0_sel:DWORD
	v_cvt_i32_f32_e32 v5, v5
	v_lshlrev_b32_e32 v2, 8, v2
	v_and_b32_e32 v2, 0xff00, v2
	v_and_b32_e32 v9, 0xff0000, v9
	v_perm_b32 v3, v3, v8, s81
	v_or3_b32 v2, v3, v2, v9
	v_lshlrev_b32_e32 v3, 8, v4
	v_and_b32_e32 v3, 0xff00, v3
	v_and_b32_e32 v4, 0xff0000, v11
	v_perm_b32 v5, v5, v10, s81
	v_or3_b32 v3, v5, v3, v4
	flat_store_dwordx2 v[6:7], v[2:3]
	ds_read_b128 v[2:5], v96 offset:1024
	s_waitcnt lgkmcnt(0)
	v_lshlrev_b32_e32 v8, 16, v2
	v_and_b32_e32 v2, 0xffff0000, v2
	v_mul_f32_e32 v2, v134, v2
	v_lshlrev_b32_e32 v9, 16, v3
	v_and_b32_e32 v3, 0xffff0000, v3
	v_mul_f32_e32 v8, v134, v8
	v_rndne_f32_e32 v2, v2
	v_mul_f32_e32 v9, v134, v9
	v_mul_f32_e32 v3, v134, v3
	v_lshlrev_b32_e32 v10, 16, v4
	v_and_b32_e32 v4, 0xffff0000, v4
	v_rndne_f32_e32 v8, v8
	v_cvt_i32_f32_e32 v2, v2
	v_rndne_f32_e32 v9, v9
	v_rndne_f32_e32 v3, v3
	v_mul_f32_e32 v4, v134, v4
	v_lshlrev_b32_e32 v11, 16, v5
	v_and_b32_e32 v5, 0xffff0000, v5
	v_cvt_i32_f32_e32 v8, v8
	v_cvt_i32_f32_sdwa v9, v9 dst_sel:WORD_1 dst_unused:UNUSED_PAD src0_sel:DWORD
	v_cvt_i32_f32_e32 v3, v3
	v_mul_f32_e32 v10, v134, v10
	v_rndne_f32_e32 v4, v4
	v_mul_f32_e32 v11, v134, v11
	v_mul_f32_e32 v5, v134, v5
	v_rndne_f32_e32 v10, v10
	v_cvt_i32_f32_e32 v4, v4
	v_rndne_f32_e32 v11, v11
	v_rndne_f32_e32 v5, v5
	v_cvt_i32_f32_e32 v10, v10
	v_cvt_i32_f32_sdwa v11, v11 dst_sel:WORD_1 dst_unused:UNUSED_PAD src0_sel:DWORD
	v_cvt_i32_f32_e32 v5, v5
	v_lshlrev_b32_e32 v2, 8, v2
	v_and_b32_e32 v2, 0xff00, v2
	v_and_b32_e32 v9, 0xff0000, v9
	v_perm_b32 v3, v3, v8, s81
	v_or3_b32 v2, v3, v2, v9
	v_lshlrev_b32_e32 v3, 8, v4
	v_and_b32_e32 v3, 0xff00, v3
	v_and_b32_e32 v4, 0xff0000, v11
	v_perm_b32 v5, v5, v10, s81
	v_or3_b32 v3, v5, v3, v4
	v_add_co_u32_e32 v4, vcc, s67, v6
	s_nop 1
	v_addc_co_u32_e32 v5, vcc, 0, v7, vcc
	flat_store_dwordx2 v[4:5], v[2:3]
	ds_read_b128 v[2:5], v96 offset:2048
	s_waitcnt lgkmcnt(0)
	v_lshlrev_b32_e32 v8, 16, v2
	v_and_b32_e32 v2, 0xffff0000, v2
	v_mul_f32_e32 v2, v131, v2
	v_lshlrev_b32_e32 v9, 16, v3
	v_and_b32_e32 v3, 0xffff0000, v3
	v_mul_f32_e32 v8, v131, v8
	v_rndne_f32_e32 v2, v2
	v_mul_f32_e32 v9, v131, v9
	v_mul_f32_e32 v3, v131, v3
	v_lshlrev_b32_e32 v10, 16, v4
	v_and_b32_e32 v4, 0xffff0000, v4
	v_rndne_f32_e32 v8, v8
	v_cvt_i32_f32_e32 v2, v2
	v_rndne_f32_e32 v9, v9
	v_rndne_f32_e32 v3, v3
	v_mul_f32_e32 v4, v131, v4
	v_lshlrev_b32_e32 v11, 16, v5
	v_and_b32_e32 v5, 0xffff0000, v5
	v_cvt_i32_f32_e32 v8, v8
	v_cvt_i32_f32_sdwa v9, v9 dst_sel:WORD_1 dst_unused:UNUSED_PAD src0_sel:DWORD
	v_cvt_i32_f32_e32 v3, v3
	v_mul_f32_e32 v10, v131, v10
	v_rndne_f32_e32 v4, v4
	v_mul_f32_e32 v11, v131, v11
	v_mul_f32_e32 v5, v131, v5
	v_rndne_f32_e32 v10, v10
	v_cvt_i32_f32_e32 v4, v4
	v_rndne_f32_e32 v11, v11
	v_rndne_f32_e32 v5, v5
	v_cvt_i32_f32_e32 v10, v10
	v_cvt_i32_f32_sdwa v11, v11 dst_sel:WORD_1 dst_unused:UNUSED_PAD src0_sel:DWORD
	v_cvt_i32_f32_e32 v5, v5
	v_lshlrev_b32_e32 v2, 8, v2
	v_and_b32_e32 v2, 0xff00, v2
	v_and_b32_e32 v9, 0xff0000, v9
	v_perm_b32 v3, v3, v8, s81
	v_or3_b32 v2, v3, v2, v9
	v_lshlrev_b32_e32 v3, 8, v4
	v_and_b32_e32 v3, 0xff00, v3
	v_and_b32_e32 v4, 0xff0000, v11
	v_perm_b32 v5, v5, v10, s81
	v_or3_b32 v3, v5, v3, v4
	v_add_co_u32_e32 v4, vcc, s33, v6
	s_nop 1
	v_addc_co_u32_e32 v5, vcc, 0, v7, vcc
	flat_store_dwordx2 v[4:5], v[2:3]
	ds_read_b128 v[2:5], v96 offset:3072
	s_waitcnt lgkmcnt(0)
	v_lshlrev_b32_e32 v8, 16, v2
	v_and_b32_e32 v2, 0xffff0000, v2
	v_mul_f32_e32 v2, v130, v2
	v_lshlrev_b32_e32 v9, 16, v3
	v_and_b32_e32 v3, 0xffff0000, v3
	v_mul_f32_e32 v8, v130, v8
	v_rndne_f32_e32 v2, v2
	v_mul_f32_e32 v9, v130, v9
	v_mul_f32_e32 v3, v130, v3
	v_lshlrev_b32_e32 v10, 16, v4
	v_and_b32_e32 v4, 0xffff0000, v4
	v_rndne_f32_e32 v8, v8
	v_cvt_i32_f32_e32 v2, v2
	v_rndne_f32_e32 v9, v9
	v_rndne_f32_e32 v3, v3
	v_mul_f32_e32 v4, v130, v4
	v_lshlrev_b32_e32 v11, 16, v5
	v_and_b32_e32 v5, 0xffff0000, v5
	v_cvt_i32_f32_e32 v8, v8
	v_cvt_i32_f32_sdwa v9, v9 dst_sel:WORD_1 dst_unused:UNUSED_PAD src0_sel:DWORD
	v_cvt_i32_f32_e32 v3, v3
	v_mul_f32_e32 v10, v130, v10
	v_rndne_f32_e32 v4, v4
	v_mul_f32_e32 v11, v130, v11
	v_mul_f32_e32 v5, v130, v5
	v_rndne_f32_e32 v10, v10
	v_cvt_i32_f32_e32 v4, v4
	v_rndne_f32_e32 v11, v11
	v_rndne_f32_e32 v5, v5
	v_cvt_i32_f32_e32 v10, v10
	v_cvt_i32_f32_sdwa v11, v11 dst_sel:WORD_1 dst_unused:UNUSED_PAD src0_sel:DWORD
	v_cvt_i32_f32_e32 v5, v5
	v_lshlrev_b32_e32 v2, 8, v2
	v_and_b32_e32 v2, 0xff00, v2
	v_and_b32_e32 v9, 0xff0000, v9
	v_perm_b32 v3, v3, v8, s81
	v_or3_b32 v2, v3, v2, v9
	v_lshlrev_b32_e32 v3, 8, v4
	v_and_b32_e32 v3, 0xff00, v3
	v_and_b32_e32 v4, 0xff0000, v11
	v_perm_b32 v5, v5, v10, s81
	v_or3_b32 v3, v5, v3, v4
	v_add_co_u32_e32 v4, vcc, s44, v6
	s_nop 1
	v_addc_co_u32_e32 v5, vcc, 0, v7, vcc
	v_lshl_add_u64 v[6:7], v[0:1], 0, s[4:5]
	flat_store_dwordx2 v[4:5], v[2:3]
	ds_read_b128 v[2:5], v96 offset:4096
	s_mov_b64 s[4:5], 0x180
	s_waitcnt lgkmcnt(0)
; #define LAS __attribute__((address_space(3)))
; __device__ __forceinline__ float bflo(unsigned w) { return __uint_as_float(w << 16); }
; __device__ __forceinline__ float bfhi(unsigned w) { return __uint_as_float(w & 0xffff0000u); }
; __device__ __forceinline__ void direct_w8_block(const Ctx& c, LAS unsigned char* lds, const float* Wsrc, const int INC_, int srccol, unsigned char* dstrow, float* swdst) {
;     ...
; #pragma unroll
;     for (int t = 0; t < 8; ++t) { unsigned char* dt = dst + t * 64; asm volatile("" : "+v"(dt));
; #pragma unroll
;         for (int j = 0; j < 4; ++j) { v4u pk;
;             if (t < 4) { pk.x = held[t & 3][j][0]; pk.y = held[t & 3][j][1]; pk.z = held[t & 3][j][2]; pk.w = held[t & 3][j][3]; }
;             else pk = *(const LAS v4u*)(hl + ((t - 4) * 4 + j) * 1024);
;             int qi[8];
; #pragma unroll
;             for (int pr = 0; pr < 4; ++pr) { qi[2 * pr] = __float2int_rn(bflo(pk[pr]) * inv[j]); qi[2 * pr + 1] = __float2int_rn(bfhi(pk[pr]) * inv[j]); }
;             v2u w; w.x = (unsigned)(qi[0] & 255) | ((unsigned)(qi[1] & 255) << 8) | ((unsigned)(qi[2] & 255) << 16) | ((unsigned)(qi[3] & 255) << 24);
;             w.y = (unsigned)(qi[4] & 255) | ((unsigned)(qi[5] & 255) << 8) | ((unsigned)(qi[6] & 255) << 16) | ((unsigned)(qi[7] & 255) << 24);
;             *(v2u*)(dt + (size_t)j * DM) = w; } }
	v_lshlrev_b32_e32 v8, 16, v2
	v_and_b32_e32 v2, 0xffff0000, v2
	v_mul_f32_e32 v2, v135, v2
	v_lshlrev_b32_e32 v9, 16, v3
	v_and_b32_e32 v3, 0xffff0000, v3
	v_mul_f32_e32 v8, v135, v8
	v_rndne_f32_e32 v2, v2
	v_mul_f32_e32 v9, v135, v9
	v_mul_f32_e32 v3, v135, v3
	v_lshlrev_b32_e32 v10, 16, v4
	v_and_b32_e32 v4, 0xffff0000, v4
	v_rndne_f32_e32 v8, v8
	v_cvt_i32_f32_e32 v2, v2
	v_rndne_f32_e32 v9, v9
	v_rndne_f32_e32 v3, v3
	v_mul_f32_e32 v4, v135, v4
	v_lshlrev_b32_e32 v11, 16, v5
	v_and_b32_e32 v5, 0xffff0000, v5
	v_cvt_i32_f32_e32 v8, v8
	v_cvt_i32_f32_sdwa v9, v9 dst_sel:WORD_1 dst_unused:UNUSED_PAD src0_sel:DWORD
	v_cvt_i32_f32_e32 v3, v3
	v_mul_f32_e32 v10, v135, v10
	v_rndne_f32_e32 v4, v4
	v_mul_f32_e32 v11, v135, v11
	v_mul_f32_e32 v5, v135, v5
	v_rndne_f32_e32 v10, v10
	v_cvt_i32_f32_e32 v4, v4
	v_rndne_f32_e32 v11, v11
	v_rndne_f32_e32 v5, v5
	v_cvt_i32_f32_e32 v10, v10
	v_cvt_i32_f32_sdwa v11, v11 dst_sel:WORD_1 dst_unused:UNUSED_PAD src0_sel:DWORD
	v_cvt_i32_f32_e32 v5, v5
	v_lshlrev_b32_e32 v2, 8, v2
	v_and_b32_e32 v2, 0xff00, v2
	v_and_b32_e32 v9, 0xff0000, v9
	v_perm_b32 v3, v3, v8, s81
	v_or3_b32 v2, v3, v2, v9
	v_lshlrev_b32_e32 v3, 8, v4
	v_and_b32_e32 v3, 0xff00, v3
	v_and_b32_e32 v4, 0xff0000, v11
	v_perm_b32 v5, v5, v10, s81
	v_or3_b32 v3, v5, v3, v4
	flat_store_dwordx2 v[6:7], v[2:3]
	ds_read_b128 v[2:5], v96 offset:5120
	s_waitcnt lgkmcnt(0)
	v_lshlrev_b32_e32 v8, 16, v2
	v_and_b32_e32 v2, 0xffff0000, v2
	v_mul_f32_e32 v2, v134, v2
	v_lshlrev_b32_e32 v9, 16, v3
	v_and_b32_e32 v3, 0xffff0000, v3
	v_mul_f32_e32 v8, v134, v8
	v_rndne_f32_e32 v2, v2
	v_mul_f32_e32 v9, v134, v9
	v_mul_f32_e32 v3, v134, v3
	v_lshlrev_b32_e32 v10, 16, v4
	v_and_b32_e32 v4, 0xffff0000, v4
	v_rndne_f32_e32 v8, v8
	v_cvt_i32_f32_e32 v2, v2
	v_rndne_f32_e32 v9, v9
	v_rndne_f32_e32 v3, v3
	v_mul_f32_e32 v4, v134, v4
	v_lshlrev_b32_e32 v11, 16, v5
	v_and_b32_e32 v5, 0xffff0000, v5
	v_cvt_i32_f32_e32 v8, v8
	v_cvt_i32_f32_sdwa v9, v9 dst_sel:WORD_1 dst_unused:UNUSED_PAD src0_sel:DWORD
	v_cvt_i32_f32_e32 v3, v3
	v_mul_f32_e32 v10, v134, v10
	v_rndne_f32_e32 v4, v4
	v_mul_f32_e32 v11, v134, v11
	v_mul_f32_e32 v5, v134, v5
	v_rndne_f32_e32 v10, v10
	v_cvt_i32_f32_e32 v4, v4
	v_rndne_f32_e32 v11, v11
	v_rndne_f32_e32 v5, v5
	v_cvt_i32_f32_e32 v10, v10
	v_cvt_i32_f32_sdwa v11, v11 dst_sel:WORD_1 dst_unused:UNUSED_PAD src0_sel:DWORD
	v_cvt_i32_f32_e32 v5, v5
	v_lshlrev_b32_e32 v2, 8, v2
	v_and_b32_e32 v2, 0xff00, v2
	v_and_b32_e32 v9, 0xff0000, v9
	v_perm_b32 v3, v3, v8, s81
	v_or3_b32 v2, v3, v2, v9
	v_lshlrev_b32_e32 v3, 8, v4
	v_and_b32_e32 v3, 0xff00, v3
	v_and_b32_e32 v4, 0xff0000, v11
	v_perm_b32 v5, v5, v10, s81
	v_or3_b32 v3, v5, v3, v4
	v_add_co_u32_e32 v4, vcc, s67, v6
	s_nop 1
	v_addc_co_u32_e32 v5, vcc, 0, v7, vcc
	flat_store_dwordx2 v[4:5], v[2:3]
	ds_read_b128 v[2:5], v96 offset:6144
	s_waitcnt lgkmcnt(0)
	v_lshlrev_b32_e32 v8, 16, v2
	v_and_b32_e32 v2, 0xffff0000, v2
	v_mul_f32_e32 v2, v131, v2
	v_lshlrev_b32_e32 v9, 16, v3
	v_and_b32_e32 v3, 0xffff0000, v3
	v_mul_f32_e32 v8, v131, v8
	v_rndne_f32_e32 v2, v2
	v_mul_f32_e32 v9, v131, v9
	v_mul_f32_e32 v3, v131, v3
	v_lshlrev_b32_e32 v10, 16, v4
	v_and_b32_e32 v4, 0xffff0000, v4
	v_rndne_f32_e32 v8, v8
	v_cvt_i32_f32_e32 v2, v2
	v_rndne_f32_e32 v9, v9
	v_rndne_f32_e32 v3, v3
	v_mul_f32_e32 v4, v131, v4
	v_lshlrev_b32_e32 v11, 16, v5
	v_and_b32_e32 v5, 0xffff0000, v5
	v_cvt_i32_f32_e32 v8, v8
	v_cvt_i32_f32_sdwa v9, v9 dst_sel:WORD_1 dst_unused:UNUSED_PAD src0_sel:DWORD
	v_cvt_i32_f32_e32 v3, v3
	v_mul_f32_e32 v10, v131, v10
	v_rndne_f32_e32 v4, v4
	v_mul_f32_e32 v11, v131, v11
	v_mul_f32_e32 v5, v131, v5
	v_rndne_f32_e32 v10, v10
	v_cvt_i32_f32_e32 v4, v4
	v_rndne_f32_e32 v11, v11
	v_rndne_f32_e32 v5, v5
	v_cvt_i32_f32_e32 v10, v10
	v_cvt_i32_f32_sdwa v11, v11 dst_sel:WORD_1 dst_unused:UNUSED_PAD src0_sel:DWORD
	v_cvt_i32_f32_e32 v5, v5
	v_lshlrev_b32_e32 v2, 8, v2
	v_and_b32_e32 v2, 0xff00, v2
	v_and_b32_e32 v9, 0xff0000, v9
	v_perm_b32 v3, v3, v8, s81
	v_or3_b32 v2, v3, v2, v9
	v_lshlrev_b32_e32 v3, 8, v4
	v_and_b32_e32 v3, 0xff00, v3
	v_and_b32_e32 v4, 0xff0000, v11
	v_perm_b32 v5, v5, v10, s81
	v_or3_b32 v3, v5, v3, v4
	v_add_co_u32_e32 v4, vcc, s33, v6
	s_nop 1
	v_addc_co_u32_e32 v5, vcc, 0, v7, vcc
	flat_store_dwordx2 v[4:5], v[2:3]
	ds_read_b128 v[2:5], v96 offset:7168
	s_waitcnt lgkmcnt(0)
	v_lshlrev_b32_e32 v8, 16, v2
	v_and_b32_e32 v2, 0xffff0000, v2
	v_mul_f32_e32 v2, v130, v2
	v_lshlrev_b32_e32 v9, 16, v3
	v_and_b32_e32 v3, 0xffff0000, v3
	v_mul_f32_e32 v8, v130, v8
	v_rndne_f32_e32 v2, v2
	v_mul_f32_e32 v9, v130, v9
	v_mul_f32_e32 v3, v130, v3
	v_lshlrev_b32_e32 v10, 16, v4
	v_and_b32_e32 v4, 0xffff0000, v4
	v_rndne_f32_e32 v8, v8
	v_cvt_i32_f32_e32 v2, v2
	v_rndne_f32_e32 v9, v9
	v_rndne_f32_e32 v3, v3
	v_mul_f32_e32 v4, v130, v4
	v_lshlrev_b32_e32 v11, 16, v5
	v_and_b32_e32 v5, 0xffff0000, v5
	v_cvt_i32_f32_e32 v8, v8
	v_cvt_i32_f32_sdwa v9, v9 dst_sel:WORD_1 dst_unused:UNUSED_PAD src0_sel:DWORD
	v_cvt_i32_f32_e32 v3, v3
	v_mul_f32_e32 v10, v130, v10
	v_rndne_f32_e32 v4, v4
	v_mul_f32_e32 v11, v130, v11
	v_mul_f32_e32 v5, v130, v5
	v_rndne_f32_e32 v10, v10
	v_cvt_i32_f32_e32 v4, v4
	v_rndne_f32_e32 v11, v11
	v_rndne_f32_e32 v5, v5
	v_cvt_i32_f32_e32 v10, v10
	v_cvt_i32_f32_sdwa v11, v11 dst_sel:WORD_1 dst_unused:UNUSED_PAD src0_sel:DWORD
	v_cvt_i32_f32_e32 v5, v5
	v_lshlrev_b32_e32 v2, 8, v2
	v_and_b32_e32 v2, 0xff00, v2
	v_and_b32_e32 v9, 0xff0000, v9
	v_perm_b32 v3, v3, v8, s81
	v_or3_b32 v2, v3, v2, v9
	v_lshlrev_b32_e32 v3, 8, v4
	v_and_b32_e32 v3, 0xff00, v3
	v_and_b32_e32 v4, 0xff0000, v11
	v_perm_b32 v5, v5, v10, s81
	v_or3_b32 v3, v5, v3, v4
	v_add_co_u32_e32 v4, vcc, s44, v6
	s_nop 1
	v_addc_co_u32_e32 v5, vcc, 0, v7, vcc
	v_lshl_add_u64 v[6:7], v[0:1], 0, s[4:5]
	flat_store_dwordx2 v[4:5], v[2:3]
	ds_read_b128 v[2:5], v96 offset:8192
	s_mov_b64 s[4:5], 0x1c0
	s_waitcnt lgkmcnt(0)
; #define LAS __attribute__((address_space(3)))
; __device__ __forceinline__ float bflo(unsigned w) { return __uint_as_float(w << 16); }
; __device__ __forceinline__ float bfhi(unsigned w) { return __uint_as_float(w & 0xffff0000u); }
; __device__ __forceinline__ void direct_w8_block(const Ctx& c, LAS unsigned char* lds, const float* Wsrc, const int INC_, int srccol, unsigned char* dstrow, float* swdst) {
;     ...
; #pragma unroll
;     for (int t = 0; t < 8; ++t) { unsigned char* dt = dst + t * 64; asm volatile("" : "+v"(dt));
; #pragma unroll
;         for (int j = 0; j < 4; ++j) { v4u pk;
;             if (t < 4) { pk.x = held[t & 3][j][0]; pk.y = held[t & 3][j][1]; pk.z = held[t & 3][j][2]; pk.w = held[t & 3][j][3]; }
;             else pk = *(const LAS v4u*)(hl + ((t - 4) * 4 + j) * 1024);
;             int qi[8];
; #pragma unroll
;             for (int pr = 0; pr < 4; ++pr) { qi[2 * pr] = __float2int_rn(bflo(pk[pr]) * inv[j]); qi[2 * pr + 1] = __float2int_rn(bfhi(pk[pr]) * inv[j]); }
;             v2u w; w.x = (unsigned)(qi[0] & 255) | ((unsigned)(qi[1] & 255) << 8) | ((unsigned)(qi[2] & 255) << 16) | ((unsigned)(qi[3] & 255) << 24);
;             w.y = (unsigned)(qi[4] & 255) | ((unsigned)(qi[5] & 255) << 8) | ((unsigned)(qi[6] & 255) << 16) | ((unsigned)(qi[7] & 255) << 24);
;             *(v2u*)(dt + (size_t)j * DM) = w; } }
	v_lshlrev_b32_e32 v8, 16, v2
	v_and_b32_e32 v2, 0xffff0000, v2
	v_mul_f32_e32 v2, v135, v2
	v_lshlrev_b32_e32 v9, 16, v3
	v_and_b32_e32 v3, 0xffff0000, v3
	v_mul_f32_e32 v8, v135, v8
	v_rndne_f32_e32 v2, v2
	v_mul_f32_e32 v9, v135, v9
	v_mul_f32_e32 v3, v135, v3
	v_lshlrev_b32_e32 v10, 16, v4
	v_and_b32_e32 v4, 0xffff0000, v4
	v_rndne_f32_e32 v8, v8
	v_cvt_i32_f32_e32 v2, v2
	v_rndne_f32_e32 v9, v9
	v_rndne_f32_e32 v3, v3
	v_mul_f32_e32 v4, v135, v4
	v_lshlrev_b32_e32 v11, 16, v5
	v_and_b32_e32 v5, 0xffff0000, v5
	v_cvt_i32_f32_e32 v8, v8
	v_cvt_i32_f32_sdwa v9, v9 dst_sel:WORD_1 dst_unused:UNUSED_PAD src0_sel:DWORD
	v_cvt_i32_f32_e32 v3, v3
	v_mul_f32_e32 v10, v135, v10
	v_rndne_f32_e32 v4, v4
	v_mul_f32_e32 v11, v135, v11
	v_mul_f32_e32 v5, v135, v5
	v_rndne_f32_e32 v10, v10
	v_cvt_i32_f32_e32 v4, v4
	v_rndne_f32_e32 v11, v11
	v_rndne_f32_e32 v5, v5
	v_cvt_i32_f32_e32 v10, v10
	v_cvt_i32_f32_sdwa v11, v11 dst_sel:WORD_1 dst_unused:UNUSED_PAD src0_sel:DWORD
	v_cvt_i32_f32_e32 v5, v5
	v_lshlrev_b32_e32 v2, 8, v2
	v_and_b32_e32 v2, 0xff00, v2
	v_and_b32_e32 v9, 0xff0000, v9
	v_perm_b32 v3, v3, v8, s81
	v_or3_b32 v2, v3, v2, v9
	v_lshlrev_b32_e32 v3, 8, v4
	v_and_b32_e32 v3, 0xff00, v3
	v_and_b32_e32 v4, 0xff0000, v11
	v_perm_b32 v5, v5, v10, s81
	v_or3_b32 v3, v5, v3, v4
	flat_store_dwordx2 v[6:7], v[2:3]
	ds_read_b128 v[2:5], v96 offset:9216
	s_waitcnt lgkmcnt(0)
	v_lshlrev_b32_e32 v8, 16, v2
	v_and_b32_e32 v2, 0xffff0000, v2
	v_mul_f32_e32 v2, v134, v2
	v_lshlrev_b32_e32 v9, 16, v3
	v_and_b32_e32 v3, 0xffff0000, v3
	v_mul_f32_e32 v8, v134, v8
	v_rndne_f32_e32 v2, v2
	v_mul_f32_e32 v9, v134, v9
	v_mul_f32_e32 v3, v134, v3
	v_lshlrev_b32_e32 v10, 16, v4
	v_and_b32_e32 v4, 0xffff0000, v4
	v_rndne_f32_e32 v8, v8
	v_cvt_i32_f32_e32 v2, v2
	v_rndne_f32_e32 v9, v9
	v_rndne_f32_e32 v3, v3
	v_mul_f32_e32 v4, v134, v4
	v_lshlrev_b32_e32 v11, 16, v5
	v_and_b32_e32 v5, 0xffff0000, v5
	v_cvt_i32_f32_e32 v8, v8
	v_cvt_i32_f32_sdwa v9, v9 dst_sel:WORD_1 dst_unused:UNUSED_PAD src0_sel:DWORD
	v_cvt_i32_f32_e32 v3, v3
	v_mul_f32_e32 v10, v134, v10
	v_rndne_f32_e32 v4, v4
	v_mul_f32_e32 v11, v134, v11
	v_mul_f32_e32 v5, v134, v5
	v_rndne_f32_e32 v10, v10
	v_cvt_i32_f32_e32 v4, v4
	v_rndne_f32_e32 v11, v11
	v_rndne_f32_e32 v5, v5
	v_cvt_i32_f32_e32 v10, v10
	v_cvt_i32_f32_sdwa v11, v11 dst_sel:WORD_1 dst_unused:UNUSED_PAD src0_sel:DWORD
	v_cvt_i32_f32_e32 v5, v5
	v_lshlrev_b32_e32 v2, 8, v2
	v_and_b32_e32 v2, 0xff00, v2
	v_and_b32_e32 v9, 0xff0000, v9
	v_perm_b32 v3, v3, v8, s81
	v_or3_b32 v2, v3, v2, v9
	v_lshlrev_b32_e32 v3, 8, v4
	v_and_b32_e32 v3, 0xff00, v3
	v_and_b32_e32 v4, 0xff0000, v11
	v_perm_b32 v5, v5, v10, s81
	v_or3_b32 v3, v5, v3, v4
	v_add_co_u32_e32 v4, vcc, s67, v6
	s_nop 1
	v_addc_co_u32_e32 v5, vcc, 0, v7, vcc
	flat_store_dwordx2 v[4:5], v[2:3]
	ds_read_b128 v[2:5], v96 offset:10240
	s_waitcnt lgkmcnt(0)
	v_lshlrev_b32_e32 v8, 16, v2
	v_and_b32_e32 v2, 0xffff0000, v2
	v_mul_f32_e32 v2, v131, v2
	v_lshlrev_b32_e32 v9, 16, v3
	v_and_b32_e32 v3, 0xffff0000, v3
	v_mul_f32_e32 v8, v131, v8
	v_rndne_f32_e32 v2, v2
	v_mul_f32_e32 v9, v131, v9
	v_mul_f32_e32 v3, v131, v3
	v_lshlrev_b32_e32 v10, 16, v4
	v_and_b32_e32 v4, 0xffff0000, v4
	v_rndne_f32_e32 v8, v8
	v_cvt_i32_f32_e32 v2, v2
	v_rndne_f32_e32 v9, v9
	v_rndne_f32_e32 v3, v3
	v_mul_f32_e32 v4, v131, v4
	v_lshlrev_b32_e32 v11, 16, v5
	v_and_b32_e32 v5, 0xffff0000, v5
	v_cvt_i32_f32_e32 v8, v8
	v_cvt_i32_f32_sdwa v9, v9 dst_sel:WORD_1 dst_unused:UNUSED_PAD src0_sel:DWORD
	v_cvt_i32_f32_e32 v3, v3
	v_mul_f32_e32 v10, v131, v10
	v_rndne_f32_e32 v4, v4
	v_mul_f32_e32 v11, v131, v11
	v_mul_f32_e32 v5, v131, v5
	v_rndne_f32_e32 v10, v10
	v_cvt_i32_f32_e32 v4, v4
	v_rndne_f32_e32 v11, v11
	v_rndne_f32_e32 v5, v5
	v_cvt_i32_f32_e32 v10, v10
	v_cvt_i32_f32_sdwa v11, v11 dst_sel:WORD_1 dst_unused:UNUSED_PAD src0_sel:DWORD
	v_cvt_i32_f32_e32 v5, v5
	v_lshlrev_b32_e32 v2, 8, v2
	v_and_b32_e32 v2, 0xff00, v2
	v_and_b32_e32 v9, 0xff0000, v9
	v_perm_b32 v3, v3, v8, s81
	v_or3_b32 v2, v3, v2, v9
	v_lshlrev_b32_e32 v3, 8, v4
	v_and_b32_e32 v3, 0xff00, v3
	v_and_b32_e32 v4, 0xff0000, v11
	v_perm_b32 v5, v5, v10, s81
	v_or3_b32 v3, v5, v3, v4
	v_add_co_u32_e32 v4, vcc, s33, v6
	s_nop 1
	v_addc_co_u32_e32 v5, vcc, 0, v7, vcc
	flat_store_dwordx2 v[4:5], v[2:3]
	ds_read_b128 v[2:5], v96 offset:11264
	s_waitcnt lgkmcnt(0)
	v_lshlrev_b32_e32 v8, 16, v2
	v_and_b32_e32 v2, 0xffff0000, v2
	v_mul_f32_e32 v2, v130, v2
	v_lshlrev_b32_e32 v9, 16, v3
	v_and_b32_e32 v3, 0xffff0000, v3
	v_mul_f32_e32 v8, v130, v8
	v_rndne_f32_e32 v2, v2
	v_mul_f32_e32 v9, v130, v9
	v_mul_f32_e32 v3, v130, v3
	v_lshlrev_b32_e32 v10, 16, v4
	v_and_b32_e32 v4, 0xffff0000, v4
	v_rndne_f32_e32 v8, v8
	v_cvt_i32_f32_e32 v2, v2
	v_rndne_f32_e32 v9, v9
	v_rndne_f32_e32 v3, v3
	v_mul_f32_e32 v4, v130, v4
	v_lshlrev_b32_e32 v11, 16, v5
	v_and_b32_e32 v5, 0xffff0000, v5
	v_cvt_i32_f32_e32 v8, v8
	v_cvt_i32_f32_sdwa v9, v9 dst_sel:WORD_1 dst_unused:UNUSED_PAD src0_sel:DWORD
	v_cvt_i32_f32_e32 v3, v3
	v_mul_f32_e32 v10, v130, v10
	v_rndne_f32_e32 v4, v4
	v_mul_f32_e32 v11, v130, v11
	v_mul_f32_e32 v5, v130, v5
	v_rndne_f32_e32 v10, v10
	v_cvt_i32_f32_e32 v4, v4
	v_rndne_f32_e32 v11, v11
	v_rndne_f32_e32 v5, v5
	v_cvt_i32_f32_e32 v10, v10
	v_cvt_i32_f32_sdwa v11, v11 dst_sel:WORD_1 dst_unused:UNUSED_PAD src0_sel:DWORD
	v_cvt_i32_f32_e32 v5, v5
	v_lshlrev_b32_e32 v2, 8, v2
	v_and_b32_e32 v2, 0xff00, v2
	v_and_b32_e32 v9, 0xff0000, v9
	v_perm_b32 v3, v3, v8, s81
	v_or3_b32 v2, v3, v2, v9
	v_lshlrev_b32_e32 v3, 8, v4
	v_and_b32_e32 v3, 0xff00, v3
	v_and_b32_e32 v4, 0xff0000, v11
	v_perm_b32 v5, v5, v10, s81
	v_or3_b32 v3, v5, v3, v4
	v_add_co_u32_e32 v4, vcc, s44, v6
	s_nop 1
	v_addc_co_u32_e32 v5, vcc, 0, v7, vcc
	flat_store_dwordx2 v[4:5], v[2:3]
	v_lshl_add_u64 v[4:5], v[0:1], 0, s[4:5]
	ds_read_b128 v[0:3], v96 offset:12288
	s_waitcnt lgkmcnt(0)
; #define LAS __attribute__((address_space(3)))
; __device__ __forceinline__ float bflo(unsigned w) { return __uint_as_float(w << 16); }
; __device__ __forceinline__ float bfhi(unsigned w) { return __uint_as_float(w & 0xffff0000u); }
; __device__ __forceinline__ void direct_w8_block(const Ctx& c, LAS unsigned char* lds, const float* Wsrc, const int INC_, int srccol, unsigned char* dstrow, float* swdst) {
;     ...
; #pragma unroll
;     for (int t = 0; t < 8; ++t) { unsigned char* dt = dst + t * 64; asm volatile("" : "+v"(dt));
; #pragma unroll
;         for (int j = 0; j < 4; ++j) { v4u pk;
;             if (t < 4) { pk.x = held[t & 3][j][0]; pk.y = held[t & 3][j][1]; pk.z = held[t & 3][j][2]; pk.w = held[t & 3][j][3]; }
;             else pk = *(const LAS v4u*)(hl + ((t - 4) * 4 + j) * 1024);
;             int qi[8];
; #pragma unroll
;             for (int pr = 0; pr < 4; ++pr) { qi[2 * pr] = __float2int_rn(bflo(pk[pr]) * inv[j]); qi[2 * pr + 1] = __float2int_rn(bfhi(pk[pr]) * inv[j]); }
;             v2u w; w.x = (unsigned)(qi[0] & 255) | ((unsigned)(qi[1] & 255) << 8) | ((unsigned)(qi[2] & 255) << 16) | ((unsigned)(qi[3] & 255) << 24);
;             w.y = (unsigned)(qi[4] & 255) | ((unsigned)(qi[5] & 255) << 8) | ((unsigned)(qi[6] & 255) << 16) | ((unsigned)(qi[7] & 255) << 24);
;             *(v2u*)(dt + (size_t)j * DM) = w; } }
	v_lshlrev_b32_e32 v6, 16, v0
	v_and_b32_e32 v0, 0xffff0000, v0
	v_mul_f32_e32 v0, v135, v0
	v_lshlrev_b32_e32 v7, 16, v1
	v_and_b32_e32 v1, 0xffff0000, v1
	v_mul_f32_e32 v6, v135, v6
	v_rndne_f32_e32 v0, v0
	v_mul_f32_e32 v7, v135, v7
	v_mul_f32_e32 v1, v135, v1
	v_lshlrev_b32_e32 v8, 16, v2
	v_and_b32_e32 v2, 0xffff0000, v2
	v_rndne_f32_e32 v6, v6
	v_cvt_i32_f32_e32 v0, v0
	v_rndne_f32_e32 v7, v7
	v_rndne_f32_e32 v1, v1
	v_mul_f32_e32 v2, v135, v2
	v_lshlrev_b32_e32 v9, 16, v3
	v_and_b32_e32 v3, 0xffff0000, v3
	v_cvt_i32_f32_e32 v6, v6
	v_cvt_i32_f32_sdwa v7, v7 dst_sel:WORD_1 dst_unused:UNUSED_PAD src0_sel:DWORD
	v_cvt_i32_f32_e32 v1, v1
	v_mul_f32_e32 v8, v135, v8
	v_rndne_f32_e32 v2, v2
	v_mul_f32_e32 v9, v135, v9
	v_mul_f32_e32 v3, v135, v3
	v_rndne_f32_e32 v8, v8
	v_cvt_i32_f32_e32 v2, v2
	v_rndne_f32_e32 v9, v9
	v_rndne_f32_e32 v3, v3
	v_cvt_i32_f32_e32 v8, v8
	v_cvt_i32_f32_sdwa v9, v9 dst_sel:WORD_1 dst_unused:UNUSED_PAD src0_sel:DWORD
	v_cvt_i32_f32_e32 v3, v3
	v_lshlrev_b32_e32 v0, 8, v0
	v_and_b32_e32 v0, 0xff00, v0
	v_and_b32_e32 v7, 0xff0000, v7
	v_perm_b32 v1, v1, v6, s81
	v_or3_b32 v0, v1, v0, v7
	v_lshlrev_b32_e32 v1, 8, v2
	v_and_b32_e32 v1, 0xff00, v1
	v_and_b32_e32 v2, 0xff0000, v9
	v_perm_b32 v3, v3, v8, s81
	v_or3_b32 v1, v3, v1, v2
	flat_store_dwordx2 v[4:5], v[0:1]
	ds_read_b128 v[0:3], v96 offset:13312
	s_waitcnt lgkmcnt(0)
	v_lshlrev_b32_e32 v6, 16, v0
	v_and_b32_e32 v0, 0xffff0000, v0
	v_mul_f32_e32 v0, v134, v0
	v_lshlrev_b32_e32 v7, 16, v1
	v_and_b32_e32 v1, 0xffff0000, v1
	v_mul_f32_e32 v6, v134, v6
	v_rndne_f32_e32 v0, v0
	v_mul_f32_e32 v7, v134, v7
	v_mul_f32_e32 v1, v134, v1
	v_lshlrev_b32_e32 v8, 16, v2
	v_and_b32_e32 v2, 0xffff0000, v2
	v_rndne_f32_e32 v6, v6
	v_cvt_i32_f32_e32 v0, v0
	v_rndne_f32_e32 v7, v7
	v_rndne_f32_e32 v1, v1
	v_mul_f32_e32 v2, v134, v2
	v_lshlrev_b32_e32 v9, 16, v3
	v_and_b32_e32 v3, 0xffff0000, v3
	v_cvt_i32_f32_e32 v6, v6
	v_cvt_i32_f32_sdwa v7, v7 dst_sel:WORD_1 dst_unused:UNUSED_PAD src0_sel:DWORD
	v_cvt_i32_f32_e32 v1, v1
	v_mul_f32_e32 v8, v134, v8
	v_rndne_f32_e32 v2, v2
	v_mul_f32_e32 v9, v134, v9
	v_mul_f32_e32 v3, v134, v3
	v_rndne_f32_e32 v8, v8
	v_cvt_i32_f32_e32 v2, v2
	v_rndne_f32_e32 v9, v9
	v_rndne_f32_e32 v3, v3
	v_cvt_i32_f32_e32 v8, v8
	v_cvt_i32_f32_sdwa v9, v9 dst_sel:WORD_1 dst_unused:UNUSED_PAD src0_sel:DWORD
	v_cvt_i32_f32_e32 v3, v3
	v_lshlrev_b32_e32 v0, 8, v0
	v_and_b32_e32 v0, 0xff00, v0
	v_and_b32_e32 v7, 0xff0000, v7
	v_perm_b32 v1, v1, v6, s81
	v_or3_b32 v0, v1, v0, v7
	v_lshlrev_b32_e32 v1, 8, v2
	v_and_b32_e32 v1, 0xff00, v1
	v_and_b32_e32 v2, 0xff0000, v9
	v_perm_b32 v3, v3, v8, s81
	v_or3_b32 v1, v3, v1, v2
	v_add_co_u32_e32 v2, vcc, s67, v4
	s_nop 1
	v_addc_co_u32_e32 v3, vcc, 0, v5, vcc
	flat_store_dwordx2 v[2:3], v[0:1]
	ds_read_b128 v[0:3], v96 offset:14336
	s_waitcnt lgkmcnt(0)
	v_lshlrev_b32_e32 v6, 16, v0
	v_and_b32_e32 v0, 0xffff0000, v0
	v_mul_f32_e32 v0, v131, v0
	v_lshlrev_b32_e32 v7, 16, v1
	v_and_b32_e32 v1, 0xffff0000, v1
	v_mul_f32_e32 v6, v131, v6
	v_rndne_f32_e32 v0, v0
	v_mul_f32_e32 v7, v131, v7
	v_mul_f32_e32 v1, v131, v1
	v_lshlrev_b32_e32 v8, 16, v2
	v_and_b32_e32 v2, 0xffff0000, v2
	v_rndne_f32_e32 v6, v6
	v_cvt_i32_f32_e32 v0, v0
	v_rndne_f32_e32 v7, v7
	v_rndne_f32_e32 v1, v1
	v_mul_f32_e32 v2, v131, v2
	v_lshlrev_b32_e32 v9, 16, v3
	v_and_b32_e32 v3, 0xffff0000, v3
	v_cvt_i32_f32_e32 v6, v6
	v_cvt_i32_f32_sdwa v7, v7 dst_sel:WORD_1 dst_unused:UNUSED_PAD src0_sel:DWORD
	v_cvt_i32_f32_e32 v1, v1
	v_mul_f32_e32 v8, v131, v8
	v_rndne_f32_e32 v2, v2
	v_mul_f32_e32 v9, v131, v9
	v_mul_f32_e32 v3, v131, v3
	v_rndne_f32_e32 v8, v8
	v_cvt_i32_f32_e32 v2, v2
	v_rndne_f32_e32 v9, v9
	v_rndne_f32_e32 v3, v3
	v_cvt_i32_f32_e32 v8, v8
	v_cvt_i32_f32_sdwa v9, v9 dst_sel:WORD_1 dst_unused:UNUSED_PAD src0_sel:DWORD
	v_cvt_i32_f32_e32 v3, v3
	v_lshlrev_b32_e32 v0, 8, v0
	v_and_b32_e32 v0, 0xff00, v0
	v_and_b32_e32 v7, 0xff0000, v7
	v_perm_b32 v1, v1, v6, s81
	v_or3_b32 v0, v1, v0, v7
	v_lshlrev_b32_e32 v1, 8, v2
	v_and_b32_e32 v1, 0xff00, v1
	v_and_b32_e32 v2, 0xff0000, v9
	v_perm_b32 v3, v3, v8, s81
	v_or3_b32 v1, v3, v1, v2
	v_add_co_u32_e32 v2, vcc, s33, v4
	s_nop 1
	v_addc_co_u32_e32 v3, vcc, 0, v5, vcc
	flat_store_dwordx2 v[2:3], v[0:1]
	ds_read_b128 v[0:3], v96 offset:15360
	s_waitcnt lgkmcnt(0)
	v_lshlrev_b32_e32 v6, 16, v0
	v_and_b32_e32 v0, 0xffff0000, v0
	v_mul_f32_e32 v0, v130, v0
	v_lshlrev_b32_e32 v7, 16, v1
	v_and_b32_e32 v1, 0xffff0000, v1
	v_mul_f32_e32 v6, v130, v6
	v_rndne_f32_e32 v0, v0
	v_mul_f32_e32 v7, v130, v7
	v_mul_f32_e32 v1, v130, v1
	v_lshlrev_b32_e32 v8, 16, v2
	v_and_b32_e32 v2, 0xffff0000, v2
	v_rndne_f32_e32 v6, v6
	v_cvt_i32_f32_e32 v0, v0
	v_rndne_f32_e32 v7, v7
	v_rndne_f32_e32 v1, v1
	v_mul_f32_e32 v2, v130, v2
	v_lshlrev_b32_e32 v9, 16, v3
	v_and_b32_e32 v3, 0xffff0000, v3
	v_cvt_i32_f32_e32 v6, v6
	v_cvt_i32_f32_sdwa v7, v7 dst_sel:WORD_1 dst_unused:UNUSED_PAD src0_sel:DWORD
	v_cvt_i32_f32_e32 v1, v1
	v_mul_f32_e32 v8, v130, v8
	v_rndne_f32_e32 v2, v2
	v_mul_f32_e32 v9, v130, v9
	v_mul_f32_e32 v3, v130, v3
	v_rndne_f32_e32 v8, v8
	v_cvt_i32_f32_e32 v2, v2
	v_rndne_f32_e32 v9, v9
	v_rndne_f32_e32 v3, v3
	v_cvt_i32_f32_e32 v8, v8
	v_cvt_i32_f32_sdwa v9, v9 dst_sel:WORD_1 dst_unused:UNUSED_PAD src0_sel:DWORD
	v_cvt_i32_f32_e32 v3, v3
	v_lshlrev_b32_e32 v0, 8, v0
	v_and_b32_e32 v0, 0xff00, v0
	v_and_b32_e32 v7, 0xff0000, v7
	v_perm_b32 v1, v1, v6, s81
	v_or3_b32 v0, v1, v0, v7
	v_lshlrev_b32_e32 v1, 8, v2
	v_and_b32_e32 v1, 0xff00, v1
	v_and_b32_e32 v2, 0xff0000, v9
	v_perm_b32 v3, v3, v8, s81
	v_or3_b32 v1, v3, v1, v2
	v_add_co_u32_e32 v2, vcc, 0x3000, v4
	s_nop 1
	v_addc_co_u32_e32 v3, vcc, 0, v5, vcc
	flat_store_dwordx2 v[2:3], v[0:1]
	s_cbranch_scc0 .LBB0_790
; #define LAS __attribute__((address_space(3)))
; __device__ __forceinline__ unsigned pk2(float lo, float hi) { return pg8::cvt_pk_bf16(lo, hi); }
; __device__ __forceinline__ void direct_w8_block(const Ctx& c, LAS unsigned char* lds, const float* Wsrc, const int INC_, int srccol, unsigned char* dstrow, float* swdst) {
;     ...
;     for (int t = 0; t < 8; ++t) { f32x4 v[8]; const float* Wt = W + (size_t)(t * 64) * INC_; asm volatile("" : "+v"(Wt));
; #pragma unroll
;         for (int e = 0; e < 8; ++e) v[e] = __builtin_nontemporal_load((const f32x4*)(Wt + (size_t)e * INC_));
; #pragma unroll
;         for (int j = 0; j < 4; ++j) {
; #pragma unroll
;             for (int e = 0; e < 8; ++e) mx[j] = fmaxf(mx[j], fabsf(v[e][j]));
;             v4u pk; pk.x = pk2(v[0][j], v[1][j]); pk.y = pk2(v[2][j], v[3][j]); pk.z = pk2(v[4][j], v[5][j]); pk.w = pk2(v[6][j], v[7][j]);
;             if (t < 4) { held[t & 3][j][0] = pk.x; held[t & 3][j][1] = pk.y; held[t & 3][j][2] = pk.z; held[t & 3][j][3] = pk.w; }
;             else *(LAS v4u*)(hl + ((t - 4) * 4 + j) * 1024) = pk; }
; __device__ __forceinline__ void phase_tail_transposes(LAS unsigned char* lds, int part, int wv) {
;     ...
;         for (int k = (idx + rot) % nidle; k < NB1 - NT0; k += nidle) direct_win_block(c, lds, 1, NT0 + k); }
.LBB0_786:
	s_add_i32 s4, s12, 0xffffe400
	s_cmpk_lt_i32 s3, 0x1a0
	s_cbranch_scc1 .Lt1w_skip
	s_add_i32 s4, s4, 0xffffc400
	s_mov_b32 s12, s4
.Lt1w_skip:
	s_cmp_lt_i32 s3, 32
	s_cselect_b32 s8, s4, s12
	s_ashr_i32 s9, s8, 31
	v_lshl_add_u64 v[130:131], s[8:9], 2, v[166:167]
	v_mov_b64_e32 v[24:25], v[130:131]
	s_mov_b64 s[8:9], 0x600000
	v_add_co_u32_e32 v4, vcc, 0x18000, v24
	v_lshl_add_u64 v[56:57], v[130:131], 0, s[8:9]
	s_nop 0
	v_addc_co_u32_e32 v5, vcc, 0, v25, vcc
	v_add_co_u32_e32 v8, vcc, 0x30000, v24
	flat_load_dwordx4 v[0:3], v[24:25] nt
	s_nop 0
	flat_load_dwordx4 v[4:7], v[4:5] nt
	v_addc_co_u32_e32 v9, vcc, 0, v25, vcc
	s_waitcnt vmcnt(0)
	v_add_co_u32_e32 v12, vcc, 0x48000, v24
	s_mov_b32 s2, 0x78000
	s_nop 0
	v_addc_co_u32_e32 v13, vcc, 0, v25, vcc
	v_add_co_u32_e32 v16, vcc, 0x60000, v24
	flat_load_dwordx4 v[8:11], v[8:9] nt
	s_nop 0
	flat_load_dwordx4 v[12:15], v[12:13] nt
	v_addc_co_u32_e32 v17, vcc, 0, v25, vcc
	v_add_co_u32_e32 v20, vcc, 0x78000, v24
	s_mov_b32 s5, 0xa8000
	s_nop 0
	v_addc_co_u32_e32 v21, vcc, 0, v25, vcc
	v_add_co_u32_e32 v26, vcc, 0x90000, v24
	flat_load_dwordx4 v[16:19], v[16:17] nt
	s_nop 0
	flat_load_dwordx4 v[20:23], v[20:21] nt
	v_addc_co_u32_e32 v27, vcc, 0, v25, vcc
	v_add_co_u32_e32 v28, vcc, 0xa8000, v24
	s_mov_b64 s[8:9], 0xc00000
	s_nop 0
	v_addc_co_u32_e32 v29, vcc, 0, v25, vcc
	flat_load_dwordx4 v[24:27], v[26:27] nt
	s_nop 0
	flat_load_dwordx4 v[28:31], v[28:29] nt
	v_lshl_add_u64 v[88:89], v[130:131], 0, s[8:9]
	v_add_co_u32_e32 v36, vcc, s61, v56
	s_mov_b64 s[8:9], 0x1200000
	s_nop 0
	v_addc_co_u32_e32 v37, vcc, 0, v57, vcc
	v_add_co_u32_e32 v40, vcc, s25, v56
	flat_load_dwordx4 v[32:35], v[56:57] nt
	s_nop 0
	flat_load_dwordx4 v[36:39], v[36:37] nt
	v_addc_co_u32_e32 v41, vcc, 0, v57, vcc
	v_add_co_u32_e32 v44, vcc, s73, v56
	v_lshl_add_u64 v[122:123], v[130:131], 0, s[8:9]
	s_nop 0
	v_addc_co_u32_e32 v45, vcc, 0, v57, vcc
	v_add_co_u32_e32 v48, vcc, s94, v56
	flat_load_dwordx4 v[40:43], v[40:41] nt
	s_nop 0
	flat_load_dwordx4 v[44:47], v[44:45] nt
	v_addc_co_u32_e32 v49, vcc, 0, v57, vcc
	v_add_co_u32_e32 v52, vcc, s2, v56
	s_waitcnt lgkmcnt(0)
	v_max3_f32 v132, |v1|, 0, |v5|
	v_addc_co_u32_e32 v53, vcc, 0, v57, vcc
	v_add_co_u32_e32 v58, vcc, s95, v56
	flat_load_dwordx4 v[48:51], v[48:49] nt
	s_nop 0
	flat_load_dwordx4 v[52:55], v[52:53] nt
	v_addc_co_u32_e32 v59, vcc, 0, v57, vcc
	v_add_co_u32_e32 v60, vcc, s5, v56
	s_waitcnt vmcnt(0)
	v_max3_f32 v132, v132, |v9|, |v13|
	v_addc_co_u32_e32 v61, vcc, 0, v57, vcc
	flat_load_dwordx4 v[56:59], v[58:59] nt
	s_nop 0
	flat_load_dwordx4 v[60:63], v[60:61] nt
	v_max3_f32 v133, |v2|, 0, |v6|
	v_add_co_u32_e32 v68, vcc, s61, v88
	v_max3_f32 v133, v133, |v10|, |v14|
	s_nop 0
	v_addc_co_u32_e32 v69, vcc, 0, v89, vcc
	v_add_co_u32_e32 v72, vcc, s25, v88
	flat_load_dwordx4 v[64:67], v[88:89] nt
	s_nop 0
	flat_load_dwordx4 v[68:71], v[68:69] nt
	v_addc_co_u32_e32 v73, vcc, 0, v89, vcc
	v_add_co_u32_e32 v76, vcc, s73, v88
	v_max3_f32 v132, v132, |v17|, |v21|
	s_nop 0
	v_addc_co_u32_e32 v77, vcc, 0, v89, vcc
	v_add_co_u32_e32 v80, vcc, s94, v88
	flat_load_dwordx4 v[72:75], v[72:73] nt
	s_nop 0
	flat_load_dwordx4 v[76:79], v[76:77] nt
	v_addc_co_u32_e32 v81, vcc, 0, v89, vcc
	v_add_co_u32_e32 v84, vcc, s2, v88
	v_max3_f32 v132, v132, |v25|, |v29|
	s_nop 0
	v_addc_co_u32_e32 v85, vcc, 0, v89, vcc
	v_add_co_u32_e32 v90, vcc, s95, v88
	flat_load_dwordx4 v[80:83], v[80:81] nt
	s_nop 0
	flat_load_dwordx4 v[84:87], v[84:85] nt
	v_addc_co_u32_e32 v91, vcc, 0, v89, vcc
	v_add_co_u32_e32 v92, vcc, s5, v88
	v_max3_f32 v132, v132, |v33|, |v37|
	s_nop 0
	v_addc_co_u32_e32 v93, vcc, 0, v89, vcc
	flat_load_dwordx4 v[88:91], v[90:91] nt
	s_nop 0
	flat_load_dwordx4 v[92:95], v[92:93] nt
	v_max3_f32 v96, |v0|, 0, |v4|
	v_add_co_u32_e32 v102, vcc, s61, v122
	v_max3_f32 v133, v133, |v18|, |v22|
	s_nop 0
	v_addc_co_u32_e32 v103, vcc, 0, v123, vcc
	v_add_co_u32_e32 v106, vcc, s25, v122
	flat_load_dwordx4 v[98:101], v[122:123] nt
	s_nop 0
	flat_load_dwordx4 v[102:105], v[102:103] nt
	v_addc_co_u32_e32 v107, vcc, 0, v123, vcc
	v_add_co_u32_e32 v110, vcc, s73, v122
	v_max3_f32 v132, v132, |v41|, |v45|
	s_nop 0
	v_addc_co_u32_e32 v111, vcc, 0, v123, vcc
	v_add_co_u32_e32 v114, vcc, s94, v122
	flat_load_dwordx4 v[106:109], v[106:107] nt
	s_nop 0
	flat_load_dwordx4 v[110:113], v[110:111] nt
	v_addc_co_u32_e32 v115, vcc, 0, v123, vcc
	v_add_co_u32_e32 v118, vcc, s2, v122
	v_max3_f32 v96, v96, |v8|, |v12|
	s_nop 0
	v_addc_co_u32_e32 v119, vcc, 0, v123, vcc
	v_add_co_u32_e32 v124, vcc, s95, v122
	flat_load_dwordx4 v[114:117], v[114:115] nt
	s_nop 0
	flat_load_dwordx4 v[118:121], v[118:119] nt
	v_addc_co_u32_e32 v125, vcc, 0, v123, vcc
	v_add_co_u32_e32 v126, vcc, s5, v122
	v_max3_f32 v133, v133, |v26|, |v30|
	s_nop 0
	v_addc_co_u32_e32 v127, vcc, 0, v123, vcc
	flat_load_dwordx4 v[122:125], v[124:125] nt
	s_nop 0
	flat_load_dwordx4 v[126:129], v[126:127] nt
	v_max3_f32 v134, |v3|, 0, |v7|
	s_waitcnt lgkmcnt(0)
	v_max3_f32 v132, v132, |v49|, |v53|
	v_max3_f32 v96, v96, |v16|, |v20|
	v_max3_f32 v134, v134, |v11|, |v15|
	s_waitcnt vmcnt(0)
; #define LAS __attribute__((address_space(3)))
; __device__ __forceinline__ unsigned pk2(float lo, float hi) { return pg8::cvt_pk_bf16(lo, hi); }
; __device__ __forceinline__ void direct_w8_block(const Ctx& c, LAS unsigned char* lds, const float* Wsrc, const int INC_, int srccol, unsigned char* dstrow, float* swdst) {
;     ...
;     for (int t = 0; t < 8; ++t) { f32x4 v[8]; const float* Wt = W + (size_t)(t * 64) * INC_; asm volatile("" : "+v"(Wt));
; #pragma unroll
;         for (int e = 0; e < 8; ++e) v[e] = __builtin_nontemporal_load((const f32x4*)(Wt + (size_t)e * INC_));
; #pragma unroll
;         for (int j = 0; j < 4; ++j) {
; #pragma unroll
;             for (int e = 0; e < 8; ++e) mx[j] = fmaxf(mx[j], fabsf(v[e][j]));
;             v4u pk; pk.x = pk2(v[0][j], v[1][j]); pk.y = pk2(v[2][j], v[3][j]); pk.z = pk2(v[4][j], v[5][j]); pk.w = pk2(v[6][j], v[7][j]);
;             if (t < 4) { held[t & 3][j][0] = pk.x; held[t & 3][j][1] = pk.y; held[t & 3][j][2] = pk.z; held[t & 3][j][3] = pk.w; }
;             else *(LAS v4u*)(hl + ((t - 4) * 4 + j) * 1024) = pk; }
;         if ((t & 3) == 3) { asm volatile("" ::: "memory"); __builtin_amdgcn_sched_barrier(0); } }
	v_max3_f32 v132, v132, |v57|, |v61|
	v_max3_f32 v133, v133, |v34|, |v38|
	v_max3_f32 v96, v96, |v24|, |v28|
	v_max3_f32 v134, v134, |v19|, |v23|
	v_max3_f32 v133, v133, |v42|, |v46|
	v_max3_f32 v134, v134, |v27|, |v31|
	v_max3_f32 v96, v96, |v32|, |v36|
	v_max3_f32 v133, v133, |v50|, |v54|
	v_max3_f32 v96, v96, |v40|, |v44|
	v_max3_f32 v132, v132, |v65|, |v69|
	v_max3_f32 v133, v133, |v58|, |v62|
	v_max3_f32 v134, v134, |v35|, |v39|
	v_max3_f32 v96, v96, |v48|, |v52|
	v_max3_f32 v134, v134, |v43|, |v47|
	v_max3_f32 v133, v133, |v66|, |v70|
	v_max3_f32 v96, v96, |v56|, |v60|
	v_max3_f32 v134, v134, |v51|, |v55|
	v_max3_f32 v134, v134, |v59|, |v63|
	v_max3_f32 v96, v96, |v64|, |v68|
	v_max3_f32 v132, v132, |v73|, |v77|
	v_max3_f32 v133, v133, |v74|, |v78|
	v_max3_f32 v96, v96, |v72|, |v76|
	v_max3_f32 v134, v134, |v67|, |v71|
	v_max3_f32 v134, v134, |v75|, |v79|
	v_max3_f32 v132, v132, |v81|, |v85|
	v_max3_f32 v133, v133, |v82|, |v86|
	v_max3_f32 v96, v96, |v80|, |v84|
	v_max3_f32 v134, v134, |v83|, |v87|
	v_max3_f32 v132, v132, |v89|, |v93|
	v_max3_f32 v133, v133, |v90|, |v94|
	v_max3_f32 v96, v96, |v88|, |v92|
	v_max3_f32 v134, v134, |v91|, |v95|
	v_max3_f32 v132, v132, |v99|, |v103|
	v_max3_f32 v96, v96, |v98|, |v102|
	v_max3_f32 v132, v132, |v107|, |v111|
	v_max3_f32 v96, v96, |v106|, |v110|
	v_max3_f32 v132, v132, |v115|, |v119|
	v_max3_f32 v96, v96, |v114|, |v118|
	v_max3_f32 v171, v132, |v123|, |v127|
	v_max3_f32 v132, v133, |v100|, |v104|
	v_max3_f32 v132, v132, |v108|, |v112|
	v_max3_f32 v132, v132, |v116|, |v120|
	v_max3_f32 v180, v132, |v124|, |v128|
	v_max3_f32 v132, v134, |v101|, |v105|
	v_max3_f32 v132, v132, |v109|, |v113|
	v_max3_f32 v96, v96, |v122|, |v126|
	v_max3_f32 v132, v132, |v117|, |v121|
	v_max3_f32 v181, v132, |v125|, |v129|
	s_mov_b64 s[8:9], 0x1800000
	v_lshl_add_u64 v[160:161], v[130:131], 0, s[8:9]
	flat_load_dwordx4 v[132:135], v[160:161] nt
	v_add_co_u32_e32 v136, vcc, s61, v160
	s_mov_b64 s[8:9], 0x1e00000
	s_nop 0
	v_addc_co_u32_e32 v137, vcc, 0, v161, vcc
	v_add_co_u32_e32 v140, vcc, s25, v160
	flat_load_dwordx4 v[136:139], v[136:137] nt
	s_nop 0
	v_addc_co_u32_e32 v141, vcc, 0, v161, vcc
	v_add_co_u32_e32 v144, vcc, s73, v160
	flat_load_dwordx4 v[140:143], v[140:141] nt
	s_nop 0
	v_addc_co_u32_e32 v145, vcc, 0, v161, vcc
	v_add_co_u32_e32 v148, vcc, s94, v160
	flat_load_dwordx4 v[144:147], v[144:145] nt
	s_nop 0
	v_addc_co_u32_e32 v149, vcc, 0, v161, vcc
	v_add_co_u32_e32 v152, vcc, s2, v160
	flat_load_dwordx4 v[148:151], v[148:149] nt
	s_nop 0
	v_addc_co_u32_e32 v153, vcc, 0, v161, vcc
	v_add_co_u32_e32 v156, vcc, s95, v160
	flat_load_dwordx4 v[152:155], v[152:153] nt
	s_nop 0
	v_addc_co_u32_e32 v157, vcc, 0, v161, vcc
	v_add_co_u32_e32 v160, vcc, s5, v160
	flat_load_dwordx4 v[156:159], v[156:157] nt
	s_nop 0
	v_addc_co_u32_e32 v161, vcc, 0, v161, vcc
	flat_load_dwordx4 v[172:175], v[160:161] nt
	v_lshl_add_u64 v[160:161], v[130:131], 0, s[8:9]
	s_mov_b64 s[8:9], 0x2400000
	s_waitcnt vmcnt(0) lgkmcnt(0)
	v_max3_f32 v96, v96, |v132|, |v136|
	v_cvt_pk_bf16_f32 v176, v132, v136
	v_max3_f32 v132, v171, |v133|, |v137|
	v_max3_f32 v132, v132, |v141|, |v145|
	v_max3_f32 v96, v96, |v140|, |v144|
	v_cvt_pk_bf16_f32 v177, v140, v144
	v_max3_f32 v132, v132, |v149|, |v153|
	v_max3_f32 v96, v96, |v148|, |v152|
	v_cvt_pk_bf16_f32 v178, v148, v152
	v_cvt_pk_bf16_f32 v144, v151, v155
	v_max3_f32 v171, v132, |v157|, |v173|
	v_max3_f32 v132, v180, |v134|, |v138|
	v_max3_f32 v132, v132, |v142|, |v146|
	v_max3_f32 v182, v96, |v156|, |v172|
	v_cvt_pk_bf16_f32 v179, v156, v172
	v_add_u32_e32 v96, s52, v162
	v_max3_f32 v132, v132, |v150|, |v154|
	ds_write_b128 v96, v[176:179]
	v_cvt_pk_bf16_f32 v179, v157, v173
	v_cvt_pk_bf16_f32 v178, v149, v153
	v_cvt_pk_bf16_f32 v177, v141, v145
	v_cvt_pk_bf16_f32 v176, v133, v137
	v_max3_f32 v180, v132, |v158|, |v174|
	v_max3_f32 v132, v181, |v135|, |v139|
	ds_write_b128 v96, v[176:179] offset:1024
	v_cvt_pk_bf16_f32 v179, v158, v174
	v_cvt_pk_bf16_f32 v178, v150, v154
	v_cvt_pk_bf16_f32 v177, v142, v146
	v_cvt_pk_bf16_f32 v176, v134, v138
	v_max3_f32 v132, v132, |v143|, |v147|
	v_cvt_pk_bf16_f32 v145, v159, v175
	v_cvt_pk_bf16_f32 v143, v143, v147
	v_cvt_pk_bf16_f32 v142, v135, v139
	ds_write_b128 v96, v[176:179] offset:2048
	ds_write_b128 v96, v[142:145] offset:3072
	v_max3_f32 v132, v132, |v151|, |v155|
	v_add_co_u32_e32 v136, vcc, s61, v160
	v_max3_f32 v181, v132, |v159|, |v175|
	s_nop 0
	v_addc_co_u32_e32 v137, vcc, 0, v161, vcc
	v_add_co_u32_e32 v140, vcc, s25, v160
	flat_load_dwordx4 v[132:135], v[160:161] nt
	s_nop 0
	v_addc_co_u32_e32 v141, vcc, 0, v161, vcc
	v_add_co_u32_e32 v144, vcc, s73, v160
	flat_load_dwordx4 v[136:139], v[136:137] nt
	s_nop 0
	v_addc_co_u32_e32 v145, vcc, 0, v161, vcc
	v_add_co_u32_e32 v148, vcc, s94, v160
	flat_load_dwordx4 v[140:143], v[140:141] nt
	s_nop 0
	v_addc_co_u32_e32 v149, vcc, 0, v161, vcc
	v_add_co_u32_e32 v152, vcc, s2, v160
	flat_load_dwordx4 v[144:147], v[144:145] nt
	s_nop 0
	v_addc_co_u32_e32 v153, vcc, 0, v161, vcc
	v_add_co_u32_e32 v156, vcc, s95, v160
	flat_load_dwordx4 v[148:151], v[148:149] nt
	s_nop 0
	v_addc_co_u32_e32 v157, vcc, 0, v161, vcc
	v_add_co_u32_e32 v160, vcc, s5, v160
	flat_load_dwordx4 v[152:155], v[152:153] nt
	s_nop 0
	v_addc_co_u32_e32 v161, vcc, 0, v161, vcc
	flat_load_dwordx4 v[156:159], v[156:157] nt
	s_waitcnt vmcnt(0) lgkmcnt(0)
	v_cvt_pk_bf16_f32 v176, v132, v136
	flat_load_dwordx4 v[172:175], v[160:161] nt
	v_max3_f32 v160, v182, |v132|, |v136|
	v_max3_f32 v132, v171, |v133|, |v137|
	v_max3_f32 v132, v132, |v141|, |v145|
	v_max3_f32 v160, v160, |v140|, |v144|
	v_cvt_pk_bf16_f32 v177, v140, v144
	v_max3_f32 v132, v132, |v149|, |v153|
	v_max3_f32 v160, v160, |v148|, |v152|
	v_cvt_pk_bf16_f32 v178, v148, v152
	v_cvt_pk_bf16_f32 v144, v151, v155
	s_waitcnt vmcnt(0) lgkmcnt(0)
; #define LAS __attribute__((address_space(3)))
; __device__ __forceinline__ unsigned pk2(float lo, float hi) { return pg8::cvt_pk_bf16(lo, hi); }
; __device__ __forceinline__ void direct_w8_block(const Ctx& c, LAS unsigned char* lds, const float* Wsrc, const int INC_, int srccol, unsigned char* dstrow, float* swdst) {
;     ...
;     for (int t = 0; t < 8; ++t) { f32x4 v[8]; const float* Wt = W + (size_t)(t * 64) * INC_; asm volatile("" : "+v"(Wt));
; #pragma unroll
;         for (int e = 0; e < 8; ++e) v[e] = __builtin_nontemporal_load((const f32x4*)(Wt + (size_t)e * INC_));
; #pragma unroll
;         for (int j = 0; j < 4; ++j) {
; #pragma unroll
;             for (int e = 0; e < 8; ++e) mx[j] = fmaxf(mx[j], fabsf(v[e][j]));
;             v4u pk; pk.x = pk2(v[0][j], v[1][j]); pk.y = pk2(v[2][j], v[3][j]); pk.z = pk2(v[4][j], v[5][j]); pk.w = pk2(v[6][j], v[7][j]);
;             if (t < 4) { held[t & 3][j][0] = pk.x; held[t & 3][j][1] = pk.y; held[t & 3][j][2] = pk.z; held[t & 3][j][3] = pk.w; }
;             else *(LAS v4u*)(hl + ((t - 4) * 4 + j) * 1024) = pk; }
;         if ((t & 3) == 3) { asm volatile("" ::: "memory"); __builtin_amdgcn_sched_barrier(0); } }
	v_max3_f32 v171, v132, |v157|, |v173|
	v_max3_f32 v132, v180, |v134|, |v138|
	v_max3_f32 v132, v132, |v142|, |v146|
	v_cvt_pk_bf16_f32 v179, v156, v172
	v_max3_f32 v132, v132, |v150|, |v154|
	v_max3_f32 v182, v160, |v156|, |v172|
	ds_write_b128 v96, v[176:179] offset:4096
	v_cvt_pk_bf16_f32 v179, v157, v173
	v_cvt_pk_bf16_f32 v178, v149, v153
	v_cvt_pk_bf16_f32 v177, v141, v145
	v_cvt_pk_bf16_f32 v176, v133, v137
	v_max3_f32 v172, v132, |v158|, |v174|
	v_max3_f32 v132, v181, |v135|, |v139|
	ds_write_b128 v96, v[176:179] offset:5120
	v_cvt_pk_bf16_f32 v179, v158, v174
	v_cvt_pk_bf16_f32 v178, v150, v154
	v_cvt_pk_bf16_f32 v177, v142, v146
	v_cvt_pk_bf16_f32 v176, v134, v138
	v_max3_f32 v132, v132, |v143|, |v147|
	v_cvt_pk_bf16_f32 v145, v159, v175
	v_cvt_pk_bf16_f32 v143, v143, v147
	v_cvt_pk_bf16_f32 v142, v135, v139
	v_lshl_add_u64 v[160:161], v[130:131], 0, s[8:9]
	ds_write_b128 v96, v[176:179] offset:6144
	ds_write_b128 v96, v[142:145] offset:7168
	v_max3_f32 v132, v132, |v151|, |v155|
	v_add_co_u32_e32 v136, vcc, s61, v160
	v_max3_f32 v184, v132, |v159|, |v175|
	s_nop 0
	v_addc_co_u32_e32 v137, vcc, 0, v161, vcc
	v_add_co_u32_e32 v140, vcc, s25, v160
	flat_load_dwordx4 v[132:135], v[160:161] nt
	s_nop 0
	v_addc_co_u32_e32 v141, vcc, 0, v161, vcc
	v_add_co_u32_e32 v144, vcc, s73, v160
	flat_load_dwordx4 v[136:139], v[136:137] nt
	s_nop 0
	v_addc_co_u32_e32 v145, vcc, 0, v161, vcc
	v_add_co_u32_e32 v148, vcc, s94, v160
	flat_load_dwordx4 v[140:143], v[140:141] nt
	s_nop 0
	v_addc_co_u32_e32 v149, vcc, 0, v161, vcc
	v_add_co_u32_e32 v152, vcc, s2, v160
	flat_load_dwordx4 v[144:147], v[144:145] nt
	s_nop 0
	v_addc_co_u32_e32 v153, vcc, 0, v161, vcc
	v_add_co_u32_e32 v156, vcc, s95, v160
	flat_load_dwordx4 v[148:151], v[148:149] nt
	s_nop 0
	v_addc_co_u32_e32 v157, vcc, 0, v161, vcc
	v_add_co_u32_e32 v160, vcc, s5, v160
	flat_load_dwordx4 v[152:155], v[152:153] nt
	s_nop 0
	v_addc_co_u32_e32 v161, vcc, 0, v161, vcc
	flat_load_dwordx4 v[156:159], v[156:157] nt
	s_mov_b64 s[8:9], 0x2a00000
	flat_load_dwordx4 v[176:179], v[160:161] nt
	s_waitcnt vmcnt(0) lgkmcnt(0)
	v_max3_f32 v160, v182, |v132|, |v136|
	v_cvt_pk_bf16_f32 v180, v132, v136
	v_max3_f32 v132, v171, |v133|, |v137|
	v_max3_f32 v132, v132, |v141|, |v145|
	v_cvt_pk_bf16_f32 v181, v140, v144
	v_max3_f32 v160, v160, |v140|, |v144|
	v_max3_f32 v132, v132, |v149|, |v153|
	v_cvt_pk_bf16_f32 v182, v148, v152
	v_cvt_pk_bf16_f32 v144, v151, v155
	v_max3_f32 v160, v160, |v148|, |v152|
	v_max3_f32 v173, v132, |v157|, |v177|
	v_max3_f32 v132, v172, |v134|, |v138|
	v_max3_f32 v132, v132, |v142|, |v146|
	v_max3_f32 v132, v132, |v150|, |v154|
	v_max3_f32 v172, v132, |v158|, |v178|
	v_max3_f32 v132, v184, |v135|, |v139|
	v_cvt_pk_bf16_f32 v183, v156, v176
	v_max3_f32 v132, v132, |v143|, |v147|
	ds_write_b128 v96, v[180:183] offset:8192
	v_cvt_pk_bf16_f32 v183, v157, v177
	v_cvt_pk_bf16_f32 v182, v149, v153
	v_cvt_pk_bf16_f32 v181, v141, v145
	v_cvt_pk_bf16_f32 v180, v133, v137
	v_max3_f32 v132, v132, |v151|, |v155|
	ds_write_b128 v96, v[180:183] offset:9216
	v_cvt_pk_bf16_f32 v183, v158, v178
	v_cvt_pk_bf16_f32 v182, v150, v154
	v_cvt_pk_bf16_f32 v181, v142, v146
	v_cvt_pk_bf16_f32 v180, v134, v138
	v_max3_f32 v171, v132, |v159|, |v179|
	v_cvt_pk_bf16_f32 v145, v159, v179
	v_cvt_pk_bf16_f32 v143, v143, v147
	v_cvt_pk_bf16_f32 v142, v135, v139
	v_lshl_add_u64 v[158:159], v[130:131], 0, s[8:9]
	ds_write_b128 v96, v[180:183] offset:10240
	ds_write_b128 v96, v[142:145] offset:11264
	flat_load_dwordx4 v[130:133], v[158:159] nt
	v_add_co_u32_e32 v134, vcc, s61, v158
	v_max3_f32 v174, v160, |v156|, |v176|
	s_nop 0
	v_addc_co_u32_e32 v135, vcc, 0, v159, vcc
	v_add_co_u32_e32 v138, vcc, s25, v158
	flat_load_dwordx4 v[134:137], v[134:135] nt
	s_nop 0
	v_addc_co_u32_e32 v139, vcc, 0, v159, vcc
	v_add_co_u32_e32 v142, vcc, s73, v158
	flat_load_dwordx4 v[138:141], v[138:139] nt
	s_nop 0
	v_addc_co_u32_e32 v143, vcc, 0, v159, vcc
	v_add_co_u32_e32 v146, vcc, s94, v158
	flat_load_dwordx4 v[142:145], v[142:143] nt
	s_nop 0
	v_addc_co_u32_e32 v147, vcc, 0, v159, vcc
	v_add_co_u32_e32 v150, vcc, s2, v158
	flat_load_dwordx4 v[146:149], v[146:147] nt
	s_nop 0
	v_addc_co_u32_e32 v151, vcc, 0, v159, vcc
	v_add_co_u32_e32 v154, vcc, s95, v158
	flat_load_dwordx4 v[150:153], v[150:151] nt
	s_nop 0
	v_addc_co_u32_e32 v155, vcc, 0, v159, vcc
	v_add_co_u32_e32 v158, vcc, s5, v158
	flat_load_dwordx4 v[154:157], v[154:155] nt
	s_nop 0
	v_addc_co_u32_e32 v159, vcc, 0, v159, vcc
	flat_load_dwordx4 v[158:161], v[158:159] nt
	s_waitcnt vmcnt(0) lgkmcnt(0)
; #define LAS __attribute__((address_space(3)))
; __device__ __forceinline__ unsigned pk2(float lo, float hi) { return pg8::cvt_pk_bf16(lo, hi); }
; __device__ __forceinline__ void direct_w8_block(const Ctx& c, LAS unsigned char* lds, const float* Wsrc, const int INC_, int srccol, unsigned char* dstrow, float* swdst) {
;     ...
;     for (int t = 0; t < 8; ++t) { f32x4 v[8]; const float* Wt = W + (size_t)(t * 64) * INC_; asm volatile("" : "+v"(Wt));
; #pragma unroll
;         for (int e = 0; e < 8; ++e) v[e] = __builtin_nontemporal_load((const f32x4*)(Wt + (size_t)e * INC_));
; #pragma unroll
;         for (int j = 0; j < 4; ++j) {
; #pragma unroll
;             for (int e = 0; e < 8; ++e) mx[j] = fmaxf(mx[j], fabsf(v[e][j]));
;             v4u pk; pk.x = pk2(v[0][j], v[1][j]); pk.y = pk2(v[2][j], v[3][j]); pk.z = pk2(v[4][j], v[5][j]); pk.w = pk2(v[6][j], v[7][j]);
;             if (t < 4) { held[t & 3][j][0] = pk.x; held[t & 3][j][1] = pk.y; held[t & 3][j][2] = pk.z; held[t & 3][j][3] = pk.w; }
;             else *(LAS v4u*)(hl + ((t - 4) * 4 + j) * 1024) = pk; }
;         if ((t & 3) == 3) { asm volatile("" ::: "memory"); __builtin_amdgcn_sched_barrier(0); } }
; #pragma unroll
;     for (int j = 0; j < 4; ++j) { float m = mx[j]; m = fmaxf(m, __shfl_xor(m, 8)); m = fmaxf(m, __shfl_xor(m, 16)); m = fmaxf(m, __shfl_xor(m, 32)); mx[j] = m; }
;     if (kr == 0) *(LAS f32x4*)(pm + wave * 32 + 4 * nc) = mx;
	v_max3_f32 v174, v174, |v130|, |v134|
	v_max3_f32 v174, v174, |v138|, |v142|
	v_cvt_pk_bf16_f32 v175, v138, v142
	v_max3_f32 v174, v174, |v146|, |v150|
	v_cvt_pk_bf16_f32 v176, v146, v150
	v_cvt_pk_bf16_f32 v142, v149, v153
	v_max3_f32 v178, v174, |v154|, |v158|
	v_cvt_pk_bf16_f32 v177, v154, v158
	v_cvt_pk_bf16_f32 v174, v130, v134
	ds_write_b128 v96, v[174:177] offset:12288
	v_max3_f32 v130, v173, |v131|, |v135|
	v_cvt_pk_bf16_f32 v174, v131, v135
	v_max3_f32 v131, v172, |v132|, |v136|
	v_max3_f32 v131, v131, |v140|, |v144|
	v_max3_f32 v131, v131, |v148|, |v152|
	v_cvt_pk_bf16_f32 v177, v155, v159
	v_cvt_pk_bf16_f32 v176, v147, v151
	v_cvt_pk_bf16_f32 v175, v139, v143
	v_max3_f32 v134, v131, |v156|, |v160|
	v_max3_f32 v131, v171, |v133|, |v137|
	v_max3_f32 v130, v130, |v139|, |v143|
	ds_write_b128 v96, v[174:177] offset:13312
	v_cvt_pk_bf16_f32 v175, v156, v160
	v_cvt_pk_bf16_f32 v174, v148, v152
	v_cvt_pk_bf16_f32 v173, v140, v144
	v_cvt_pk_bf16_f32 v172, v132, v136
	v_max3_f32 v131, v131, |v141|, |v145|
	v_cvt_pk_bf16_f32 v143, v157, v161
	v_cvt_pk_bf16_f32 v141, v141, v145
	v_cvt_pk_bf16_f32 v140, v133, v137
	ds_write_b128 v96, v[172:175] offset:14336
	ds_write_b128 v96, v[140:143] offset:15360
	v_max3_f32 v130, v130, |v147|, |v151|
	v_max3_f32 v131, v131, |v149|, |v153|
	v_max3_f32 v130, v130, |v155|, |v159|
	v_max3_f32 v135, v131, |v157|, |v161|
	v_and_b32_e32 v132, 64, v238
	v_xor_b32_e32 v131, 8, v238
	v_add_u32_e32 v132, 64, v132
	v_cmp_lt_i32_e32 vcc, v131, v132
	v_xor_b32_e32 v137, 32, v238
	s_nop 0
	v_cndmask_b32_e32 v131, v238, v131, vcc
	v_lshlrev_b32_e32 v133, 2, v131
	v_xor_b32_e32 v131, 16, v238
	v_cmp_lt_i32_e32 vcc, v131, v132
	s_nop 1
	v_cndmask_b32_e32 v131, v238, v131, vcc
	v_lshlrev_b32_e32 v136, 2, v131
	ds_bpermute_b32 v131, v133, v178
	v_cmp_lt_i32_e32 vcc, v137, v132
	s_waitcnt lgkmcnt(0)
	v_max_f32_e32 v131, v131, v131
	v_cndmask_b32_e32 v132, v238, v137, vcc
	ds_bpermute_b32 v137, v133, v130
	v_max_f32_e32 v131, v178, v131
	ds_bpermute_b32 v138, v136, v131
	v_lshlrev_b32_e32 v139, 2, v132
	s_waitcnt lgkmcnt(1)
	v_max_f32_e32 v132, v137, v137
	v_max_f32_e32 v132, v130, v132
	ds_bpermute_b32 v137, v136, v132
	s_waitcnt lgkmcnt(1)
	v_max_f32_e32 v130, v138, v138
	ds_bpermute_b32 v138, v133, v134
	ds_bpermute_b32 v133, v133, v135
	v_max_f32_e32 v130, v131, v130
	s_waitcnt lgkmcnt(2)
	v_max_f32_e32 v137, v137, v137
	v_max_f32_e32 v132, v132, v137
	s_waitcnt lgkmcnt(1)
	v_max_f32_e32 v137, v138, v138
	s_waitcnt lgkmcnt(0)
	v_max_f32_e32 v133, v133, v133
	v_max_f32_e32 v137, v134, v137
	v_max_f32_e32 v140, v135, v133
	ds_bpermute_b32 v138, v136, v137
	ds_bpermute_b32 v136, v136, v140
	ds_bpermute_b32 v131, v139, v130
	ds_bpermute_b32 v134, v139, v132
	s_waitcnt lgkmcnt(3)
	v_max_f32_e32 v133, v138, v138
	s_waitcnt lgkmcnt(2)
	v_max_f32_e32 v136, v136, v136
	v_max_f32_e32 v133, v137, v133
	v_max_f32_e32 v136, v140, v136
	ds_bpermute_b32 v135, v139, v133
	ds_bpermute_b32 v137, v139, v136
	s_and_saveexec_b64 s[8:9], s[6:7]
	s_cbranch_execz .LBB0_788
	s_waitcnt lgkmcnt(0)
	v_max_f32_e32 v137, v137, v137
	v_max_f32_e32 v136, v136, v136
	v_max_f32_e32 v131, v131, v131
	v_max_f32_e32 v130, v130, v130
	v_max_f32_e32 v139, v136, v137
	v_max_f32_e32 v136, v130, v131
	v_max_f32_e32 v130, v134, v134
	v_max_f32_e32 v131, v132, v132
	v_max_f32_e32 v137, v131, v130
	v_max_f32_e32 v130, v135, v135
	v_max_f32_e32 v131, v133, v133
	v_max_f32_e32 v138, v131, v130
	ds_write_b128 v163, v[136:139]
